# strategy 6.3/7.4b: mid-segment s_setprio 0/1 flip pairs deleted inside the 32-MFMA segments of the GEMM K-loops (priority stays 1 across a segment)
# speedup vs baseline: 1.0101x; 1.0101x over previous
; #define PG8_STAGE(bufoff, gbase, voff) do { _Pragma("unroll") for (int _i = 0; _i < 2; ++_i) \
;         __builtin_amdgcn_global_load_lds((const unsigned*)((const char*)(gbase) + (voff)[_i]), (PG8_LAS unsigned*)(lds + (bufoff) + ldsw + _i * 8192), 16, 0, 0); } while (0)
; #define PG8_LDA(dst, b, h) do { _Pragma("unroll") for (int m = 0; m < 4; ++m) _Pragma("unroll") for (int k = 0; k < 2; ++k) dst[m][k] = *(const PG8_LAS bf16x8*)(lds + PG8_SA(b, h) + aoff + m * 2048 + k * 1024); } while (0)
; #define PG8_LDB(dst, b, h) do { _Pragma("unroll") for (int n = 0; n < 2; ++n) _Pragma("unroll") for (int k = 0; k < 2; ++k) dst[n][k] = *(const PG8_LAS bf16x8*)(lds + PG8_SB(b, h) + boff + n * 2048 + k * 1024); } while (0)
; #define PG8_MMA(ai, bj, At, Bt) do { __builtin_amdgcn_s_setprio(1); _Pragma("unroll") for (int m = 0; m < 4; ++m) _Pragma("unroll") for (int n = 0; n < 2; ++n) _Pragma("unroll") for (int k = 0; k < 2; ++k) \
;         acc[ai][bj][m][n] = __builtin_amdgcn_mfma_f32_16x16x32_bf16(Bt[n][k], At[m][k], acc[ai][bj][m][n], 0, 0, 0); __builtin_amdgcn_s_setprio(0); } while (0)
; #define PG8_BAR __builtin_amdgcn_s_barrier()
; template <class Epi, class Sched, bool ALIGN_EPI = false, bool SP2 = false>
; __device__ __forceinline__ void gemm_phase(PG8_LAS unsigned char* lds, const Gemm g, const Sched& S, const Epi& E) {
;     ...
;         const bool has_next = S.next(ui + 1, nxt);
;         const char* nA = has_next ? (const char*)g.A + (size_t)nxt.pm * tstep : cA; const char* nB = has_next ? (const char*)g.Bt + (size_t)nxt.pn * tstep : cB;
;         for (int t = 0; t < nt; t += 2) {
;             const bool last = (t == nt - 2);
;             const char* a1 = cA + (size_t)(t + 1) * kstep;
;             const char* a2 = last ? nA : cA + (size_t)(t + 2) * kstep; const char* b2 = last ? nB : cB + (size_t)(t + 2) * kstep;
;             const char* a3 = a2 + kstep; const char* b3 = b2 + kstep;
;             if (last && has_next) S.a_ready(nxt);
;             if constexpr (SP2) {
;             PG8_LDB(B0, 0, 0); PG8_LDB(B1, 0, 1); PG8_SCHED; PG8_LDA(At, 0, 0); PG8_STAGE(PG8_SA(1, 1), a1 + hstep, voffA);
;             PG8_WAIT_V(8); PG8_WAIT_L(0); PG8_BAR; PG8_MMA(0, 0, At, B0); PG8_MMA(0, 1, At, B1); PG8_BAR; PG8_SCHED;
;             PG8_LDA(At, 0, 1); PG8_STAGE(PG8_SB(0, 0), b2, voffB); PG8_STAGE(PG8_SB(0, 1), b2 + hstep, voffB); PG8_STAGE(PG8_SA(0, 0), a2, voffA);
.LBB0_43:
	s_ashr_i32 s47, s46, 31
	s_lshl_b64 s[24:25], s[46:47], 19
	s_add_u32 s48, s26, s24
	s_addc_u32 s49, s27, s25
	s_and_b64 s[24:25], s[40:41], exec
	s_cselect_b32 s1, s49, s61
	s_cselect_b32 s12, s48, s60
	s_ashr_i32 s3, s2, 31
	s_lshl_b64 s[24:25], s[2:3], 19
	s_add_u32 s56, s23, s24
	s_addc_u32 s57, s29, s25
	s_and_b64 s[24:25], s[40:41], exec
	s_cselect_b32 s3, s57, s63
	s_cselect_b32 s22, s56, s62
	s_add_u32 s60, s60, 0x40080
	s_addc_u32 s61, s61, 0
	s_add_u32 s33, s62, 0x100
	s_addc_u32 s44, s63, 0
	s_mov_b32 s45, -2
	s_add_u32 s24, s60, 0xfffc0080
	s_addc_u32 s25, s61, -1
	s_add_i32 s47, 0, 0x10000
	s_cmp_eq_u32 s45, 12
	s_cselect_b32 s65, s1, s25
	s_cselect_b32 s64, s12, s24
	v_add_u32_e32 v150, s47, v153
	s_cselect_b32 s63, s3, s44
	s_cselect_b32 s62, s22, s33
	s_add_i32 s50, 0, 0x14000
	ds_read_b128 v[146:149], v150
	ds_read_b128 v[156:159], v150 offset:1024
	ds_read_b128 v[160:163], v150 offset:2048
	ds_read_b128 v[164:167], v150 offset:3072
	v_add_u32_e32 v150, s50, v153
	ds_read_b128 v[168:171], v150
	ds_read_b128 v[192:195], v150 offset:1024
	ds_read_b128 v[196:199], v150 offset:2048
	ds_read_b128 v[200:203], v150 offset:3072
	v_lshl_add_u64 v[150:151], s[60:61], 0, v[142:143]
	s_add_i32 m0, s68, 0xc000
	ds_read_b128 v[204:207], v155
	ds_read_b128 v[208:211], v155 offset:1024
	ds_read_b128 v[212:215], v155 offset:2048
	ds_read_b128 v[216:219], v155 offset:3072
	ds_read_b128 v[220:223], v155 offset:4096
	ds_read_b128 v[224:227], v155 offset:5120
	ds_read_b128 v[228:231], v155 offset:6144
	ds_read_b128 v[232:235], v155 offset:7168
	global_load_lds_dwordx4 v[150:151], off
	v_lshl_add_u64 v[150:151], s[60:61], 0, v[144:145]
	s_add_i32 m0, s68, 0xe000
	s_nop 0
	global_load_lds_dwordx4 v[150:151], off
	s_waitcnt vmcnt(10)
	s_waitcnt lgkmcnt(0)
	s_barrier
	s_setprio 1
	s_waitcnt lgkmcnt(0)
	v_mfma_f32_16x16x32_bf16 v[124:127], v[146:149], v[204:207], 0
	v_mfma_f32_16x16x32_bf16 v[120:123], v[160:163], v[204:207], 0
	v_mfma_f32_16x16x32_bf16 v[108:111], v[146:149], v[212:215], 0
	v_mfma_f32_16x16x32_bf16 v[104:107], v[160:163], v[212:215], 0
	v_mfma_f32_16x16x32_bf16 v[92:95], v[146:149], v[220:223], 0
	v_mfma_f32_16x16x32_bf16 v[88:91], v[160:163], v[220:223], 0
	v_mfma_f32_16x16x32_bf16 v[76:79], v[146:149], v[228:231], 0
	v_mfma_f32_16x16x32_bf16 v[72:75], v[160:163], v[228:231], 0
	v_mfma_f32_16x16x32_bf16 v[124:127], v[156:159], v[208:211], v[124:127]
	v_mfma_f32_16x16x32_bf16 v[120:123], v[164:167], v[208:211], v[120:123]
	v_mfma_f32_16x16x32_bf16 v[108:111], v[156:159], v[216:219], v[108:111]
	v_mfma_f32_16x16x32_bf16 v[104:107], v[164:167], v[216:219], v[104:107]
	v_mfma_f32_16x16x32_bf16 v[92:95], v[156:159], v[224:227], v[92:95]
	v_mfma_f32_16x16x32_bf16 v[88:91], v[164:167], v[224:227], v[88:91]
	v_mfma_f32_16x16x32_bf16 v[76:79], v[156:159], v[232:235], v[76:79]
	v_mfma_f32_16x16x32_bf16 v[72:75], v[164:167], v[232:235], v[72:75]
	v_mfma_f32_16x16x32_bf16 v[116:119], v[168:171], v[204:207], 0
	v_mfma_f32_16x16x32_bf16 v[112:115], v[196:199], v[204:207], 0
	v_mfma_f32_16x16x32_bf16 v[100:103], v[168:171], v[212:215], 0
	v_mfma_f32_16x16x32_bf16 v[96:99], v[196:199], v[212:215], 0
	v_mfma_f32_16x16x32_bf16 v[84:87], v[168:171], v[220:223], 0
	v_mfma_f32_16x16x32_bf16 v[80:83], v[196:199], v[220:223], 0
	v_mfma_f32_16x16x32_bf16 v[68:71], v[168:171], v[228:231], 0
	v_mfma_f32_16x16x32_bf16 v[64:67], v[196:199], v[228:231], 0
	v_mfma_f32_16x16x32_bf16 v[116:119], v[192:195], v[208:211], v[116:119]
	v_mfma_f32_16x16x32_bf16 v[112:115], v[200:203], v[208:211], v[112:115]
	v_mfma_f32_16x16x32_bf16 v[100:103], v[192:195], v[216:219], v[100:103]
	v_mfma_f32_16x16x32_bf16 v[96:99], v[200:203], v[216:219], v[96:99]
	v_mfma_f32_16x16x32_bf16 v[84:87], v[192:195], v[224:227], v[84:87]
	v_mfma_f32_16x16x32_bf16 v[80:83], v[200:203], v[224:227], v[80:83]
	v_mfma_f32_16x16x32_bf16 v[68:71], v[192:195], v[232:235], v[68:71]
	v_mfma_f32_16x16x32_bf16 v[64:67], v[200:203], v[232:235], v[64:67]
	s_setprio 0
	s_barrier
	s_add_i32 s24, s47, s66
	v_lshl_add_u64 v[150:151], s[62:63], 0, v[132:133]
	s_mov_b32 m0, s24
	ds_read_b128 v[204:207], v155 offset:16384
	ds_read_b128 v[208:211], v155 offset:17408
	ds_read_b128 v[212:215], v155 offset:18432
	ds_read_b128 v[216:219], v155 offset:19456
	ds_read_b128 v[220:223], v155 offset:20480
	ds_read_b128 v[224:227], v155 offset:21504
	ds_read_b128 v[228:231], v155 offset:22528
	ds_read_b128 v[232:235], v155 offset:23552
	global_load_lds_dwordx4 v[150:151], off
	s_add_i32 m0, s24, 0x2000
	s_add_u32 s24, s62, 0x40000
	v_lshl_add_u64 v[236:237], s[62:63], 0, v[128:129]
	s_addc_u32 s25, s63, 0
	s_add_i32 s47, s50, s66
	global_load_lds_dwordx4 v[236:237], off
	v_lshl_add_u64 v[238:239], s[24:25], 0, v[132:133]
	s_mov_b32 m0, s47
	v_lshl_add_u64 v[240:241], s[64:65], 0, v[130:131]
	global_load_lds_dwordx4 v[238:239], off
	v_lshl_add_u64 v[238:239], s[24:25], 0, v[128:129]
	s_add_i32 m0, s47, 0x2000
	s_nop 0
	global_load_lds_dwordx4 v[238:239], off
	v_lshl_add_u64 v[238:239], s[64:65], 0, v[140:141]
	s_mov_b32 m0, s68
	s_nop 0
	global_load_lds_dwordx4 v[238:239], off
	s_mov_b32 m0, s69
	s_nop 0
	global_load_lds_dwordx4 v[240:241], off
	s_waitcnt vmcnt(16)
	s_waitcnt lgkmcnt(0)
	s_barrier
; #define PG8_STAGE(bufoff, gbase, voff) do { _Pragma("unroll") for (int _i = 0; _i < 2; ++_i) \
;         __builtin_amdgcn_global_load_lds((const unsigned*)((const char*)(gbase) + (voff)[_i]), (PG8_LAS unsigned*)(lds + (bufoff) + ldsw + _i * 8192), 16, 0, 0); } while (0)
; #define PG8_LDA(dst, b, h) do { _Pragma("unroll") for (int m = 0; m < 4; ++m) _Pragma("unroll") for (int k = 0; k < 2; ++k) dst[m][k] = *(const PG8_LAS bf16x8*)(lds + PG8_SA(b, h) + aoff + m * 2048 + k * 1024); } while (0)
; #define PG8_LDB(dst, b, h) do { _Pragma("unroll") for (int n = 0; n < 2; ++n) _Pragma("unroll") for (int k = 0; k < 2; ++k) dst[n][k] = *(const PG8_LAS bf16x8*)(lds + PG8_SB(b, h) + boff + n * 2048 + k * 1024); } while (0)
; #define PG8_MMA(ai, bj, At, Bt) do { __builtin_amdgcn_s_setprio(1); _Pragma("unroll") for (int m = 0; m < 4; ++m) _Pragma("unroll") for (int n = 0; n < 2; ++n) _Pragma("unroll") for (int k = 0; k < 2; ++k) \
;         acc[ai][bj][m][n] = __builtin_amdgcn_mfma_f32_16x16x32_bf16(Bt[n][k], At[m][k], acc[ai][bj][m][n], 0, 0, 0); __builtin_amdgcn_s_setprio(0); } while (0)
; #define PG8_WAIT_V(n) asm volatile("s_waitcnt vmcnt(" #n ")" ::: "memory")
; #define PG8_WAIT_L(n) asm volatile("s_waitcnt lgkmcnt(" #n ")" ::: "memory")
; #define PG8_BAR __builtin_amdgcn_s_barrier()
; #define PG8_SCHED __builtin_amdgcn_sched_barrier(0)
; template <class Epi, class Sched, bool ALIGN_EPI = false, bool SP2 = false>
; __device__ __forceinline__ void gemm_phase(PG8_LAS unsigned char* lds, const Gemm g, const Sched& S, const Epi& E) {
;     ...
;             PG8_WAIT_V(8); PG8_WAIT_L(0); PG8_BAR; PG8_MMA(1, 0, At, B0); PG8_MMA(1, 1, At, B1); PG8_BAR; PG8_SCHED;
;             PG8_LDB(B0, 1, 0); PG8_LDB(B1, 1, 1); PG8_SCHED; PG8_LDA(At, 1, 0); PG8_STAGE(PG8_SA(0, 1), a2 + hstep, voffA);
;             PG8_WAIT_V(8); PG8_WAIT_L(0); PG8_BAR; PG8_MMA(0, 0, At, B0); PG8_MMA(0, 1, At, B1); PG8_BAR; PG8_SCHED;
	s_setprio 1
	s_waitcnt lgkmcnt(0)
	v_mfma_f32_16x16x32_bf16 v[60:63], v[146:149], v[204:207], 0
	v_mfma_f32_16x16x32_bf16 v[56:59], v[160:163], v[204:207], 0
	v_mfma_f32_16x16x32_bf16 v[44:47], v[146:149], v[212:215], 0
	v_mfma_f32_16x16x32_bf16 v[40:43], v[160:163], v[212:215], 0
	v_mfma_f32_16x16x32_bf16 v[28:31], v[146:149], v[220:223], 0
	v_mfma_f32_16x16x32_bf16 v[24:27], v[160:163], v[220:223], 0
	v_mfma_f32_16x16x32_bf16 v[12:15], v[146:149], v[228:231], 0
	v_mfma_f32_16x16x32_bf16 v[8:11], v[160:163], v[228:231], 0
	v_mfma_f32_16x16x32_bf16 v[60:63], v[156:159], v[208:211], v[60:63]
	v_mfma_f32_16x16x32_bf16 v[56:59], v[164:167], v[208:211], v[56:59]
	v_mfma_f32_16x16x32_bf16 v[44:47], v[156:159], v[216:219], v[44:47]
	v_mfma_f32_16x16x32_bf16 v[40:43], v[164:167], v[216:219], v[40:43]
	v_mfma_f32_16x16x32_bf16 v[28:31], v[156:159], v[224:227], v[28:31]
	v_mfma_f32_16x16x32_bf16 v[24:27], v[164:167], v[224:227], v[24:27]
	v_mfma_f32_16x16x32_bf16 v[12:15], v[156:159], v[232:235], v[12:15]
	v_mfma_f32_16x16x32_bf16 v[8:11], v[164:167], v[232:235], v[8:11]
	v_mfma_f32_16x16x32_bf16 v[52:55], v[168:171], v[204:207], 0
	v_mfma_f32_16x16x32_bf16 v[48:51], v[196:199], v[204:207], 0
	v_mfma_f32_16x16x32_bf16 v[36:39], v[168:171], v[212:215], 0
	v_mfma_f32_16x16x32_bf16 v[32:35], v[196:199], v[212:215], 0
	v_mfma_f32_16x16x32_bf16 v[20:23], v[168:171], v[220:223], 0
	v_mfma_f32_16x16x32_bf16 v[16:19], v[196:199], v[220:223], 0
	v_mfma_f32_16x16x32_bf16 v[4:7], v[168:171], v[228:231], 0
	v_mfma_f32_16x16x32_bf16 v[0:3], v[196:199], v[228:231], 0
	v_mfma_f32_16x16x32_bf16 v[52:55], v[192:195], v[208:211], v[52:55]
	v_mfma_f32_16x16x32_bf16 v[48:51], v[200:203], v[208:211], v[48:51]
	v_mfma_f32_16x16x32_bf16 v[36:39], v[192:195], v[216:219], v[36:39]
	v_mfma_f32_16x16x32_bf16 v[32:35], v[200:203], v[216:219], v[32:35]
	v_mfma_f32_16x16x32_bf16 v[20:23], v[192:195], v[224:227], v[20:23]
	v_mfma_f32_16x16x32_bf16 v[16:19], v[200:203], v[224:227], v[16:19]
	v_mfma_f32_16x16x32_bf16 v[4:7], v[192:195], v[232:235], v[4:7]
	v_mfma_f32_16x16x32_bf16 v[0:3], v[200:203], v[232:235], v[0:3]
	s_setprio 0
	s_barrier
	s_add_i32 s47, 0, 0x18000
	s_add_i32 s50, 0, 0x1c000
	v_add_u32_e32 v164, s47, v153
	v_add_u32_e32 v184, s50, v153
	ds_read_b128 v[146:149], v164
	ds_read_b128 v[156:159], v164 offset:1024
	ds_read_b128 v[160:163], v164 offset:2048
	ds_read_b128 v[164:167], v164 offset:3072
	ds_read_b128 v[168:171], v184
	ds_read_b128 v[192:195], v184 offset:1024
	ds_read_b128 v[196:199], v184 offset:2048
	ds_read_b128 v[200:203], v184 offset:3072
	s_add_u32 s24, s64, 0x40000
	s_addc_u32 s25, s65, 0
	s_mov_b32 m0, s71
	v_lshl_add_u64 v[242:243], s[24:25], 0, v[140:141]
	ds_read_b128 v[204:207], v155 offset:32768
	ds_read_b128 v[208:211], v155 offset:33792
	ds_read_b128 v[212:215], v155 offset:34816
	ds_read_b128 v[216:219], v155 offset:35840
	ds_read_b128 v[220:223], v155 offset:36864
	ds_read_b128 v[224:227], v155 offset:37888
	ds_read_b128 v[228:231], v155 offset:38912
	ds_read_b128 v[232:235], v155 offset:39936
	global_load_lds_dwordx4 v[242:243], off
	v_lshl_add_u64 v[242:243], s[24:25], 0, v[130:131]
	s_mov_b32 m0, s87
	s_nop 0
	global_load_lds_dwordx4 v[242:243], off
	s_waitcnt vmcnt(8)
	s_waitcnt lgkmcnt(0)
	s_barrier
	s_setprio 1
	s_waitcnt lgkmcnt(0)
	v_mfma_f32_16x16x32_bf16 v[124:127], v[146:149], v[204:207], v[124:127]
	v_mfma_f32_16x16x32_bf16 v[120:123], v[160:163], v[204:207], v[120:123]
	v_mfma_f32_16x16x32_bf16 v[108:111], v[146:149], v[212:215], v[108:111]
	v_mfma_f32_16x16x32_bf16 v[104:107], v[160:163], v[212:215], v[104:107]
	v_mfma_f32_16x16x32_bf16 v[92:95], v[146:149], v[220:223], v[92:95]
	v_mfma_f32_16x16x32_bf16 v[88:91], v[160:163], v[220:223], v[88:91]
	v_mfma_f32_16x16x32_bf16 v[76:79], v[146:149], v[228:231], v[76:79]
	v_mfma_f32_16x16x32_bf16 v[72:75], v[160:163], v[228:231], v[72:75]
	v_mfma_f32_16x16x32_bf16 v[124:127], v[156:159], v[208:211], v[124:127]
	v_mfma_f32_16x16x32_bf16 v[120:123], v[164:167], v[208:211], v[120:123]
	v_mfma_f32_16x16x32_bf16 v[108:111], v[156:159], v[216:219], v[108:111]
	v_mfma_f32_16x16x32_bf16 v[104:107], v[164:167], v[216:219], v[104:107]
	v_mfma_f32_16x16x32_bf16 v[92:95], v[156:159], v[224:227], v[92:95]
	v_mfma_f32_16x16x32_bf16 v[88:91], v[164:167], v[224:227], v[88:91]
	v_mfma_f32_16x16x32_bf16 v[76:79], v[156:159], v[232:235], v[76:79]
	v_mfma_f32_16x16x32_bf16 v[72:75], v[164:167], v[232:235], v[72:75]
	v_mfma_f32_16x16x32_bf16 v[116:119], v[168:171], v[204:207], v[116:119]
	v_mfma_f32_16x16x32_bf16 v[112:115], v[196:199], v[204:207], v[112:115]
	v_mfma_f32_16x16x32_bf16 v[100:103], v[168:171], v[212:215], v[100:103]
	v_mfma_f32_16x16x32_bf16 v[96:99], v[196:199], v[212:215], v[96:99]
	v_mfma_f32_16x16x32_bf16 v[84:87], v[168:171], v[220:223], v[84:87]
	v_mfma_f32_16x16x32_bf16 v[80:83], v[196:199], v[220:223], v[80:83]
	v_mfma_f32_16x16x32_bf16 v[68:71], v[168:171], v[228:231], v[68:71]
	v_mfma_f32_16x16x32_bf16 v[64:67], v[196:199], v[228:231], v[64:67]
	v_mfma_f32_16x16x32_bf16 v[116:119], v[192:195], v[208:211], v[116:119]
	v_mfma_f32_16x16x32_bf16 v[112:115], v[200:203], v[208:211], v[112:115]
	v_mfma_f32_16x16x32_bf16 v[100:103], v[192:195], v[216:219], v[100:103]
	v_mfma_f32_16x16x32_bf16 v[96:99], v[200:203], v[216:219], v[96:99]
	v_mfma_f32_16x16x32_bf16 v[84:87], v[192:195], v[224:227], v[84:87]
	v_mfma_f32_16x16x32_bf16 v[80:83], v[200:203], v[224:227], v[80:83]
	v_mfma_f32_16x16x32_bf16 v[68:71], v[192:195], v[232:235], v[68:71]
	v_mfma_f32_16x16x32_bf16 v[64:67], v[200:203], v[232:235], v[64:67]
	s_setprio 0
	s_barrier
; #define PG8_STAGE(bufoff, gbase, voff) do { _Pragma("unroll") for (int _i = 0; _i < 2; ++_i) \
;         __builtin_amdgcn_global_load_lds((const unsigned*)((const char*)(gbase) + (voff)[_i]), (PG8_LAS unsigned*)(lds + (bufoff) + ldsw + _i * 8192), 16, 0, 0); } while (0)
; #define PG8_LDA(dst, b, h) do { _Pragma("unroll") for (int m = 0; m < 4; ++m) _Pragma("unroll") for (int k = 0; k < 2; ++k) dst[m][k] = *(const PG8_LAS bf16x8*)(lds + PG8_SA(b, h) + aoff + m * 2048 + k * 1024); } while (0)
; #define PG8_LDB(dst, b, h) do { _Pragma("unroll") for (int n = 0; n < 2; ++n) _Pragma("unroll") for (int k = 0; k < 2; ++k) dst[n][k] = *(const PG8_LAS bf16x8*)(lds + PG8_SB(b, h) + boff + n * 2048 + k * 1024); } while (0)
; template <class Epi, class Sched, bool ALIGN_EPI = false, bool SP2 = false>
; __device__ __forceinline__ void gemm_phase(PG8_LAS unsigned char* lds, const Gemm g, const Sched& S, const Epi& E) {
;     ...
;         for (int t = 0; t < nt; t += 2) {
;             const bool last = (t == nt - 2);
;             const char* a1 = cA + (size_t)(t + 1) * kstep;
;             const char* a2 = last ? nA : cA + (size_t)(t + 2) * kstep; const char* b2 = last ? nB : cB + (size_t)(t + 2) * kstep;
;             const char* a3 = a2 + kstep; const char* b3 = b2 + kstep;
;             if (last && has_next) S.a_ready(nxt);
;             if constexpr (SP2) {
;             PG8_LDB(B0, 0, 0); PG8_LDB(B1, 0, 1); PG8_SCHED; PG8_LDA(At, 0, 0); PG8_STAGE(PG8_SA(1, 1), a1 + hstep, voffA);
;             PG8_WAIT_V(8); PG8_WAIT_L(0); PG8_BAR; PG8_MMA(0, 0, At, B0); PG8_MMA(0, 1, At, B1); PG8_BAR; PG8_SCHED;
;             PG8_LDA(At, 0, 1); PG8_STAGE(PG8_SB(0, 0), b2, voffB); PG8_STAGE(PG8_SB(0, 1), b2 + hstep, voffB); PG8_STAGE(PG8_SA(0, 0), a2, voffA);
;             PG8_WAIT_V(8); PG8_WAIT_L(0); PG8_BAR; PG8_MMA(1, 0, At, B0); PG8_MMA(1, 1, At, B1); PG8_BAR; PG8_SCHED;
;             PG8_LDB(B0, 1, 0); PG8_LDB(B1, 1, 1); PG8_SCHED; PG8_LDA(At, 1, 0); PG8_STAGE(PG8_SA(0, 1), a2 + hstep, voffA);
;             PG8_WAIT_V(8); PG8_WAIT_L(0); PG8_BAR; PG8_MMA(0, 0, At, B0); PG8_MMA(0, 1, At, B1); PG8_BAR; PG8_SCHED;
;             PG8_LDA(At, 1, 1); PG8_STAGE(PG8_SB(1, 0), b3, voffB); PG8_STAGE(PG8_SB(1, 1), b3 + hstep, voffB); PG8_STAGE(PG8_SA(1, 0), a3, voffA);
;             PG8_WAIT_V(8); PG8_WAIT_L(0); PG8_BAR; PG8_MMA(1, 0, At, B0); PG8_MMA(1, 1, At, B1); PG8_BAR; PG8_SCHED;
	s_add_i32 s24, s47, s66
	v_lshl_add_u64 v[150:151], v[150:151], 0, s[14:15]
	s_mov_b32 m0, s24
	ds_read_b128 v[204:207], v155 offset:49152
	ds_read_b128 v[208:211], v155 offset:50176
	ds_read_b128 v[212:215], v155 offset:51200
	ds_read_b128 v[216:219], v155 offset:52224
	ds_read_b128 v[220:223], v155 offset:53248
	ds_read_b128 v[224:227], v155 offset:54272
	ds_read_b128 v[228:231], v155 offset:55296
	ds_read_b128 v[232:235], v155 offset:56320
	global_load_lds_dwordx4 v[150:151], off
	s_add_i32 m0, s24, 0x2000
	s_add_u32 s24, s62, 0x40080
	v_lshl_add_u64 v[150:151], v[236:237], 0, s[14:15]
	s_addc_u32 s25, s63, 0
	s_add_i32 s47, s50, s66
	global_load_lds_dwordx4 v[150:151], off
	v_lshl_add_u64 v[150:151], s[24:25], 0, v[132:133]
	s_mov_b32 m0, s47
	s_nop 0
	global_load_lds_dwordx4 v[150:151], off
	v_lshl_add_u64 v[150:151], s[24:25], 0, v[128:129]
	s_add_i32 m0, s47, 0x2000
	s_nop 0
	global_load_lds_dwordx4 v[150:151], off
	v_lshl_add_u64 v[150:151], v[238:239], 0, s[14:15]
	s_mov_b32 m0, s88
	s_nop 0
	global_load_lds_dwordx4 v[150:151], off
	v_lshl_add_u64 v[150:151], v[240:241], 0, s[14:15]
	s_mov_b32 m0, s89
	s_nop 0
	global_load_lds_dwordx4 v[150:151], off
	s_waitcnt vmcnt(8)
	s_waitcnt lgkmcnt(0)
	s_barrier
	s_setprio 1
	s_waitcnt lgkmcnt(0)
	v_mfma_f32_16x16x32_bf16 v[60:63], v[146:149], v[204:207], v[60:63]
	v_mfma_f32_16x16x32_bf16 v[56:59], v[160:163], v[204:207], v[56:59]
	v_mfma_f32_16x16x32_bf16 v[44:47], v[146:149], v[212:215], v[44:47]
	v_mfma_f32_16x16x32_bf16 v[40:43], v[160:163], v[212:215], v[40:43]
	v_mfma_f32_16x16x32_bf16 v[28:31], v[146:149], v[220:223], v[28:31]
	v_mfma_f32_16x16x32_bf16 v[24:27], v[160:163], v[220:223], v[24:27]
	v_mfma_f32_16x16x32_bf16 v[12:15], v[146:149], v[228:231], v[12:15]
	v_mfma_f32_16x16x32_bf16 v[8:11], v[160:163], v[228:231], v[8:11]
	v_mfma_f32_16x16x32_bf16 v[60:63], v[156:159], v[208:211], v[60:63]
	v_mfma_f32_16x16x32_bf16 v[56:59], v[164:167], v[208:211], v[56:59]
	v_mfma_f32_16x16x32_bf16 v[44:47], v[156:159], v[216:219], v[44:47]
	v_mfma_f32_16x16x32_bf16 v[40:43], v[164:167], v[216:219], v[40:43]
	v_mfma_f32_16x16x32_bf16 v[28:31], v[156:159], v[224:227], v[28:31]
	v_mfma_f32_16x16x32_bf16 v[24:27], v[164:167], v[224:227], v[24:27]
	v_mfma_f32_16x16x32_bf16 v[12:15], v[156:159], v[232:235], v[12:15]
	v_mfma_f32_16x16x32_bf16 v[8:11], v[164:167], v[232:235], v[8:11]
	v_mfma_f32_16x16x32_bf16 v[52:55], v[168:171], v[204:207], v[52:55]
	v_mfma_f32_16x16x32_bf16 v[48:51], v[196:199], v[204:207], v[48:51]
	v_mfma_f32_16x16x32_bf16 v[36:39], v[168:171], v[212:215], v[36:39]
	v_mfma_f32_16x16x32_bf16 v[32:35], v[196:199], v[212:215], v[32:35]
	v_mfma_f32_16x16x32_bf16 v[20:23], v[168:171], v[220:223], v[20:23]
	v_mfma_f32_16x16x32_bf16 v[16:19], v[196:199], v[220:223], v[16:19]
	v_mfma_f32_16x16x32_bf16 v[4:7], v[168:171], v[228:231], v[4:7]
	v_mfma_f32_16x16x32_bf16 v[0:3], v[196:199], v[228:231], v[0:3]
	v_mfma_f32_16x16x32_bf16 v[52:55], v[192:195], v[208:211], v[52:55]
	v_mfma_f32_16x16x32_bf16 v[48:51], v[200:203], v[208:211], v[48:51]
	v_mfma_f32_16x16x32_bf16 v[36:39], v[192:195], v[216:219], v[36:39]
	v_mfma_f32_16x16x32_bf16 v[32:35], v[200:203], v[216:219], v[32:35]
	v_mfma_f32_16x16x32_bf16 v[20:23], v[192:195], v[224:227], v[20:23]
	v_mfma_f32_16x16x32_bf16 v[16:19], v[200:203], v[224:227], v[16:19]
	v_mfma_f32_16x16x32_bf16 v[4:7], v[192:195], v[232:235], v[4:7]
	v_mfma_f32_16x16x32_bf16 v[0:3], v[200:203], v[232:235], v[0:3]
	s_setprio 0
	s_barrier
	s_add_i32 s45, s45, 2
	s_add_u32 s60, s60, 0x100
	s_addc_u32 s61, s61, 0
	s_add_u32 s33, s33, 0x100
	s_addc_u32 s44, s44, 0
	s_cmp_gt_u32 s45, 13
.LBB0_44:
	s_add_u32 s24, s60, 0xfffc0080
	s_addc_u32 s25, s61, -1
	s_add_i32 s47, 0, 0x10000
	s_cmp_eq_u32 s45, 12
	s_cselect_b32 s65, s1, s25
	s_cselect_b32 s64, s12, s24
	v_add_u32_e32 v150, s47, v153
	s_cselect_b32 s63, s3, s44
	s_cselect_b32 s62, s22, s33
	s_add_i32 s50, 0, 0x14000
	ds_read_b128 v[146:149], v150
	ds_read_b128 v[156:159], v150 offset:1024
	ds_read_b128 v[160:163], v150 offset:2048
	ds_read_b128 v[164:167], v150 offset:3072
	v_add_u32_e32 v150, s50, v153
	ds_read_b128 v[168:171], v150
	ds_read_b128 v[192:195], v150 offset:1024
	ds_read_b128 v[196:199], v150 offset:2048
	ds_read_b128 v[200:203], v150 offset:3072
	v_lshl_add_u64 v[150:151], s[60:61], 0, v[142:143]
	s_add_i32 m0, s68, 0xc000
	ds_read_b128 v[204:207], v155
	ds_read_b128 v[208:211], v155 offset:1024
	ds_read_b128 v[212:215], v155 offset:2048
	ds_read_b128 v[216:219], v155 offset:3072
	ds_read_b128 v[220:223], v155 offset:4096
	ds_read_b128 v[224:227], v155 offset:5120
	ds_read_b128 v[228:231], v155 offset:6144
	ds_read_b128 v[232:235], v155 offset:7168
	global_load_lds_dwordx4 v[150:151], off
	v_lshl_add_u64 v[150:151], s[60:61], 0, v[144:145]
	s_add_i32 m0, s68, 0xe000
	s_nop 0
	global_load_lds_dwordx4 v[150:151], off
	s_waitcnt vmcnt(8)
	s_waitcnt lgkmcnt(0)
	s_barrier
; #define PG8_STAGE(bufoff, gbase, voff) do { _Pragma("unroll") for (int _i = 0; _i < 2; ++_i) \
;         __builtin_amdgcn_global_load_lds((const unsigned*)((const char*)(gbase) + (voff)[_i]), (PG8_LAS unsigned*)(lds + (bufoff) + ldsw + _i * 8192), 16, 0, 0); } while (0)
; #define PG8_LDA(dst, b, h) do { _Pragma("unroll") for (int m = 0; m < 4; ++m) _Pragma("unroll") for (int k = 0; k < 2; ++k) dst[m][k] = *(const PG8_LAS bf16x8*)(lds + PG8_SA(b, h) + aoff + m * 2048 + k * 1024); } while (0)
; #define PG8_MMA(ai, bj, At, Bt) do { __builtin_amdgcn_s_setprio(1); _Pragma("unroll") for (int m = 0; m < 4; ++m) _Pragma("unroll") for (int n = 0; n < 2; ++n) _Pragma("unroll") for (int k = 0; k < 2; ++k) \
;         acc[ai][bj][m][n] = __builtin_amdgcn_mfma_f32_16x16x32_bf16(Bt[n][k], At[m][k], acc[ai][bj][m][n], 0, 0, 0); __builtin_amdgcn_s_setprio(0); } while (0)
; #define PG8_WAIT_V(n) asm volatile("s_waitcnt vmcnt(" #n ")" ::: "memory")
; #define PG8_WAIT_L(n) asm volatile("s_waitcnt lgkmcnt(" #n ")" ::: "memory")
; #define PG8_BAR __builtin_amdgcn_s_barrier()
; #define PG8_SCHED __builtin_amdgcn_sched_barrier(0)
; template <class Epi, class Sched, bool ALIGN_EPI = false, bool SP2 = false>
; __device__ __forceinline__ void gemm_phase(PG8_LAS unsigned char* lds, const Gemm g, const Sched& S, const Epi& E) {
;     ...
;             PG8_WAIT_V(8); PG8_WAIT_L(0); PG8_BAR; PG8_MMA(0, 0, At, B0); PG8_MMA(0, 1, At, B1); PG8_BAR; PG8_SCHED;
;             PG8_LDA(At, 0, 1); PG8_STAGE(PG8_SB(0, 0), b2, voffB); PG8_STAGE(PG8_SB(0, 1), b2 + hstep, voffB); PG8_STAGE(PG8_SA(0, 0), a2, voffA);
;             PG8_WAIT_V(8); PG8_WAIT_L(0); PG8_BAR; PG8_MMA(1, 0, At, B0); PG8_MMA(1, 1, At, B1); PG8_BAR; PG8_SCHED;
	s_setprio 1
	s_waitcnt lgkmcnt(0)
	v_mfma_f32_16x16x32_bf16 v[124:127], v[146:149], v[204:207], v[124:127]
	v_mfma_f32_16x16x32_bf16 v[120:123], v[160:163], v[204:207], v[120:123]
	v_mfma_f32_16x16x32_bf16 v[108:111], v[146:149], v[212:215], v[108:111]
	v_mfma_f32_16x16x32_bf16 v[104:107], v[160:163], v[212:215], v[104:107]
	v_mfma_f32_16x16x32_bf16 v[92:95], v[146:149], v[220:223], v[92:95]
	v_mfma_f32_16x16x32_bf16 v[88:91], v[160:163], v[220:223], v[88:91]
	v_mfma_f32_16x16x32_bf16 v[76:79], v[146:149], v[228:231], v[76:79]
	v_mfma_f32_16x16x32_bf16 v[72:75], v[160:163], v[228:231], v[72:75]
	v_mfma_f32_16x16x32_bf16 v[124:127], v[156:159], v[208:211], v[124:127]
	v_mfma_f32_16x16x32_bf16 v[120:123], v[164:167], v[208:211], v[120:123]
	v_mfma_f32_16x16x32_bf16 v[108:111], v[156:159], v[216:219], v[108:111]
	v_mfma_f32_16x16x32_bf16 v[104:107], v[164:167], v[216:219], v[104:107]
	v_mfma_f32_16x16x32_bf16 v[92:95], v[156:159], v[224:227], v[92:95]
	v_mfma_f32_16x16x32_bf16 v[88:91], v[164:167], v[224:227], v[88:91]
	v_mfma_f32_16x16x32_bf16 v[76:79], v[156:159], v[232:235], v[76:79]
	v_mfma_f32_16x16x32_bf16 v[72:75], v[164:167], v[232:235], v[72:75]
	v_mfma_f32_16x16x32_bf16 v[116:119], v[168:171], v[204:207], v[116:119]
	v_mfma_f32_16x16x32_bf16 v[112:115], v[196:199], v[204:207], v[112:115]
	v_mfma_f32_16x16x32_bf16 v[100:103], v[168:171], v[212:215], v[100:103]
	v_mfma_f32_16x16x32_bf16 v[96:99], v[196:199], v[212:215], v[96:99]
	v_mfma_f32_16x16x32_bf16 v[84:87], v[168:171], v[220:223], v[84:87]
	v_mfma_f32_16x16x32_bf16 v[80:83], v[196:199], v[220:223], v[80:83]
	v_mfma_f32_16x16x32_bf16 v[68:71], v[168:171], v[228:231], v[68:71]
	v_mfma_f32_16x16x32_bf16 v[64:67], v[196:199], v[228:231], v[64:67]
	v_mfma_f32_16x16x32_bf16 v[116:119], v[192:195], v[208:211], v[116:119]
	v_mfma_f32_16x16x32_bf16 v[112:115], v[200:203], v[208:211], v[112:115]
	v_mfma_f32_16x16x32_bf16 v[100:103], v[192:195], v[216:219], v[100:103]
	v_mfma_f32_16x16x32_bf16 v[96:99], v[200:203], v[216:219], v[96:99]
	v_mfma_f32_16x16x32_bf16 v[84:87], v[192:195], v[224:227], v[84:87]
	v_mfma_f32_16x16x32_bf16 v[80:83], v[200:203], v[224:227], v[80:83]
	v_mfma_f32_16x16x32_bf16 v[68:71], v[192:195], v[232:235], v[68:71]
	v_mfma_f32_16x16x32_bf16 v[64:67], v[200:203], v[232:235], v[64:67]
	s_setprio 0
	s_barrier
	s_add_i32 s24, s47, s66
	v_lshl_add_u64 v[150:151], s[62:63], 0, v[132:133]
	s_mov_b32 m0, s24
	ds_read_b128 v[204:207], v155 offset:16384
	ds_read_b128 v[208:211], v155 offset:17408
	ds_read_b128 v[212:215], v155 offset:18432
	ds_read_b128 v[216:219], v155 offset:19456
	ds_read_b128 v[220:223], v155 offset:20480
	ds_read_b128 v[224:227], v155 offset:21504
	ds_read_b128 v[228:231], v155 offset:22528
	ds_read_b128 v[232:235], v155 offset:23552
	global_load_lds_dwordx4 v[150:151], off
	s_add_i32 m0, s24, 0x2000
	s_add_u32 s24, s62, 0x40000
	v_lshl_add_u64 v[236:237], s[62:63], 0, v[128:129]
	s_addc_u32 s25, s63, 0
	s_add_i32 s47, s50, s66
	global_load_lds_dwordx4 v[236:237], off
	v_lshl_add_u64 v[238:239], s[24:25], 0, v[132:133]
	s_mov_b32 m0, s47
	v_lshl_add_u64 v[240:241], s[64:65], 0, v[130:131]
	global_load_lds_dwordx4 v[238:239], off
	v_lshl_add_u64 v[238:239], s[24:25], 0, v[128:129]
	s_add_i32 m0, s47, 0x2000
	s_nop 0
	global_load_lds_dwordx4 v[238:239], off
	v_lshl_add_u64 v[238:239], s[64:65], 0, v[140:141]
	s_mov_b32 m0, s68
	s_nop 0
	global_load_lds_dwordx4 v[238:239], off
	s_mov_b32 m0, s69
	s_nop 0
	global_load_lds_dwordx4 v[240:241], off
	s_waitcnt vmcnt(8)
	s_waitcnt lgkmcnt(0)
	s_barrier
	s_setprio 1
	s_waitcnt lgkmcnt(0)
	v_mfma_f32_16x16x32_bf16 v[60:63], v[146:149], v[204:207], v[60:63]
	v_mfma_f32_16x16x32_bf16 v[56:59], v[160:163], v[204:207], v[56:59]
	v_mfma_f32_16x16x32_bf16 v[44:47], v[146:149], v[212:215], v[44:47]
	v_mfma_f32_16x16x32_bf16 v[40:43], v[160:163], v[212:215], v[40:43]
	v_mfma_f32_16x16x32_bf16 v[28:31], v[146:149], v[220:223], v[28:31]
	v_mfma_f32_16x16x32_bf16 v[24:27], v[160:163], v[220:223], v[24:27]
	v_mfma_f32_16x16x32_bf16 v[12:15], v[146:149], v[228:231], v[12:15]
	v_mfma_f32_16x16x32_bf16 v[8:11], v[160:163], v[228:231], v[8:11]
	v_mfma_f32_16x16x32_bf16 v[60:63], v[156:159], v[208:211], v[60:63]
	v_mfma_f32_16x16x32_bf16 v[56:59], v[164:167], v[208:211], v[56:59]
	v_mfma_f32_16x16x32_bf16 v[44:47], v[156:159], v[216:219], v[44:47]
	v_mfma_f32_16x16x32_bf16 v[40:43], v[164:167], v[216:219], v[40:43]
	v_mfma_f32_16x16x32_bf16 v[28:31], v[156:159], v[224:227], v[28:31]
	v_mfma_f32_16x16x32_bf16 v[24:27], v[164:167], v[224:227], v[24:27]
	v_mfma_f32_16x16x32_bf16 v[12:15], v[156:159], v[232:235], v[12:15]
	v_mfma_f32_16x16x32_bf16 v[8:11], v[164:167], v[232:235], v[8:11]
	v_mfma_f32_16x16x32_bf16 v[52:55], v[168:171], v[204:207], v[52:55]
	v_mfma_f32_16x16x32_bf16 v[48:51], v[196:199], v[204:207], v[48:51]
	v_mfma_f32_16x16x32_bf16 v[36:39], v[168:171], v[212:215], v[36:39]
	v_mfma_f32_16x16x32_bf16 v[32:35], v[196:199], v[212:215], v[32:35]
	v_mfma_f32_16x16x32_bf16 v[20:23], v[168:171], v[220:223], v[20:23]
	v_mfma_f32_16x16x32_bf16 v[16:19], v[196:199], v[220:223], v[16:19]
	v_mfma_f32_16x16x32_bf16 v[4:7], v[168:171], v[228:231], v[4:7]
	v_mfma_f32_16x16x32_bf16 v[0:3], v[196:199], v[228:231], v[0:3]
	v_mfma_f32_16x16x32_bf16 v[52:55], v[192:195], v[208:211], v[52:55]
	v_mfma_f32_16x16x32_bf16 v[48:51], v[200:203], v[208:211], v[48:51]
	v_mfma_f32_16x16x32_bf16 v[36:39], v[192:195], v[216:219], v[36:39]
	v_mfma_f32_16x16x32_bf16 v[32:35], v[200:203], v[216:219], v[32:35]
	v_mfma_f32_16x16x32_bf16 v[20:23], v[192:195], v[224:227], v[20:23]
	v_mfma_f32_16x16x32_bf16 v[16:19], v[200:203], v[224:227], v[16:19]
	v_mfma_f32_16x16x32_bf16 v[4:7], v[192:195], v[232:235], v[4:7]
	v_mfma_f32_16x16x32_bf16 v[0:3], v[200:203], v[232:235], v[0:3]
	s_setprio 0
	s_barrier
; #define PG8_STAGE(bufoff, gbase, voff) do { _Pragma("unroll") for (int _i = 0; _i < 2; ++_i) \
;         __builtin_amdgcn_global_load_lds((const unsigned*)((const char*)(gbase) + (voff)[_i]), (PG8_LAS unsigned*)(lds + (bufoff) + ldsw + _i * 8192), 16, 0, 0); } while (0)
; #define PG8_LDA(dst, b, h) do { _Pragma("unroll") for (int m = 0; m < 4; ++m) _Pragma("unroll") for (int k = 0; k < 2; ++k) dst[m][k] = *(const PG8_LAS bf16x8*)(lds + PG8_SA(b, h) + aoff + m * 2048 + k * 1024); } while (0)
; #define PG8_LDB(dst, b, h) do { _Pragma("unroll") for (int n = 0; n < 2; ++n) _Pragma("unroll") for (int k = 0; k < 2; ++k) dst[n][k] = *(const PG8_LAS bf16x8*)(lds + PG8_SB(b, h) + boff + n * 2048 + k * 1024); } while (0)
; #define PG8_MMA(ai, bj, At, Bt) do { __builtin_amdgcn_s_setprio(1); _Pragma("unroll") for (int m = 0; m < 4; ++m) _Pragma("unroll") for (int n = 0; n < 2; ++n) _Pragma("unroll") for (int k = 0; k < 2; ++k) \
;         acc[ai][bj][m][n] = __builtin_amdgcn_mfma_f32_16x16x32_bf16(Bt[n][k], At[m][k], acc[ai][bj][m][n], 0, 0, 0); __builtin_amdgcn_s_setprio(0); } while (0)
; #define PG8_WAIT_V(n) asm volatile("s_waitcnt vmcnt(" #n ")" ::: "memory")
; #define PG8_WAIT_L(n) asm volatile("s_waitcnt lgkmcnt(" #n ")" ::: "memory")
; #define PG8_BAR __builtin_amdgcn_s_barrier()
; #define PG8_SCHED __builtin_amdgcn_sched_barrier(0)
; template <class Epi, class Sched, bool ALIGN_EPI = false, bool SP2 = false>
; __device__ __forceinline__ void gemm_phase(PG8_LAS unsigned char* lds, const Gemm g, const Sched& S, const Epi& E) {
;     ...
;             PG8_LDB(B0, 1, 0); PG8_LDB(B1, 1, 1); PG8_SCHED; PG8_LDA(At, 1, 0); PG8_STAGE(PG8_SA(0, 1), a2 + hstep, voffA);
;             PG8_WAIT_V(8); PG8_WAIT_L(0); PG8_BAR; PG8_MMA(0, 0, At, B0); PG8_MMA(0, 1, At, B1); PG8_BAR; PG8_SCHED;
	s_add_i32 s47, 0, 0x18000
	s_add_i32 s50, 0, 0x1c000
	v_add_u32_e32 v164, s47, v153
	v_add_u32_e32 v184, s50, v153
	ds_read_b128 v[146:149], v164
	ds_read_b128 v[156:159], v164 offset:1024
	ds_read_b128 v[160:163], v164 offset:2048
	ds_read_b128 v[164:167], v164 offset:3072
	ds_read_b128 v[168:171], v184
	ds_read_b128 v[192:195], v184 offset:1024
	ds_read_b128 v[196:199], v184 offset:2048
	ds_read_b128 v[200:203], v184 offset:3072
	s_add_u32 s24, s64, 0x40000
	s_addc_u32 s25, s65, 0
	s_mov_b32 m0, s71
	v_lshl_add_u64 v[242:243], s[24:25], 0, v[140:141]
	ds_read_b128 v[204:207], v155 offset:32768
	ds_read_b128 v[208:211], v155 offset:33792
	ds_read_b128 v[212:215], v155 offset:34816
	ds_read_b128 v[216:219], v155 offset:35840
	ds_read_b128 v[220:223], v155 offset:36864
	ds_read_b128 v[224:227], v155 offset:37888
	ds_read_b128 v[228:231], v155 offset:38912
	ds_read_b128 v[232:235], v155 offset:39936
	global_load_lds_dwordx4 v[242:243], off
	v_lshl_add_u64 v[242:243], s[24:25], 0, v[130:131]
	s_mov_b32 m0, s87
	s_nop 0
	global_load_lds_dwordx4 v[242:243], off
	s_waitcnt vmcnt(8)
	s_waitcnt lgkmcnt(0)
	s_barrier
	s_setprio 1
	s_waitcnt lgkmcnt(0)
	v_mfma_f32_16x16x32_bf16 v[124:127], v[146:149], v[204:207], v[124:127]
	v_mfma_f32_16x16x32_bf16 v[120:123], v[160:163], v[204:207], v[120:123]
	v_mfma_f32_16x16x32_bf16 v[108:111], v[146:149], v[212:215], v[108:111]
	v_mfma_f32_16x16x32_bf16 v[104:107], v[160:163], v[212:215], v[104:107]
	v_mfma_f32_16x16x32_bf16 v[92:95], v[146:149], v[220:223], v[92:95]
	v_mfma_f32_16x16x32_bf16 v[88:91], v[160:163], v[220:223], v[88:91]
	v_mfma_f32_16x16x32_bf16 v[76:79], v[146:149], v[228:231], v[76:79]
	v_mfma_f32_16x16x32_bf16 v[72:75], v[160:163], v[228:231], v[72:75]
	v_mfma_f32_16x16x32_bf16 v[124:127], v[156:159], v[208:211], v[124:127]
	v_mfma_f32_16x16x32_bf16 v[120:123], v[164:167], v[208:211], v[120:123]
	v_mfma_f32_16x16x32_bf16 v[108:111], v[156:159], v[216:219], v[108:111]
	v_mfma_f32_16x16x32_bf16 v[104:107], v[164:167], v[216:219], v[104:107]
	v_mfma_f32_16x16x32_bf16 v[92:95], v[156:159], v[224:227], v[92:95]
	v_mfma_f32_16x16x32_bf16 v[88:91], v[164:167], v[224:227], v[88:91]
	v_mfma_f32_16x16x32_bf16 v[76:79], v[156:159], v[232:235], v[76:79]
	v_mfma_f32_16x16x32_bf16 v[72:75], v[164:167], v[232:235], v[72:75]
	v_mfma_f32_16x16x32_bf16 v[116:119], v[168:171], v[204:207], v[116:119]
	v_mfma_f32_16x16x32_bf16 v[112:115], v[196:199], v[204:207], v[112:115]
	v_mfma_f32_16x16x32_bf16 v[100:103], v[168:171], v[212:215], v[100:103]
	v_mfma_f32_16x16x32_bf16 v[96:99], v[196:199], v[212:215], v[96:99]
	v_mfma_f32_16x16x32_bf16 v[84:87], v[168:171], v[220:223], v[84:87]
	v_mfma_f32_16x16x32_bf16 v[80:83], v[196:199], v[220:223], v[80:83]
	v_mfma_f32_16x16x32_bf16 v[68:71], v[168:171], v[228:231], v[68:71]
	v_mfma_f32_16x16x32_bf16 v[64:67], v[196:199], v[228:231], v[64:67]
	v_mfma_f32_16x16x32_bf16 v[116:119], v[192:195], v[208:211], v[116:119]
	v_mfma_f32_16x16x32_bf16 v[112:115], v[200:203], v[208:211], v[112:115]
	v_mfma_f32_16x16x32_bf16 v[100:103], v[192:195], v[216:219], v[100:103]
	v_mfma_f32_16x16x32_bf16 v[96:99], v[200:203], v[216:219], v[96:99]
	v_mfma_f32_16x16x32_bf16 v[84:87], v[192:195], v[224:227], v[84:87]
	v_mfma_f32_16x16x32_bf16 v[80:83], v[200:203], v[224:227], v[80:83]
	v_mfma_f32_16x16x32_bf16 v[68:71], v[192:195], v[232:235], v[68:71]
	v_mfma_f32_16x16x32_bf16 v[64:67], v[200:203], v[232:235], v[64:67]
	s_setprio 0
	s_barrier
; #define PG8_STAGE(bufoff, gbase, voff) do { _Pragma("unroll") for (int _i = 0; _i < 2; ++_i) \
;         __builtin_amdgcn_global_load_lds((const unsigned*)((const char*)(gbase) + (voff)[_i]), (PG8_LAS unsigned*)(lds + (bufoff) + ldsw + _i * 8192), 16, 0, 0); } while (0)
; #define PG8_LDA(dst, b, h) do { _Pragma("unroll") for (int m = 0; m < 4; ++m) _Pragma("unroll") for (int k = 0; k < 2; ++k) dst[m][k] = *(const PG8_LAS bf16x8*)(lds + PG8_SA(b, h) + aoff + m * 2048 + k * 1024); } while (0)
; #define PG8_MMA(ai, bj, At, Bt) do { __builtin_amdgcn_s_setprio(1); _Pragma("unroll") for (int m = 0; m < 4; ++m) _Pragma("unroll") for (int n = 0; n < 2; ++n) _Pragma("unroll") for (int k = 0; k < 2; ++k) \
;         acc[ai][bj][m][n] = __builtin_amdgcn_mfma_f32_16x16x32_bf16(Bt[n][k], At[m][k], acc[ai][bj][m][n], 0, 0, 0); __builtin_amdgcn_s_setprio(0); } while (0)
; #define PG8_WAIT_V(n) asm volatile("s_waitcnt vmcnt(" #n ")" ::: "memory")
; #define PG8_WAIT_L(n) asm volatile("s_waitcnt lgkmcnt(" #n ")" ::: "memory")
; #define PG8_BAR __builtin_amdgcn_s_barrier()
; #define PG8_SCHED __builtin_amdgcn_sched_barrier(0)
; template <class Epi, class Sched, bool ALIGN_EPI = false, bool SP2 = false>
; __device__ __forceinline__ void gemm_phase(PG8_LAS unsigned char* lds, const Gemm g, const Sched& S, const Epi& E) {
;     ...
;             PG8_LDA(At, 1, 1); PG8_STAGE(PG8_SB(1, 0), b3, voffB); PG8_STAGE(PG8_SB(1, 1), b3 + hstep, voffB); PG8_STAGE(PG8_SA(1, 0), a3, voffA);
;             PG8_WAIT_V(8); PG8_WAIT_L(0); PG8_BAR; PG8_MMA(1, 0, At, B0); PG8_MMA(1, 1, At, B1); PG8_BAR; PG8_SCHED;
;     ...
;         if constexpr (ALIGN_EPI) { if (wr == 0) PG8_BAR; }
	s_add_i32 s24, s47, s66
	v_lshl_add_u64 v[150:151], v[150:151], 0, s[14:15]
	s_mov_b32 m0, s24
	ds_read_b128 v[204:207], v155 offset:49152
	ds_read_b128 v[208:211], v155 offset:50176
	ds_read_b128 v[212:215], v155 offset:51200
	ds_read_b128 v[216:219], v155 offset:52224
	ds_read_b128 v[220:223], v155 offset:53248
	ds_read_b128 v[224:227], v155 offset:54272
	ds_read_b128 v[228:231], v155 offset:55296
	ds_read_b128 v[232:235], v155 offset:56320
	global_load_lds_dwordx4 v[150:151], off
	s_add_i32 m0, s24, 0x2000
	s_add_u32 s24, s62, 0x40080
	v_lshl_add_u64 v[150:151], v[236:237], 0, s[14:15]
	s_addc_u32 s25, s63, 0
	s_add_i32 s47, s50, s66
	global_load_lds_dwordx4 v[150:151], off
	v_lshl_add_u64 v[150:151], s[24:25], 0, v[132:133]
	s_mov_b32 m0, s47
	s_nop 0
	global_load_lds_dwordx4 v[150:151], off
	v_lshl_add_u64 v[150:151], s[24:25], 0, v[128:129]
	s_add_i32 m0, s47, 0x2000
	s_nop 0
	global_load_lds_dwordx4 v[150:151], off
	v_lshl_add_u64 v[150:151], v[238:239], 0, s[14:15]
	s_mov_b32 m0, s88
	s_nop 0
	global_load_lds_dwordx4 v[150:151], off
	v_lshl_add_u64 v[150:151], v[240:241], 0, s[14:15]
	s_mov_b32 m0, s89
	s_nop 0
	global_load_lds_dwordx4 v[150:151], off
	s_waitcnt vmcnt(8)
	s_waitcnt lgkmcnt(0)
	s_barrier
	s_setprio 1
	s_waitcnt lgkmcnt(0)
	v_mfma_f32_16x16x32_bf16 v[60:63], v[146:149], v[204:207], v[60:63]
	v_mfma_f32_16x16x32_bf16 v[56:59], v[160:163], v[204:207], v[56:59]
	v_mfma_f32_16x16x32_bf16 v[44:47], v[146:149], v[212:215], v[44:47]
	v_mfma_f32_16x16x32_bf16 v[40:43], v[160:163], v[212:215], v[40:43]
	v_mfma_f32_16x16x32_bf16 v[28:31], v[146:149], v[220:223], v[28:31]
	v_mfma_f32_16x16x32_bf16 v[24:27], v[160:163], v[220:223], v[24:27]
	v_mfma_f32_16x16x32_bf16 v[12:15], v[146:149], v[228:231], v[12:15]
	v_mfma_f32_16x16x32_bf16 v[8:11], v[160:163], v[228:231], v[8:11]
	v_mfma_f32_16x16x32_bf16 v[60:63], v[156:159], v[208:211], v[60:63]
	v_mfma_f32_16x16x32_bf16 v[56:59], v[164:167], v[208:211], v[56:59]
	v_mfma_f32_16x16x32_bf16 v[44:47], v[156:159], v[216:219], v[44:47]
	v_mfma_f32_16x16x32_bf16 v[40:43], v[164:167], v[216:219], v[40:43]
	v_mfma_f32_16x16x32_bf16 v[28:31], v[156:159], v[224:227], v[28:31]
	v_mfma_f32_16x16x32_bf16 v[24:27], v[164:167], v[224:227], v[24:27]
	v_mfma_f32_16x16x32_bf16 v[12:15], v[156:159], v[232:235], v[12:15]
	v_mfma_f32_16x16x32_bf16 v[8:11], v[164:167], v[232:235], v[8:11]
	v_mfma_f32_16x16x32_bf16 v[52:55], v[168:171], v[204:207], v[52:55]
	v_mfma_f32_16x16x32_bf16 v[48:51], v[196:199], v[204:207], v[48:51]
	v_mfma_f32_16x16x32_bf16 v[36:39], v[168:171], v[212:215], v[36:39]
	v_mfma_f32_16x16x32_bf16 v[32:35], v[196:199], v[212:215], v[32:35]
	v_mfma_f32_16x16x32_bf16 v[20:23], v[168:171], v[220:223], v[20:23]
	v_mfma_f32_16x16x32_bf16 v[16:19], v[196:199], v[220:223], v[16:19]
	v_mfma_f32_16x16x32_bf16 v[4:7], v[168:171], v[228:231], v[4:7]
	v_mfma_f32_16x16x32_bf16 v[0:3], v[196:199], v[228:231], v[0:3]
	v_mfma_f32_16x16x32_bf16 v[52:55], v[192:195], v[208:211], v[52:55]
	v_mfma_f32_16x16x32_bf16 v[48:51], v[200:203], v[208:211], v[48:51]
	v_mfma_f32_16x16x32_bf16 v[36:39], v[192:195], v[216:219], v[36:39]
	v_mfma_f32_16x16x32_bf16 v[32:35], v[200:203], v[216:219], v[32:35]
	v_mfma_f32_16x16x32_bf16 v[20:23], v[192:195], v[224:227], v[20:23]
	v_mfma_f32_16x16x32_bf16 v[16:19], v[200:203], v[224:227], v[16:19]
	v_mfma_f32_16x16x32_bf16 v[4:7], v[192:195], v[232:235], v[4:7]
	v_mfma_f32_16x16x32_bf16 v[0:3], v[200:203], v[232:235], v[0:3]
	s_setprio 0
	s_barrier
	s_add_i32 s45, s45, 2
	s_add_u32 s60, s60, 0x100
	s_addc_u32 s61, s61, 0
	s_add_u32 s33, s33, 0x100
	s_addc_u32 s44, s44, 0
	s_cmp_gt_u32 s45, 13
	s_cbranch_scc0 .LBB0_44
	s_and_b64 vcc, exec, s[20:21]
	s_cbranch_vccz .LBB0_47
	s_barrier

; #define PG8_STAGE(bufoff, gbase, voff) do { _Pragma("unroll") for (int _i = 0; _i < 2; ++_i) \
;         __builtin_amdgcn_global_load_lds((const unsigned*)((const char*)(gbase) + (voff)[_i]), (PG8_LAS unsigned*)(lds + (bufoff) + ldsw + _i * 8192), 16, 0, 0); } while (0)
; #define PG8_LDA(dst, b, h) do { _Pragma("unroll") for (int m = 0; m < 4; ++m) _Pragma("unroll") for (int k = 0; k < 2; ++k) dst[m][k] = *(const PG8_LAS bf16x8*)(lds + PG8_SA(b, h) + aoff + m * 2048 + k * 1024); } while (0)
; #define PG8_LDB(dst, b, h) do { _Pragma("unroll") for (int n = 0; n < 2; ++n) _Pragma("unroll") for (int k = 0; k < 2; ++k) dst[n][k] = *(const PG8_LAS bf16x8*)(lds + PG8_SB(b, h) + boff + n * 2048 + k * 1024); } while (0)
; #define PG8_MMA(ai, bj, At, Bt) do { __builtin_amdgcn_s_setprio(1); _Pragma("unroll") for (int m = 0; m < 4; ++m) _Pragma("unroll") for (int n = 0; n < 2; ++n) _Pragma("unroll") for (int k = 0; k < 2; ++k) \
;         acc[ai][bj][m][n] = __builtin_amdgcn_mfma_f32_16x16x32_bf16(Bt[n][k], At[m][k], acc[ai][bj][m][n], 0, 0, 0); __builtin_amdgcn_s_setprio(0); } while (0)
; #define PG8_WAIT_V(n) asm volatile("s_waitcnt vmcnt(" #n ")" ::: "memory")
; #define PG8_WAIT_L(n) asm volatile("s_waitcnt lgkmcnt(" #n ")" ::: "memory")
; #define PG8_BAR __builtin_amdgcn_s_barrier()
; template <class Epi, class Sched, bool ALIGN_EPI = false, bool SP2 = false>
; __device__ __forceinline__ void gemm_phase(PG8_LAS unsigned char* lds, const Gemm g, const Sched& S, const Epi& E) {
;     ...
;             const char* a1 = cA + (size_t)(t + 1) * kstep;
;             const char* a2 = last ? nA : cA + (size_t)(t + 2) * kstep; const char* b2 = last ? nB : cB + (size_t)(t + 2) * kstep;
;             const char* a3 = a2 + kstep; const char* b3 = b2 + kstep;
;             if (last && has_next) S.a_ready(nxt);
;             if constexpr (SP2) {
;             PG8_LDB(B0, 0, 0); PG8_LDB(B1, 0, 1); PG8_SCHED; PG8_LDA(At, 0, 0); PG8_STAGE(PG8_SA(1, 1), a1 + hstep, voffA);
;             PG8_WAIT_V(8); PG8_WAIT_L(0); PG8_BAR; PG8_MMA(0, 0, At, B0); PG8_MMA(0, 1, At, B1); PG8_BAR; PG8_SCHED;
;             PG8_LDA(At, 0, 1); PG8_STAGE(PG8_SB(0, 0), b2, voffB); PG8_STAGE(PG8_SB(0, 1), b2 + hstep, voffB); PG8_STAGE(PG8_SA(0, 0), a2, voffA);
;             PG8_WAIT_V(8); PG8_WAIT_L(0); PG8_BAR; PG8_MMA(1, 0, At, B0); PG8_MMA(1, 1, At, B1); PG8_BAR; PG8_SCHED;
.LBB0_121:
	s_add_u32 s22, s46, 0x100
	s_addc_u32 s33, s47, 0
	s_mov_b32 s50, -2
	s_add_u32 s42, s44, 0x100
	s_addc_u32 s43, s45, 0
	s_add_i32 s24, 0, 0x10000
	s_cmp_eq_u32 s50, 8
	s_cselect_b32 s69, s65, s43
	s_cselect_b32 s68, s64, s42
	s_cselect_b32 s47, s67, s33
	s_cselect_b32 s46, s66, s22
	s_add_i32 s51, 0, 0x14000
	v_add_u32_e32 v162, s24, v150
	v_add_u32_e32 v170, s51, v150
	ds_read_b128 v[146:149], v162
	ds_read_b128 v[154:157], v162 offset:1024
	ds_read_b128 v[158:161], v162 offset:2048
	ds_read_b128 v[162:165], v162 offset:3072
	ds_read_b128 v[166:169], v170
	ds_read_b128 v[192:195], v170 offset:1024
	ds_read_b128 v[196:199], v170 offset:2048
	ds_read_b128 v[200:203], v170 offset:3072
	v_lshl_add_u64 v[170:171], s[44:45], 0, v[142:143]
	s_add_i32 m0, s71, 0xc000
	ds_read_b128 v[204:207], v153
	ds_read_b128 v[208:211], v153 offset:1024
	ds_read_b128 v[212:215], v153 offset:2048
	ds_read_b128 v[216:219], v153 offset:3072
	ds_read_b128 v[220:223], v153 offset:4096
	ds_read_b128 v[224:227], v153 offset:5120
	ds_read_b128 v[228:231], v153 offset:6144
	ds_read_b128 v[232:235], v153 offset:7168
	global_load_lds_dwordx4 v[170:171], off
	v_lshl_add_u64 v[170:171], s[44:45], 0, v[144:145]
	s_add_i32 m0, s71, 0xe000
	s_nop 0
	global_load_lds_dwordx4 v[170:171], off
	s_waitcnt vmcnt(8)
	s_waitcnt lgkmcnt(0)
	s_barrier
	s_setprio 1
	s_waitcnt lgkmcnt(0)
	v_mfma_f32_16x16x32_bf16 v[124:127], v[146:149], v[204:207], 0
	v_mfma_f32_16x16x32_bf16 v[120:123], v[158:161], v[204:207], 0
	v_mfma_f32_16x16x32_bf16 v[108:111], v[146:149], v[212:215], 0
	v_mfma_f32_16x16x32_bf16 v[104:107], v[158:161], v[212:215], 0
	v_mfma_f32_16x16x32_bf16 v[92:95], v[146:149], v[220:223], 0
	v_mfma_f32_16x16x32_bf16 v[88:91], v[158:161], v[220:223], 0
	v_mfma_f32_16x16x32_bf16 v[76:79], v[146:149], v[228:231], 0
	v_mfma_f32_16x16x32_bf16 v[72:75], v[158:161], v[228:231], 0
	v_mfma_f32_16x16x32_bf16 v[124:127], v[154:157], v[208:211], v[124:127]
	v_mfma_f32_16x16x32_bf16 v[120:123], v[162:165], v[208:211], v[120:123]
	v_mfma_f32_16x16x32_bf16 v[108:111], v[154:157], v[216:219], v[108:111]
	v_mfma_f32_16x16x32_bf16 v[104:107], v[162:165], v[216:219], v[104:107]
	v_mfma_f32_16x16x32_bf16 v[92:95], v[154:157], v[224:227], v[92:95]
	v_mfma_f32_16x16x32_bf16 v[88:91], v[162:165], v[224:227], v[88:91]
	v_mfma_f32_16x16x32_bf16 v[76:79], v[154:157], v[232:235], v[76:79]
	v_mfma_f32_16x16x32_bf16 v[72:75], v[162:165], v[232:235], v[72:75]
	v_mfma_f32_16x16x32_bf16 v[116:119], v[166:169], v[204:207], 0
	v_mfma_f32_16x16x32_bf16 v[112:115], v[196:199], v[204:207], 0
	v_mfma_f32_16x16x32_bf16 v[100:103], v[166:169], v[212:215], 0
	v_mfma_f32_16x16x32_bf16 v[96:99], v[196:199], v[212:215], 0
	v_mfma_f32_16x16x32_bf16 v[84:87], v[166:169], v[220:223], 0
	v_mfma_f32_16x16x32_bf16 v[80:83], v[196:199], v[220:223], 0
	v_mfma_f32_16x16x32_bf16 v[68:71], v[166:169], v[228:231], 0
	v_mfma_f32_16x16x32_bf16 v[64:67], v[196:199], v[228:231], 0
	v_mfma_f32_16x16x32_bf16 v[116:119], v[192:195], v[208:211], v[116:119]
	v_mfma_f32_16x16x32_bf16 v[112:115], v[200:203], v[208:211], v[112:115]
	v_mfma_f32_16x16x32_bf16 v[100:103], v[192:195], v[216:219], v[100:103]
	v_mfma_f32_16x16x32_bf16 v[96:99], v[200:203], v[216:219], v[96:99]
	v_mfma_f32_16x16x32_bf16 v[84:87], v[192:195], v[224:227], v[84:87]
	v_mfma_f32_16x16x32_bf16 v[80:83], v[200:203], v[224:227], v[80:83]
	v_mfma_f32_16x16x32_bf16 v[68:71], v[192:195], v[232:235], v[68:71]
	v_mfma_f32_16x16x32_bf16 v[64:67], v[200:203], v[232:235], v[64:67]
	s_setprio 0
	s_barrier
	s_add_i32 s24, s24, s29
	v_lshl_add_u64 v[170:171], s[46:47], 0, v[128:129]
	s_mov_b32 m0, s24
	ds_read_b128 v[204:207], v153 offset:16384
	ds_read_b128 v[208:211], v153 offset:17408
	ds_read_b128 v[212:215], v153 offset:18432
	ds_read_b128 v[216:219], v153 offset:19456
	ds_read_b128 v[220:223], v153 offset:20480
	ds_read_b128 v[224:227], v153 offset:21504
	ds_read_b128 v[228:231], v153 offset:22528
	ds_read_b128 v[232:235], v153 offset:23552
	global_load_lds_dwordx4 v[170:171], off
	s_add_i32 m0, s24, 0x2000
	s_add_u32 s24, s46, 0x30000
	v_lshl_add_u64 v[236:237], s[46:47], 0, v[130:131]
	s_addc_u32 s25, s47, 0
	s_add_i32 s44, s51, s29
	global_load_lds_dwordx4 v[236:237], off
	v_lshl_add_u64 v[238:239], s[24:25], 0, v[128:129]
	s_mov_b32 m0, s44
	v_lshl_add_u64 v[240:241], s[68:69], 0, v[130:131]
	global_load_lds_dwordx4 v[238:239], off
	v_lshl_add_u64 v[238:239], s[24:25], 0, v[130:131]
	s_add_i32 m0, s44, 0x2000
	s_nop 0
	global_load_lds_dwordx4 v[238:239], off
	v_lshl_add_u64 v[238:239], s[68:69], 0, v[128:129]
	s_mov_b32 m0, s71
	s_nop 0
	global_load_lds_dwordx4 v[238:239], off
	s_mov_b32 m0, s87
	s_nop 0
	global_load_lds_dwordx4 v[240:241], off
	s_waitcnt vmcnt(8)
	s_waitcnt lgkmcnt(0)
	s_barrier
; #define PG8_STAGE(bufoff, gbase, voff) do { _Pragma("unroll") for (int _i = 0; _i < 2; ++_i) \
;         __builtin_amdgcn_global_load_lds((const unsigned*)((const char*)(gbase) + (voff)[_i]), (PG8_LAS unsigned*)(lds + (bufoff) + ldsw + _i * 8192), 16, 0, 0); } while (0)
; #define PG8_LDA(dst, b, h) do { _Pragma("unroll") for (int m = 0; m < 4; ++m) _Pragma("unroll") for (int k = 0; k < 2; ++k) dst[m][k] = *(const PG8_LAS bf16x8*)(lds + PG8_SA(b, h) + aoff + m * 2048 + k * 1024); } while (0)
; #define PG8_LDB(dst, b, h) do { _Pragma("unroll") for (int n = 0; n < 2; ++n) _Pragma("unroll") for (int k = 0; k < 2; ++k) dst[n][k] = *(const PG8_LAS bf16x8*)(lds + PG8_SB(b, h) + boff + n * 2048 + k * 1024); } while (0)
; #define PG8_MMA(ai, bj, At, Bt) do { __builtin_amdgcn_s_setprio(1); _Pragma("unroll") for (int m = 0; m < 4; ++m) _Pragma("unroll") for (int n = 0; n < 2; ++n) _Pragma("unroll") for (int k = 0; k < 2; ++k) \
;         acc[ai][bj][m][n] = __builtin_amdgcn_mfma_f32_16x16x32_bf16(Bt[n][k], At[m][k], acc[ai][bj][m][n], 0, 0, 0); __builtin_amdgcn_s_setprio(0); } while (0)
; #define PG8_WAIT_V(n) asm volatile("s_waitcnt vmcnt(" #n ")" ::: "memory")
; #define PG8_WAIT_L(n) asm volatile("s_waitcnt lgkmcnt(" #n ")" ::: "memory")
; #define PG8_BAR __builtin_amdgcn_s_barrier()
; #define PG8_SCHED __builtin_amdgcn_sched_barrier(0)
; template <class Epi, class Sched, bool ALIGN_EPI = false, bool SP2 = false>
; __device__ __forceinline__ void gemm_phase(PG8_LAS unsigned char* lds, const Gemm g, const Sched& S, const Epi& E) {
;     ...
;             PG8_WAIT_V(8); PG8_WAIT_L(0); PG8_BAR; PG8_MMA(1, 0, At, B0); PG8_MMA(1, 1, At, B1); PG8_BAR; PG8_SCHED;
;             PG8_LDB(B0, 1, 0); PG8_LDB(B1, 1, 1); PG8_SCHED; PG8_LDA(At, 1, 0); PG8_STAGE(PG8_SA(0, 1), a2 + hstep, voffA);
;             PG8_WAIT_V(8); PG8_WAIT_L(0); PG8_BAR; PG8_MMA(0, 0, At, B0); PG8_MMA(0, 1, At, B1); PG8_BAR; PG8_SCHED;
	s_setprio 1
	s_waitcnt lgkmcnt(0)
	v_mfma_f32_16x16x32_bf16 v[60:63], v[146:149], v[204:207], 0
	v_mfma_f32_16x16x32_bf16 v[56:59], v[158:161], v[204:207], 0
	v_mfma_f32_16x16x32_bf16 v[44:47], v[146:149], v[212:215], 0
	v_mfma_f32_16x16x32_bf16 v[40:43], v[158:161], v[212:215], 0
	v_mfma_f32_16x16x32_bf16 v[28:31], v[146:149], v[220:223], 0
	v_mfma_f32_16x16x32_bf16 v[24:27], v[158:161], v[220:223], 0
	v_mfma_f32_16x16x32_bf16 v[12:15], v[146:149], v[228:231], 0
	v_mfma_f32_16x16x32_bf16 v[8:11], v[158:161], v[228:231], 0
	v_mfma_f32_16x16x32_bf16 v[60:63], v[154:157], v[208:211], v[60:63]
	v_mfma_f32_16x16x32_bf16 v[56:59], v[162:165], v[208:211], v[56:59]
	v_mfma_f32_16x16x32_bf16 v[44:47], v[154:157], v[216:219], v[44:47]
	v_mfma_f32_16x16x32_bf16 v[40:43], v[162:165], v[216:219], v[40:43]
	v_mfma_f32_16x16x32_bf16 v[28:31], v[154:157], v[224:227], v[28:31]
	v_mfma_f32_16x16x32_bf16 v[24:27], v[162:165], v[224:227], v[24:27]
	v_mfma_f32_16x16x32_bf16 v[12:15], v[154:157], v[232:235], v[12:15]
	v_mfma_f32_16x16x32_bf16 v[8:11], v[162:165], v[232:235], v[8:11]
	v_mfma_f32_16x16x32_bf16 v[52:55], v[166:169], v[204:207], 0
	v_mfma_f32_16x16x32_bf16 v[48:51], v[196:199], v[204:207], 0
	v_mfma_f32_16x16x32_bf16 v[36:39], v[166:169], v[212:215], 0
	v_mfma_f32_16x16x32_bf16 v[32:35], v[196:199], v[212:215], 0
	v_mfma_f32_16x16x32_bf16 v[20:23], v[166:169], v[220:223], 0
	v_mfma_f32_16x16x32_bf16 v[16:19], v[196:199], v[220:223], 0
	v_mfma_f32_16x16x32_bf16 v[4:7], v[166:169], v[228:231], 0
	v_mfma_f32_16x16x32_bf16 v[0:3], v[196:199], v[228:231], 0
	v_mfma_f32_16x16x32_bf16 v[52:55], v[192:195], v[208:211], v[52:55]
	v_mfma_f32_16x16x32_bf16 v[48:51], v[200:203], v[208:211], v[48:51]
	v_mfma_f32_16x16x32_bf16 v[36:39], v[192:195], v[216:219], v[36:39]
	v_mfma_f32_16x16x32_bf16 v[32:35], v[200:203], v[216:219], v[32:35]
	v_mfma_f32_16x16x32_bf16 v[20:23], v[192:195], v[224:227], v[20:23]
	v_mfma_f32_16x16x32_bf16 v[16:19], v[200:203], v[224:227], v[16:19]
	v_mfma_f32_16x16x32_bf16 v[4:7], v[192:195], v[232:235], v[4:7]
	v_mfma_f32_16x16x32_bf16 v[0:3], v[200:203], v[232:235], v[0:3]
	s_setprio 0
	s_barrier
	s_add_i32 s44, 0, 0x18000
	s_add_i32 s45, 0, 0x1c000
	v_add_u32_e32 v162, s44, v150
	v_add_u32_e32 v184, s45, v150
	ds_read_b128 v[146:149], v162
	ds_read_b128 v[154:157], v162 offset:1024
	ds_read_b128 v[158:161], v162 offset:2048
	ds_read_b128 v[162:165], v162 offset:3072
	ds_read_b128 v[166:169], v184
	ds_read_b128 v[192:195], v184 offset:1024
	ds_read_b128 v[196:199], v184 offset:2048
	ds_read_b128 v[200:203], v184 offset:3072
	s_add_u32 s24, s68, 0x30000
	s_addc_u32 s25, s69, 0
	s_mov_b32 m0, s88
	v_lshl_add_u64 v[242:243], s[24:25], 0, v[128:129]
	ds_read_b128 v[204:207], v153 offset:32768
	ds_read_b128 v[208:211], v153 offset:33792
	ds_read_b128 v[212:215], v153 offset:34816
	ds_read_b128 v[216:219], v153 offset:35840
	ds_read_b128 v[220:223], v153 offset:36864
	ds_read_b128 v[224:227], v153 offset:37888
	ds_read_b128 v[228:231], v153 offset:38912
	ds_read_b128 v[232:235], v153 offset:39936
	global_load_lds_dwordx4 v[242:243], off
	v_lshl_add_u64 v[242:243], s[24:25], 0, v[130:131]
	s_mov_b32 m0, s89
	s_nop 0
	global_load_lds_dwordx4 v[242:243], off
	s_waitcnt vmcnt(8)
	s_waitcnt lgkmcnt(0)
	s_barrier
	s_setprio 1
	s_waitcnt lgkmcnt(0)
	v_mfma_f32_16x16x32_bf16 v[124:127], v[146:149], v[204:207], v[124:127]
	v_mfma_f32_16x16x32_bf16 v[120:123], v[158:161], v[204:207], v[120:123]
	v_mfma_f32_16x16x32_bf16 v[108:111], v[146:149], v[212:215], v[108:111]
	v_mfma_f32_16x16x32_bf16 v[104:107], v[158:161], v[212:215], v[104:107]
	v_mfma_f32_16x16x32_bf16 v[92:95], v[146:149], v[220:223], v[92:95]
	v_mfma_f32_16x16x32_bf16 v[88:91], v[158:161], v[220:223], v[88:91]
	v_mfma_f32_16x16x32_bf16 v[76:79], v[146:149], v[228:231], v[76:79]
	v_mfma_f32_16x16x32_bf16 v[72:75], v[158:161], v[228:231], v[72:75]
	v_mfma_f32_16x16x32_bf16 v[124:127], v[154:157], v[208:211], v[124:127]
	v_mfma_f32_16x16x32_bf16 v[120:123], v[162:165], v[208:211], v[120:123]
	v_mfma_f32_16x16x32_bf16 v[108:111], v[154:157], v[216:219], v[108:111]
	v_mfma_f32_16x16x32_bf16 v[104:107], v[162:165], v[216:219], v[104:107]
	v_mfma_f32_16x16x32_bf16 v[92:95], v[154:157], v[224:227], v[92:95]
	v_mfma_f32_16x16x32_bf16 v[88:91], v[162:165], v[224:227], v[88:91]
	v_mfma_f32_16x16x32_bf16 v[76:79], v[154:157], v[232:235], v[76:79]
	v_mfma_f32_16x16x32_bf16 v[72:75], v[162:165], v[232:235], v[72:75]
	v_mfma_f32_16x16x32_bf16 v[116:119], v[166:169], v[204:207], v[116:119]
	v_mfma_f32_16x16x32_bf16 v[112:115], v[196:199], v[204:207], v[112:115]
	v_mfma_f32_16x16x32_bf16 v[100:103], v[166:169], v[212:215], v[100:103]
	v_mfma_f32_16x16x32_bf16 v[96:99], v[196:199], v[212:215], v[96:99]
	v_mfma_f32_16x16x32_bf16 v[84:87], v[166:169], v[220:223], v[84:87]
	v_mfma_f32_16x16x32_bf16 v[80:83], v[196:199], v[220:223], v[80:83]
	v_mfma_f32_16x16x32_bf16 v[68:71], v[166:169], v[228:231], v[68:71]
	v_mfma_f32_16x16x32_bf16 v[64:67], v[196:199], v[228:231], v[64:67]
	v_mfma_f32_16x16x32_bf16 v[116:119], v[192:195], v[208:211], v[116:119]
	v_mfma_f32_16x16x32_bf16 v[112:115], v[200:203], v[208:211], v[112:115]
	v_mfma_f32_16x16x32_bf16 v[100:103], v[192:195], v[216:219], v[100:103]
	v_mfma_f32_16x16x32_bf16 v[96:99], v[200:203], v[216:219], v[96:99]
	v_mfma_f32_16x16x32_bf16 v[84:87], v[192:195], v[224:227], v[84:87]
	v_mfma_f32_16x16x32_bf16 v[80:83], v[200:203], v[224:227], v[80:83]
	v_mfma_f32_16x16x32_bf16 v[68:71], v[192:195], v[232:235], v[68:71]
	v_mfma_f32_16x16x32_bf16 v[64:67], v[200:203], v[232:235], v[64:67]
	s_setprio 0
	s_barrier
; #define PG8_STAGE(bufoff, gbase, voff) do { _Pragma("unroll") for (int _i = 0; _i < 2; ++_i) \
;         __builtin_amdgcn_global_load_lds((const unsigned*)((const char*)(gbase) + (voff)[_i]), (PG8_LAS unsigned*)(lds + (bufoff) + ldsw + _i * 8192), 16, 0, 0); } while (0)
; #define PG8_LDA(dst, b, h) do { _Pragma("unroll") for (int m = 0; m < 4; ++m) _Pragma("unroll") for (int k = 0; k < 2; ++k) dst[m][k] = *(const PG8_LAS bf16x8*)(lds + PG8_SA(b, h) + aoff + m * 2048 + k * 1024); } while (0)
; #define PG8_LDB(dst, b, h) do { _Pragma("unroll") for (int n = 0; n < 2; ++n) _Pragma("unroll") for (int k = 0; k < 2; ++k) dst[n][k] = *(const PG8_LAS bf16x8*)(lds + PG8_SB(b, h) + boff + n * 2048 + k * 1024); } while (0)
; template <class Epi, class Sched, bool ALIGN_EPI = false, bool SP2 = false>
; __device__ __forceinline__ void gemm_phase(PG8_LAS unsigned char* lds, const Gemm g, const Sched& S, const Epi& E) {
;     ...
;         for (int t = 0; t < nt; t += 2) {
;             const bool last = (t == nt - 2);
;             const char* a1 = cA + (size_t)(t + 1) * kstep;
;             const char* a2 = last ? nA : cA + (size_t)(t + 2) * kstep; const char* b2 = last ? nB : cB + (size_t)(t + 2) * kstep;
;             const char* a3 = a2 + kstep; const char* b3 = b2 + kstep;
;             if (last && has_next) S.a_ready(nxt);
;             if constexpr (SP2) {
;             PG8_LDB(B0, 0, 0); PG8_LDB(B1, 0, 1); PG8_SCHED; PG8_LDA(At, 0, 0); PG8_STAGE(PG8_SA(1, 1), a1 + hstep, voffA);
;             PG8_WAIT_V(8); PG8_WAIT_L(0); PG8_BAR; PG8_MMA(0, 0, At, B0); PG8_MMA(0, 1, At, B1); PG8_BAR; PG8_SCHED;
;             PG8_LDA(At, 0, 1); PG8_STAGE(PG8_SB(0, 0), b2, voffB); PG8_STAGE(PG8_SB(0, 1), b2 + hstep, voffB); PG8_STAGE(PG8_SA(0, 0), a2, voffA);
;             PG8_WAIT_V(8); PG8_WAIT_L(0); PG8_BAR; PG8_MMA(1, 0, At, B0); PG8_MMA(1, 1, At, B1); PG8_BAR; PG8_SCHED;
;             PG8_LDB(B0, 1, 0); PG8_LDB(B1, 1, 1); PG8_SCHED; PG8_LDA(At, 1, 0); PG8_STAGE(PG8_SA(0, 1), a2 + hstep, voffA);
;             PG8_WAIT_V(8); PG8_WAIT_L(0); PG8_BAR; PG8_MMA(0, 0, At, B0); PG8_MMA(0, 1, At, B1); PG8_BAR; PG8_SCHED;
;             PG8_LDA(At, 1, 1); PG8_STAGE(PG8_SB(1, 0), b3, voffB); PG8_STAGE(PG8_SB(1, 1), b3 + hstep, voffB); PG8_STAGE(PG8_SA(1, 0), a3, voffA);
;             PG8_WAIT_V(8); PG8_WAIT_L(0); PG8_BAR; PG8_MMA(1, 0, At, B0); PG8_MMA(1, 1, At, B1); PG8_BAR; PG8_SCHED;
	s_add_i32 s24, s44, s29
	v_lshl_add_u64 v[170:171], v[170:171], 0, s[14:15]
	s_mov_b32 m0, s24
	ds_read_b128 v[204:207], v153 offset:49152
	ds_read_b128 v[208:211], v153 offset:50176
	ds_read_b128 v[212:215], v153 offset:51200
	ds_read_b128 v[216:219], v153 offset:52224
	ds_read_b128 v[220:223], v153 offset:53248
	ds_read_b128 v[224:227], v153 offset:54272
	ds_read_b128 v[228:231], v153 offset:55296
	ds_read_b128 v[232:235], v153 offset:56320
	global_load_lds_dwordx4 v[170:171], off
	s_add_i32 m0, s24, 0x2000
	s_add_u32 s24, s46, 0x30080
	v_lshl_add_u64 v[170:171], v[236:237], 0, s[14:15]
	s_addc_u32 s25, s47, 0
	s_add_i32 s44, s45, s29
	global_load_lds_dwordx4 v[170:171], off
	v_lshl_add_u64 v[170:171], s[24:25], 0, v[128:129]
	s_mov_b32 m0, s44
	s_nop 0
	global_load_lds_dwordx4 v[170:171], off
	v_lshl_add_u64 v[170:171], s[24:25], 0, v[130:131]
	s_add_i32 m0, s44, 0x2000
	s_nop 0
	global_load_lds_dwordx4 v[170:171], off
	v_lshl_add_u64 v[170:171], v[238:239], 0, s[14:15]
	s_mov_b32 m0, s91
	s_nop 0
	global_load_lds_dwordx4 v[170:171], off
	v_lshl_add_u64 v[170:171], v[240:241], 0, s[14:15]
	s_mov_b32 m0, s92
	s_nop 0
	global_load_lds_dwordx4 v[170:171], off
	s_waitcnt vmcnt(8)
	s_waitcnt lgkmcnt(0)
	s_barrier
	s_setprio 1
	s_waitcnt lgkmcnt(0)
	v_mfma_f32_16x16x32_bf16 v[60:63], v[146:149], v[204:207], v[60:63]
	v_mfma_f32_16x16x32_bf16 v[56:59], v[158:161], v[204:207], v[56:59]
	v_mfma_f32_16x16x32_bf16 v[44:47], v[146:149], v[212:215], v[44:47]
	v_mfma_f32_16x16x32_bf16 v[40:43], v[158:161], v[212:215], v[40:43]
	v_mfma_f32_16x16x32_bf16 v[28:31], v[146:149], v[220:223], v[28:31]
	v_mfma_f32_16x16x32_bf16 v[24:27], v[158:161], v[220:223], v[24:27]
	v_mfma_f32_16x16x32_bf16 v[12:15], v[146:149], v[228:231], v[12:15]
	v_mfma_f32_16x16x32_bf16 v[8:11], v[158:161], v[228:231], v[8:11]
	v_mfma_f32_16x16x32_bf16 v[60:63], v[154:157], v[208:211], v[60:63]
	v_mfma_f32_16x16x32_bf16 v[56:59], v[162:165], v[208:211], v[56:59]
	v_mfma_f32_16x16x32_bf16 v[44:47], v[154:157], v[216:219], v[44:47]
	v_mfma_f32_16x16x32_bf16 v[40:43], v[162:165], v[216:219], v[40:43]
	v_mfma_f32_16x16x32_bf16 v[28:31], v[154:157], v[224:227], v[28:31]
	v_mfma_f32_16x16x32_bf16 v[24:27], v[162:165], v[224:227], v[24:27]
	v_mfma_f32_16x16x32_bf16 v[12:15], v[154:157], v[232:235], v[12:15]
	v_mfma_f32_16x16x32_bf16 v[8:11], v[162:165], v[232:235], v[8:11]
	v_mfma_f32_16x16x32_bf16 v[52:55], v[166:169], v[204:207], v[52:55]
	v_mfma_f32_16x16x32_bf16 v[48:51], v[196:199], v[204:207], v[48:51]
	v_mfma_f32_16x16x32_bf16 v[36:39], v[166:169], v[212:215], v[36:39]
	v_mfma_f32_16x16x32_bf16 v[32:35], v[196:199], v[212:215], v[32:35]
	v_mfma_f32_16x16x32_bf16 v[20:23], v[166:169], v[220:223], v[20:23]
	v_mfma_f32_16x16x32_bf16 v[16:19], v[196:199], v[220:223], v[16:19]
	v_mfma_f32_16x16x32_bf16 v[4:7], v[166:169], v[228:231], v[4:7]
	v_mfma_f32_16x16x32_bf16 v[0:3], v[196:199], v[228:231], v[0:3]
	v_mfma_f32_16x16x32_bf16 v[52:55], v[192:195], v[208:211], v[52:55]
	v_mfma_f32_16x16x32_bf16 v[48:51], v[200:203], v[208:211], v[48:51]
	v_mfma_f32_16x16x32_bf16 v[36:39], v[192:195], v[216:219], v[36:39]
	v_mfma_f32_16x16x32_bf16 v[32:35], v[200:203], v[216:219], v[32:35]
	v_mfma_f32_16x16x32_bf16 v[20:23], v[192:195], v[224:227], v[20:23]
	v_mfma_f32_16x16x32_bf16 v[16:19], v[200:203], v[224:227], v[16:19]
	v_mfma_f32_16x16x32_bf16 v[4:7], v[192:195], v[232:235], v[4:7]
	v_mfma_f32_16x16x32_bf16 v[0:3], v[200:203], v[232:235], v[0:3]
	s_setprio 0
	s_barrier
	s_add_i32 s50, s50, 2
	s_add_u32 s22, s22, 0x100
	s_addc_u32 s33, s33, 0
	s_cmp_gt_u32 s50, 9
	s_mov_b64 s[44:45], s[42:43]
.LBB0_122:
	s_add_u32 s42, s44, 0x100
	s_addc_u32 s43, s45, 0
	s_add_i32 s24, 0, 0x10000
	s_cmp_eq_u32 s50, 8
	s_cselect_b32 s69, s65, s43
	s_cselect_b32 s68, s64, s42
	s_cselect_b32 s47, s67, s33
	s_cselect_b32 s46, s66, s22
	s_add_i32 s51, 0, 0x14000
	v_add_u32_e32 v162, s24, v150
	v_add_u32_e32 v170, s51, v150
	ds_read_b128 v[146:149], v162
	ds_read_b128 v[154:157], v162 offset:1024
	ds_read_b128 v[158:161], v162 offset:2048
	ds_read_b128 v[162:165], v162 offset:3072
	ds_read_b128 v[166:169], v170
	ds_read_b128 v[192:195], v170 offset:1024
	ds_read_b128 v[196:199], v170 offset:2048
	ds_read_b128 v[200:203], v170 offset:3072
	v_lshl_add_u64 v[170:171], s[44:45], 0, v[142:143]
	s_add_i32 m0, s71, 0xc000
	ds_read_b128 v[204:207], v153
	ds_read_b128 v[208:211], v153 offset:1024
	ds_read_b128 v[212:215], v153 offset:2048
	ds_read_b128 v[216:219], v153 offset:3072
	ds_read_b128 v[220:223], v153 offset:4096
	ds_read_b128 v[224:227], v153 offset:5120
	ds_read_b128 v[228:231], v153 offset:6144
	ds_read_b128 v[232:235], v153 offset:7168
	global_load_lds_dwordx4 v[170:171], off
	v_lshl_add_u64 v[170:171], s[44:45], 0, v[144:145]
	s_add_i32 m0, s71, 0xe000
	s_nop 0
	global_load_lds_dwordx4 v[170:171], off
	s_waitcnt vmcnt(8)
	s_waitcnt lgkmcnt(0)
	s_barrier
; #define PG8_STAGE(bufoff, gbase, voff) do { _Pragma("unroll") for (int _i = 0; _i < 2; ++_i) \
;         __builtin_amdgcn_global_load_lds((const unsigned*)((const char*)(gbase) + (voff)[_i]), (PG8_LAS unsigned*)(lds + (bufoff) + ldsw + _i * 8192), 16, 0, 0); } while (0)
; #define PG8_LDA(dst, b, h) do { _Pragma("unroll") for (int m = 0; m < 4; ++m) _Pragma("unroll") for (int k = 0; k < 2; ++k) dst[m][k] = *(const PG8_LAS bf16x8*)(lds + PG8_SA(b, h) + aoff + m * 2048 + k * 1024); } while (0)
; #define PG8_MMA(ai, bj, At, Bt) do { __builtin_amdgcn_s_setprio(1); _Pragma("unroll") for (int m = 0; m < 4; ++m) _Pragma("unroll") for (int n = 0; n < 2; ++n) _Pragma("unroll") for (int k = 0; k < 2; ++k) \
;         acc[ai][bj][m][n] = __builtin_amdgcn_mfma_f32_16x16x32_bf16(Bt[n][k], At[m][k], acc[ai][bj][m][n], 0, 0, 0); __builtin_amdgcn_s_setprio(0); } while (0)
; #define PG8_WAIT_V(n) asm volatile("s_waitcnt vmcnt(" #n ")" ::: "memory")
; #define PG8_WAIT_L(n) asm volatile("s_waitcnt lgkmcnt(" #n ")" ::: "memory")
; #define PG8_BAR __builtin_amdgcn_s_barrier()
; #define PG8_SCHED __builtin_amdgcn_sched_barrier(0)
; template <class Epi, class Sched, bool ALIGN_EPI = false, bool SP2 = false>
; __device__ __forceinline__ void gemm_phase(PG8_LAS unsigned char* lds, const Gemm g, const Sched& S, const Epi& E) {
;     ...
;             PG8_WAIT_V(8); PG8_WAIT_L(0); PG8_BAR; PG8_MMA(0, 0, At, B0); PG8_MMA(0, 1, At, B1); PG8_BAR; PG8_SCHED;
;             PG8_LDA(At, 0, 1); PG8_STAGE(PG8_SB(0, 0), b2, voffB); PG8_STAGE(PG8_SB(0, 1), b2 + hstep, voffB); PG8_STAGE(PG8_SA(0, 0), a2, voffA);
;             PG8_WAIT_V(8); PG8_WAIT_L(0); PG8_BAR; PG8_MMA(1, 0, At, B0); PG8_MMA(1, 1, At, B1); PG8_BAR; PG8_SCHED;
	s_setprio 1
	s_waitcnt lgkmcnt(0)
	v_mfma_f32_16x16x32_bf16 v[124:127], v[146:149], v[204:207], v[124:127]
	v_mfma_f32_16x16x32_bf16 v[120:123], v[158:161], v[204:207], v[120:123]
	v_mfma_f32_16x16x32_bf16 v[108:111], v[146:149], v[212:215], v[108:111]
	v_mfma_f32_16x16x32_bf16 v[104:107], v[158:161], v[212:215], v[104:107]
	v_mfma_f32_16x16x32_bf16 v[92:95], v[146:149], v[220:223], v[92:95]
	v_mfma_f32_16x16x32_bf16 v[88:91], v[158:161], v[220:223], v[88:91]
	v_mfma_f32_16x16x32_bf16 v[76:79], v[146:149], v[228:231], v[76:79]
	v_mfma_f32_16x16x32_bf16 v[72:75], v[158:161], v[228:231], v[72:75]
	v_mfma_f32_16x16x32_bf16 v[124:127], v[154:157], v[208:211], v[124:127]
	v_mfma_f32_16x16x32_bf16 v[120:123], v[162:165], v[208:211], v[120:123]
	v_mfma_f32_16x16x32_bf16 v[108:111], v[154:157], v[216:219], v[108:111]
	v_mfma_f32_16x16x32_bf16 v[104:107], v[162:165], v[216:219], v[104:107]
	v_mfma_f32_16x16x32_bf16 v[92:95], v[154:157], v[224:227], v[92:95]
	v_mfma_f32_16x16x32_bf16 v[88:91], v[162:165], v[224:227], v[88:91]
	v_mfma_f32_16x16x32_bf16 v[76:79], v[154:157], v[232:235], v[76:79]
	v_mfma_f32_16x16x32_bf16 v[72:75], v[162:165], v[232:235], v[72:75]
	v_mfma_f32_16x16x32_bf16 v[116:119], v[166:169], v[204:207], v[116:119]
	v_mfma_f32_16x16x32_bf16 v[112:115], v[196:199], v[204:207], v[112:115]
	v_mfma_f32_16x16x32_bf16 v[100:103], v[166:169], v[212:215], v[100:103]
	v_mfma_f32_16x16x32_bf16 v[96:99], v[196:199], v[212:215], v[96:99]
	v_mfma_f32_16x16x32_bf16 v[84:87], v[166:169], v[220:223], v[84:87]
	v_mfma_f32_16x16x32_bf16 v[80:83], v[196:199], v[220:223], v[80:83]
	v_mfma_f32_16x16x32_bf16 v[68:71], v[166:169], v[228:231], v[68:71]
	v_mfma_f32_16x16x32_bf16 v[64:67], v[196:199], v[228:231], v[64:67]
	v_mfma_f32_16x16x32_bf16 v[116:119], v[192:195], v[208:211], v[116:119]
	v_mfma_f32_16x16x32_bf16 v[112:115], v[200:203], v[208:211], v[112:115]
	v_mfma_f32_16x16x32_bf16 v[100:103], v[192:195], v[216:219], v[100:103]
	v_mfma_f32_16x16x32_bf16 v[96:99], v[200:203], v[216:219], v[96:99]
	v_mfma_f32_16x16x32_bf16 v[84:87], v[192:195], v[224:227], v[84:87]
	v_mfma_f32_16x16x32_bf16 v[80:83], v[200:203], v[224:227], v[80:83]
	v_mfma_f32_16x16x32_bf16 v[68:71], v[192:195], v[232:235], v[68:71]
	v_mfma_f32_16x16x32_bf16 v[64:67], v[200:203], v[232:235], v[64:67]
	s_setprio 0
	s_barrier
	s_add_i32 s24, s24, s29
	v_lshl_add_u64 v[170:171], s[46:47], 0, v[128:129]
	s_mov_b32 m0, s24
	ds_read_b128 v[204:207], v153 offset:16384
	ds_read_b128 v[208:211], v153 offset:17408
	ds_read_b128 v[212:215], v153 offset:18432
	ds_read_b128 v[216:219], v153 offset:19456
	ds_read_b128 v[220:223], v153 offset:20480
	ds_read_b128 v[224:227], v153 offset:21504
	ds_read_b128 v[228:231], v153 offset:22528
	ds_read_b128 v[232:235], v153 offset:23552
	global_load_lds_dwordx4 v[170:171], off
	s_add_i32 m0, s24, 0x2000
	s_add_u32 s24, s46, 0x30000
	v_lshl_add_u64 v[236:237], s[46:47], 0, v[130:131]
	s_addc_u32 s25, s47, 0
	s_add_i32 s44, s51, s29
	global_load_lds_dwordx4 v[236:237], off
	v_lshl_add_u64 v[238:239], s[24:25], 0, v[128:129]
	s_mov_b32 m0, s44
	v_lshl_add_u64 v[240:241], s[68:69], 0, v[130:131]
	global_load_lds_dwordx4 v[238:239], off
	v_lshl_add_u64 v[238:239], s[24:25], 0, v[130:131]
	s_add_i32 m0, s44, 0x2000
	s_nop 0
	global_load_lds_dwordx4 v[238:239], off
	v_lshl_add_u64 v[238:239], s[68:69], 0, v[128:129]
	s_mov_b32 m0, s71
	s_nop 0
	global_load_lds_dwordx4 v[238:239], off
	s_mov_b32 m0, s87
	s_nop 0
	global_load_lds_dwordx4 v[240:241], off
	s_waitcnt vmcnt(8)
	s_waitcnt lgkmcnt(0)
	s_barrier
	s_setprio 1
	s_waitcnt lgkmcnt(0)
	v_mfma_f32_16x16x32_bf16 v[60:63], v[146:149], v[204:207], v[60:63]
	v_mfma_f32_16x16x32_bf16 v[56:59], v[158:161], v[204:207], v[56:59]
	v_mfma_f32_16x16x32_bf16 v[44:47], v[146:149], v[212:215], v[44:47]
	v_mfma_f32_16x16x32_bf16 v[40:43], v[158:161], v[212:215], v[40:43]
	v_mfma_f32_16x16x32_bf16 v[28:31], v[146:149], v[220:223], v[28:31]
	v_mfma_f32_16x16x32_bf16 v[24:27], v[158:161], v[220:223], v[24:27]
	v_mfma_f32_16x16x32_bf16 v[12:15], v[146:149], v[228:231], v[12:15]
	v_mfma_f32_16x16x32_bf16 v[8:11], v[158:161], v[228:231], v[8:11]
	v_mfma_f32_16x16x32_bf16 v[60:63], v[154:157], v[208:211], v[60:63]
	v_mfma_f32_16x16x32_bf16 v[56:59], v[162:165], v[208:211], v[56:59]
	v_mfma_f32_16x16x32_bf16 v[44:47], v[154:157], v[216:219], v[44:47]
	v_mfma_f32_16x16x32_bf16 v[40:43], v[162:165], v[216:219], v[40:43]
	v_mfma_f32_16x16x32_bf16 v[28:31], v[154:157], v[224:227], v[28:31]
	v_mfma_f32_16x16x32_bf16 v[24:27], v[162:165], v[224:227], v[24:27]
	v_mfma_f32_16x16x32_bf16 v[12:15], v[154:157], v[232:235], v[12:15]
	v_mfma_f32_16x16x32_bf16 v[8:11], v[162:165], v[232:235], v[8:11]
	v_mfma_f32_16x16x32_bf16 v[52:55], v[166:169], v[204:207], v[52:55]
	v_mfma_f32_16x16x32_bf16 v[48:51], v[196:199], v[204:207], v[48:51]
	v_mfma_f32_16x16x32_bf16 v[36:39], v[166:169], v[212:215], v[36:39]
	v_mfma_f32_16x16x32_bf16 v[32:35], v[196:199], v[212:215], v[32:35]
	v_mfma_f32_16x16x32_bf16 v[20:23], v[166:169], v[220:223], v[20:23]
	v_mfma_f32_16x16x32_bf16 v[16:19], v[196:199], v[220:223], v[16:19]
	v_mfma_f32_16x16x32_bf16 v[4:7], v[166:169], v[228:231], v[4:7]
	v_mfma_f32_16x16x32_bf16 v[0:3], v[196:199], v[228:231], v[0:3]
	v_mfma_f32_16x16x32_bf16 v[52:55], v[192:195], v[208:211], v[52:55]
	v_mfma_f32_16x16x32_bf16 v[48:51], v[200:203], v[208:211], v[48:51]
	v_mfma_f32_16x16x32_bf16 v[36:39], v[192:195], v[216:219], v[36:39]
	v_mfma_f32_16x16x32_bf16 v[32:35], v[200:203], v[216:219], v[32:35]
	v_mfma_f32_16x16x32_bf16 v[20:23], v[192:195], v[224:227], v[20:23]
	v_mfma_f32_16x16x32_bf16 v[16:19], v[200:203], v[224:227], v[16:19]
	v_mfma_f32_16x16x32_bf16 v[4:7], v[192:195], v[232:235], v[4:7]
	v_mfma_f32_16x16x32_bf16 v[0:3], v[200:203], v[232:235], v[0:3]
	s_setprio 0
	s_barrier
; #define PG8_STAGE(bufoff, gbase, voff) do { _Pragma("unroll") for (int _i = 0; _i < 2; ++_i) \
;         __builtin_amdgcn_global_load_lds((const unsigned*)((const char*)(gbase) + (voff)[_i]), (PG8_LAS unsigned*)(lds + (bufoff) + ldsw + _i * 8192), 16, 0, 0); } while (0)
; #define PG8_LDA(dst, b, h) do { _Pragma("unroll") for (int m = 0; m < 4; ++m) _Pragma("unroll") for (int k = 0; k < 2; ++k) dst[m][k] = *(const PG8_LAS bf16x8*)(lds + PG8_SA(b, h) + aoff + m * 2048 + k * 1024); } while (0)
; #define PG8_LDB(dst, b, h) do { _Pragma("unroll") for (int n = 0; n < 2; ++n) _Pragma("unroll") for (int k = 0; k < 2; ++k) dst[n][k] = *(const PG8_LAS bf16x8*)(lds + PG8_SB(b, h) + boff + n * 2048 + k * 1024); } while (0)
; #define PG8_MMA(ai, bj, At, Bt) do { __builtin_amdgcn_s_setprio(1); _Pragma("unroll") for (int m = 0; m < 4; ++m) _Pragma("unroll") for (int n = 0; n < 2; ++n) _Pragma("unroll") for (int k = 0; k < 2; ++k) \
;         acc[ai][bj][m][n] = __builtin_amdgcn_mfma_f32_16x16x32_bf16(Bt[n][k], At[m][k], acc[ai][bj][m][n], 0, 0, 0); __builtin_amdgcn_s_setprio(0); } while (0)
; #define PG8_WAIT_V(n) asm volatile("s_waitcnt vmcnt(" #n ")" ::: "memory")
; #define PG8_WAIT_L(n) asm volatile("s_waitcnt lgkmcnt(" #n ")" ::: "memory")
; #define PG8_BAR __builtin_amdgcn_s_barrier()
; #define PG8_SCHED __builtin_amdgcn_sched_barrier(0)
; template <class Epi, class Sched, bool ALIGN_EPI = false, bool SP2 = false>
; __device__ __forceinline__ void gemm_phase(PG8_LAS unsigned char* lds, const Gemm g, const Sched& S, const Epi& E) {
;     ...
;             PG8_LDB(B0, 1, 0); PG8_LDB(B1, 1, 1); PG8_SCHED; PG8_LDA(At, 1, 0); PG8_STAGE(PG8_SA(0, 1), a2 + hstep, voffA);
;             PG8_WAIT_V(8); PG8_WAIT_L(0); PG8_BAR; PG8_MMA(0, 0, At, B0); PG8_MMA(0, 1, At, B1); PG8_BAR; PG8_SCHED;
	s_add_i32 s44, 0, 0x18000
	s_add_i32 s45, 0, 0x1c000
	v_add_u32_e32 v162, s44, v150
	v_add_u32_e32 v184, s45, v150
	ds_read_b128 v[146:149], v162
	ds_read_b128 v[154:157], v162 offset:1024
	ds_read_b128 v[158:161], v162 offset:2048
	ds_read_b128 v[162:165], v162 offset:3072
	ds_read_b128 v[166:169], v184
	ds_read_b128 v[192:195], v184 offset:1024
	ds_read_b128 v[196:199], v184 offset:2048
	ds_read_b128 v[200:203], v184 offset:3072
	s_add_u32 s24, s68, 0x30000
	s_addc_u32 s25, s69, 0
	s_mov_b32 m0, s88
	v_lshl_add_u64 v[242:243], s[24:25], 0, v[128:129]
	ds_read_b128 v[204:207], v153 offset:32768
	ds_read_b128 v[208:211], v153 offset:33792
	ds_read_b128 v[212:215], v153 offset:34816
	ds_read_b128 v[216:219], v153 offset:35840
	ds_read_b128 v[220:223], v153 offset:36864
	ds_read_b128 v[224:227], v153 offset:37888
	ds_read_b128 v[228:231], v153 offset:38912
	ds_read_b128 v[232:235], v153 offset:39936
	global_load_lds_dwordx4 v[242:243], off
	v_lshl_add_u64 v[242:243], s[24:25], 0, v[130:131]
	s_mov_b32 m0, s89
	s_nop 0
	global_load_lds_dwordx4 v[242:243], off
	s_waitcnt vmcnt(8)
	s_waitcnt lgkmcnt(0)
	s_barrier
	s_setprio 1
	s_waitcnt lgkmcnt(0)
	v_mfma_f32_16x16x32_bf16 v[124:127], v[146:149], v[204:207], v[124:127]
	v_mfma_f32_16x16x32_bf16 v[120:123], v[158:161], v[204:207], v[120:123]
	v_mfma_f32_16x16x32_bf16 v[108:111], v[146:149], v[212:215], v[108:111]
	v_mfma_f32_16x16x32_bf16 v[104:107], v[158:161], v[212:215], v[104:107]
	v_mfma_f32_16x16x32_bf16 v[92:95], v[146:149], v[220:223], v[92:95]
	v_mfma_f32_16x16x32_bf16 v[88:91], v[158:161], v[220:223], v[88:91]
	v_mfma_f32_16x16x32_bf16 v[76:79], v[146:149], v[228:231], v[76:79]
	v_mfma_f32_16x16x32_bf16 v[72:75], v[158:161], v[228:231], v[72:75]
	v_mfma_f32_16x16x32_bf16 v[124:127], v[154:157], v[208:211], v[124:127]
	v_mfma_f32_16x16x32_bf16 v[120:123], v[162:165], v[208:211], v[120:123]
	v_mfma_f32_16x16x32_bf16 v[108:111], v[154:157], v[216:219], v[108:111]
	v_mfma_f32_16x16x32_bf16 v[104:107], v[162:165], v[216:219], v[104:107]
	v_mfma_f32_16x16x32_bf16 v[92:95], v[154:157], v[224:227], v[92:95]
	v_mfma_f32_16x16x32_bf16 v[88:91], v[162:165], v[224:227], v[88:91]
	v_mfma_f32_16x16x32_bf16 v[76:79], v[154:157], v[232:235], v[76:79]
	v_mfma_f32_16x16x32_bf16 v[72:75], v[162:165], v[232:235], v[72:75]
	v_mfma_f32_16x16x32_bf16 v[116:119], v[166:169], v[204:207], v[116:119]
	v_mfma_f32_16x16x32_bf16 v[112:115], v[196:199], v[204:207], v[112:115]
	v_mfma_f32_16x16x32_bf16 v[100:103], v[166:169], v[212:215], v[100:103]
	v_mfma_f32_16x16x32_bf16 v[96:99], v[196:199], v[212:215], v[96:99]
	v_mfma_f32_16x16x32_bf16 v[84:87], v[166:169], v[220:223], v[84:87]
	v_mfma_f32_16x16x32_bf16 v[80:83], v[196:199], v[220:223], v[80:83]
	v_mfma_f32_16x16x32_bf16 v[68:71], v[166:169], v[228:231], v[68:71]
	v_mfma_f32_16x16x32_bf16 v[64:67], v[196:199], v[228:231], v[64:67]
	v_mfma_f32_16x16x32_bf16 v[116:119], v[192:195], v[208:211], v[116:119]
	v_mfma_f32_16x16x32_bf16 v[112:115], v[200:203], v[208:211], v[112:115]
	v_mfma_f32_16x16x32_bf16 v[100:103], v[192:195], v[216:219], v[100:103]
	v_mfma_f32_16x16x32_bf16 v[96:99], v[200:203], v[216:219], v[96:99]
	v_mfma_f32_16x16x32_bf16 v[84:87], v[192:195], v[224:227], v[84:87]
	v_mfma_f32_16x16x32_bf16 v[80:83], v[200:203], v[224:227], v[80:83]
	v_mfma_f32_16x16x32_bf16 v[68:71], v[192:195], v[232:235], v[68:71]
	v_mfma_f32_16x16x32_bf16 v[64:67], v[200:203], v[232:235], v[64:67]
	s_setprio 0
	s_barrier
; #define PG8_STAGE(bufoff, gbase, voff) do { _Pragma("unroll") for (int _i = 0; _i < 2; ++_i) \
;         __builtin_amdgcn_global_load_lds((const unsigned*)((const char*)(gbase) + (voff)[_i]), (PG8_LAS unsigned*)(lds + (bufoff) + ldsw + _i * 8192), 16, 0, 0); } while (0)
; #define PG8_LDA(dst, b, h) do { _Pragma("unroll") for (int m = 0; m < 4; ++m) _Pragma("unroll") for (int k = 0; k < 2; ++k) dst[m][k] = *(const PG8_LAS bf16x8*)(lds + PG8_SA(b, h) + aoff + m * 2048 + k * 1024); } while (0)
; #define PG8_MMA(ai, bj, At, Bt) do { __builtin_amdgcn_s_setprio(1); _Pragma("unroll") for (int m = 0; m < 4; ++m) _Pragma("unroll") for (int n = 0; n < 2; ++n) _Pragma("unroll") for (int k = 0; k < 2; ++k) \
;         acc[ai][bj][m][n] = __builtin_amdgcn_mfma_f32_16x16x32_bf16(Bt[n][k], At[m][k], acc[ai][bj][m][n], 0, 0, 0); __builtin_amdgcn_s_setprio(0); } while (0)
; #define PG8_WAIT_V(n) asm volatile("s_waitcnt vmcnt(" #n ")" ::: "memory")
; #define PG8_WAIT_L(n) asm volatile("s_waitcnt lgkmcnt(" #n ")" ::: "memory")
; #define PG8_BAR __builtin_amdgcn_s_barrier()
; #define PG8_SCHED __builtin_amdgcn_sched_barrier(0)
; template <class Epi, class Sched, bool ALIGN_EPI = false, bool SP2 = false>
; __device__ __forceinline__ void gemm_phase(PG8_LAS unsigned char* lds, const Gemm g, const Sched& S, const Epi& E) {
;     ...
;             PG8_LDA(At, 1, 1); PG8_STAGE(PG8_SB(1, 0), b3, voffB); PG8_STAGE(PG8_SB(1, 1), b3 + hstep, voffB); PG8_STAGE(PG8_SA(1, 0), a3, voffA);
;             PG8_WAIT_V(8); PG8_WAIT_L(0); PG8_BAR; PG8_MMA(1, 0, At, B0); PG8_MMA(1, 1, At, B1); PG8_BAR; PG8_SCHED;
;     ...
;         if constexpr (ALIGN_EPI) { if (wr == 0) PG8_BAR; }
	s_add_i32 s24, s44, s29
	v_lshl_add_u64 v[170:171], v[170:171], 0, s[14:15]
	s_mov_b32 m0, s24
	ds_read_b128 v[204:207], v153 offset:49152
	ds_read_b128 v[208:211], v153 offset:50176
	ds_read_b128 v[212:215], v153 offset:51200
	ds_read_b128 v[216:219], v153 offset:52224
	ds_read_b128 v[220:223], v153 offset:53248
	ds_read_b128 v[224:227], v153 offset:54272
	ds_read_b128 v[228:231], v153 offset:55296
	ds_read_b128 v[232:235], v153 offset:56320
	global_load_lds_dwordx4 v[170:171], off
	s_add_i32 m0, s24, 0x2000
	s_add_u32 s24, s46, 0x30080
	v_lshl_add_u64 v[170:171], v[236:237], 0, s[14:15]
	s_addc_u32 s25, s47, 0
	s_add_i32 s44, s45, s29
	global_load_lds_dwordx4 v[170:171], off
	v_lshl_add_u64 v[170:171], s[24:25], 0, v[128:129]
	s_mov_b32 m0, s44
	s_nop 0
	global_load_lds_dwordx4 v[170:171], off
	v_lshl_add_u64 v[170:171], s[24:25], 0, v[130:131]
	s_add_i32 m0, s44, 0x2000
	s_nop 0
	global_load_lds_dwordx4 v[170:171], off
	v_lshl_add_u64 v[170:171], v[238:239], 0, s[14:15]
	s_mov_b32 m0, s91
	s_nop 0
	global_load_lds_dwordx4 v[170:171], off
	v_lshl_add_u64 v[170:171], v[240:241], 0, s[14:15]
	s_mov_b32 m0, s92
	s_nop 0
	global_load_lds_dwordx4 v[170:171], off
	s_waitcnt vmcnt(8)
	s_waitcnt lgkmcnt(0)
	s_barrier
	s_setprio 1
	s_waitcnt lgkmcnt(0)
	v_mfma_f32_16x16x32_bf16 v[60:63], v[146:149], v[204:207], v[60:63]
	v_mfma_f32_16x16x32_bf16 v[56:59], v[158:161], v[204:207], v[56:59]
	v_mfma_f32_16x16x32_bf16 v[44:47], v[146:149], v[212:215], v[44:47]
	v_mfma_f32_16x16x32_bf16 v[40:43], v[158:161], v[212:215], v[40:43]
	v_mfma_f32_16x16x32_bf16 v[28:31], v[146:149], v[220:223], v[28:31]
	v_mfma_f32_16x16x32_bf16 v[24:27], v[158:161], v[220:223], v[24:27]
	v_mfma_f32_16x16x32_bf16 v[12:15], v[146:149], v[228:231], v[12:15]
	v_mfma_f32_16x16x32_bf16 v[8:11], v[158:161], v[228:231], v[8:11]
	v_mfma_f32_16x16x32_bf16 v[60:63], v[154:157], v[208:211], v[60:63]
	v_mfma_f32_16x16x32_bf16 v[56:59], v[162:165], v[208:211], v[56:59]
	v_mfma_f32_16x16x32_bf16 v[44:47], v[154:157], v[216:219], v[44:47]
	v_mfma_f32_16x16x32_bf16 v[40:43], v[162:165], v[216:219], v[40:43]
	v_mfma_f32_16x16x32_bf16 v[28:31], v[154:157], v[224:227], v[28:31]
	v_mfma_f32_16x16x32_bf16 v[24:27], v[162:165], v[224:227], v[24:27]
	v_mfma_f32_16x16x32_bf16 v[12:15], v[154:157], v[232:235], v[12:15]
	v_mfma_f32_16x16x32_bf16 v[8:11], v[162:165], v[232:235], v[8:11]
	v_mfma_f32_16x16x32_bf16 v[52:55], v[166:169], v[204:207], v[52:55]
	v_mfma_f32_16x16x32_bf16 v[48:51], v[196:199], v[204:207], v[48:51]
	v_mfma_f32_16x16x32_bf16 v[36:39], v[166:169], v[212:215], v[36:39]
	v_mfma_f32_16x16x32_bf16 v[32:35], v[196:199], v[212:215], v[32:35]
	v_mfma_f32_16x16x32_bf16 v[20:23], v[166:169], v[220:223], v[20:23]
	v_mfma_f32_16x16x32_bf16 v[16:19], v[196:199], v[220:223], v[16:19]
	v_mfma_f32_16x16x32_bf16 v[4:7], v[166:169], v[228:231], v[4:7]
	v_mfma_f32_16x16x32_bf16 v[0:3], v[196:199], v[228:231], v[0:3]
	v_mfma_f32_16x16x32_bf16 v[52:55], v[192:195], v[208:211], v[52:55]
	v_mfma_f32_16x16x32_bf16 v[48:51], v[200:203], v[208:211], v[48:51]
	v_mfma_f32_16x16x32_bf16 v[36:39], v[192:195], v[216:219], v[36:39]
	v_mfma_f32_16x16x32_bf16 v[32:35], v[200:203], v[216:219], v[32:35]
	v_mfma_f32_16x16x32_bf16 v[20:23], v[192:195], v[224:227], v[20:23]
	v_mfma_f32_16x16x32_bf16 v[16:19], v[200:203], v[224:227], v[16:19]
	v_mfma_f32_16x16x32_bf16 v[4:7], v[192:195], v[232:235], v[4:7]
	v_mfma_f32_16x16x32_bf16 v[0:3], v[200:203], v[232:235], v[0:3]
	s_setprio 0
	s_barrier
	s_add_i32 s50, s50, 2
	s_add_u32 s22, s22, 0x100
	s_addc_u32 s33, s33, 0
	s_cmp_gt_u32 s50, 9
	s_mov_b64 s[44:45], s[42:43]
	s_cbranch_scc0 .LBB0_122
	s_and_b64 vcc, exec, s[2:3]
	s_cbranch_vccz .LBB0_125
	s_barrier

; #define PG8_STAGE(bufoff, gbase, voff) do { _Pragma("unroll") for (int _i = 0; _i < 2; ++_i) \
;         __builtin_amdgcn_global_load_lds((const unsigned*)((const char*)(gbase) + (voff)[_i]), (PG8_LAS unsigned*)(lds + (bufoff) + ldsw + _i * 8192), 16, 0, 0); } while (0)
; #define PG8_LDA(dst, b, h) do { _Pragma("unroll") for (int m = 0; m < 4; ++m) _Pragma("unroll") for (int k = 0; k < 2; ++k) dst[m][k] = *(const PG8_LAS bf16x8*)(lds + PG8_SA(b, h) + aoff + m * 2048 + k * 1024); } while (0)
; #define PG8_LDB(dst, b, h) do { _Pragma("unroll") for (int n = 0; n < 2; ++n) _Pragma("unroll") for (int k = 0; k < 2; ++k) dst[n][k] = *(const PG8_LAS bf16x8*)(lds + PG8_SB(b, h) + boff + n * 2048 + k * 1024); } while (0)
; #define PG8_MMA(ai, bj, At, Bt) do { __builtin_amdgcn_s_setprio(1); _Pragma("unroll") for (int m = 0; m < 4; ++m) _Pragma("unroll") for (int n = 0; n < 2; ++n) _Pragma("unroll") for (int k = 0; k < 2; ++k) \
;         acc[ai][bj][m][n] = __builtin_amdgcn_mfma_f32_16x16x32_bf16(Bt[n][k], At[m][k], acc[ai][bj][m][n], 0, 0, 0); __builtin_amdgcn_s_setprio(0); } while (0)
; #define PG8_BAR __builtin_amdgcn_s_barrier()
; template <class Epi, class Sched, bool ALIGN_EPI = false, bool SP2 = false>
; __device__ __forceinline__ void gemm_phase(PG8_LAS unsigned char* lds, const Gemm g, const Sched& S, const Epi& E) {
;     ...
;         const bool has_next = S.next(ui + 1, nxt);
;         const char* nA = has_next ? (const char*)g.A + (size_t)nxt.pm * tstep : cA; const char* nB = has_next ? (const char*)g.Bt + (size_t)nxt.pn * tstep : cB;
;         for (int t = 0; t < nt; t += 2) {
;             const bool last = (t == nt - 2);
;             const char* a1 = cA + (size_t)(t + 1) * kstep;
;             const char* a2 = last ? nA : cA + (size_t)(t + 2) * kstep; const char* b2 = last ? nB : cB + (size_t)(t + 2) * kstep;
;             const char* a3 = a2 + kstep; const char* b3 = b2 + kstep;
;             if (last && has_next) S.a_ready(nxt);
;             if constexpr (SP2) {
;             PG8_LDB(B0, 0, 0); PG8_LDB(B1, 0, 1); PG8_SCHED; PG8_LDA(At, 0, 0); PG8_STAGE(PG8_SA(1, 1), a1 + hstep, voffA);
;             PG8_WAIT_V(8); PG8_WAIT_L(0); PG8_BAR; PG8_MMA(0, 0, At, B0); PG8_MMA(0, 1, At, B1); PG8_BAR; PG8_SCHED;
;             PG8_LDA(At, 0, 1); PG8_STAGE(PG8_SB(0, 0), b2, voffB); PG8_STAGE(PG8_SB(0, 1), b2 + hstep, voffB); PG8_STAGE(PG8_SA(0, 0), a2, voffA);
.LBB0_174:
	s_ashr_i32 s39, s38, 31
	s_lshl_b64 s[0:1], s[38:39], 19
	s_add_u32 s48, s23, s0
	s_addc_u32 s49, s12, s1
	s_and_b64 s[0:1], s[42:43], exec
	s_cselect_b32 s0, s49, s57
	s_cselect_b32 s1, s48, s56
	s_ashr_i32 s37, s36, 31
	s_lshl_b64 s[24:25], s[36:37], 19
	s_add_u32 s52, s85, s24
	s_addc_u32 s53, s86, s25
	s_and_b64 s[24:25], s[42:43], exec
	s_cselect_b32 s10, s53, s59
	s_cselect_b32 s22, s52, s58
	s_add_u32 s56, s56, 0x40080
	s_addc_u32 s57, s57, 0
	s_add_u32 s33, s58, 0x100
	s_addc_u32 s37, s59, 0
	s_mov_b32 s39, -2
	s_waitcnt lgkmcnt(0)
	s_add_u32 s24, s56, 0xfffc0080
	s_addc_u32 s25, s57, -1
	s_add_i32 s45, 0, 0x10000
	s_cmp_eq_u32 s39, 12
	s_cselect_b32 s61, s0, s25
	s_cselect_b32 s60, s1, s24
	v_add_u32_e32 v132, s45, v192
	s_cselect_b32 s59, s10, s37
	s_cselect_b32 s58, s22, s33
	s_add_i32 s47, 0, 0x14000
	ds_read_b128 v[128:131], v132
	ds_read_b128 v[158:161], v132 offset:1024
	ds_read_b128 v[162:165], v132 offset:2048
	ds_read_b128 v[166:169], v132 offset:3072
	v_add_u32_e32 v132, s47, v192
	ds_read_b128 v[194:197], v132
	ds_read_b128 v[198:201], v132 offset:1024
	ds_read_b128 v[202:205], v132 offset:2048
	ds_read_b128 v[206:209], v132 offset:3072
	v_lshl_add_u64 v[170:171], s[56:57], 0, v[154:155]
	s_add_i32 m0, s73, 0xc000
	ds_read_b128 v[210:213], v193
	ds_read_b128 v[214:217], v193 offset:1024
	ds_read_b128 v[218:221], v193 offset:2048
	ds_read_b128 v[222:225], v193 offset:3072
	ds_read_b128 v[226:229], v193 offset:4096
	ds_read_b128 v[230:233], v193 offset:5120
	ds_read_b128 v[234:237], v193 offset:6144
	ds_read_b128 v[238:241], v193 offset:7168
	global_load_lds_dwordx4 v[170:171], off
	v_lshl_add_u64 v[170:171], s[56:57], 0, v[156:157]
	s_add_i32 m0, s73, 0xe000
	s_nop 0
	global_load_lds_dwordx4 v[170:171], off
	s_waitcnt vmcnt(8)
	s_waitcnt lgkmcnt(0)
	s_barrier
	s_setprio 1
	s_waitcnt lgkmcnt(0)
	v_mfma_f32_16x16x32_bf16 v[124:127], v[128:131], v[210:213], 0
	v_mfma_f32_16x16x32_bf16 v[120:123], v[162:165], v[210:213], 0
	v_mfma_f32_16x16x32_bf16 v[108:111], v[128:131], v[218:221], 0
	v_mfma_f32_16x16x32_bf16 v[104:107], v[162:165], v[218:221], 0
	v_mfma_f32_16x16x32_bf16 v[92:95], v[128:131], v[226:229], 0
	v_mfma_f32_16x16x32_bf16 v[88:91], v[162:165], v[226:229], 0
	v_mfma_f32_16x16x32_bf16 v[76:79], v[128:131], v[234:237], 0
	v_mfma_f32_16x16x32_bf16 v[72:75], v[162:165], v[234:237], 0
	v_mfma_f32_16x16x32_bf16 v[124:127], v[158:161], v[214:217], v[124:127]
	v_mfma_f32_16x16x32_bf16 v[120:123], v[166:169], v[214:217], v[120:123]
	v_mfma_f32_16x16x32_bf16 v[108:111], v[158:161], v[222:225], v[108:111]
	v_mfma_f32_16x16x32_bf16 v[104:107], v[166:169], v[222:225], v[104:107]
	v_mfma_f32_16x16x32_bf16 v[92:95], v[158:161], v[230:233], v[92:95]
	v_mfma_f32_16x16x32_bf16 v[88:91], v[166:169], v[230:233], v[88:91]
	v_mfma_f32_16x16x32_bf16 v[76:79], v[158:161], v[238:241], v[76:79]
	v_mfma_f32_16x16x32_bf16 v[72:75], v[166:169], v[238:241], v[72:75]
	v_mfma_f32_16x16x32_bf16 v[116:119], v[194:197], v[210:213], 0
	v_mfma_f32_16x16x32_bf16 v[112:115], v[202:205], v[210:213], 0
	v_mfma_f32_16x16x32_bf16 v[100:103], v[194:197], v[218:221], 0
	v_mfma_f32_16x16x32_bf16 v[96:99], v[202:205], v[218:221], 0
	v_mfma_f32_16x16x32_bf16 v[84:87], v[194:197], v[226:229], 0
	v_mfma_f32_16x16x32_bf16 v[80:83], v[202:205], v[226:229], 0
	v_mfma_f32_16x16x32_bf16 v[68:71], v[194:197], v[234:237], 0
	v_mfma_f32_16x16x32_bf16 v[64:67], v[202:205], v[234:237], 0
	v_mfma_f32_16x16x32_bf16 v[116:119], v[198:201], v[214:217], v[116:119]
	v_mfma_f32_16x16x32_bf16 v[112:115], v[206:209], v[214:217], v[112:115]
	v_mfma_f32_16x16x32_bf16 v[100:103], v[198:201], v[222:225], v[100:103]
	v_mfma_f32_16x16x32_bf16 v[96:99], v[206:209], v[222:225], v[96:99]
	v_mfma_f32_16x16x32_bf16 v[84:87], v[198:201], v[230:233], v[84:87]
	v_mfma_f32_16x16x32_bf16 v[80:83], v[206:209], v[230:233], v[80:83]
	v_mfma_f32_16x16x32_bf16 v[68:71], v[198:201], v[238:241], v[68:71]
	v_mfma_f32_16x16x32_bf16 v[64:67], v[206:209], v[238:241], v[64:67]
	s_setprio 0
	s_barrier
	s_add_i32 s24, s45, s29
	v_lshl_add_u64 v[170:171], s[58:59], 0, v[142:143]
	s_mov_b32 m0, s24
	ds_read_b128 v[210:213], v193 offset:16384
	ds_read_b128 v[214:217], v193 offset:17408
	ds_read_b128 v[218:221], v193 offset:18432
	ds_read_b128 v[222:225], v193 offset:19456
	ds_read_b128 v[226:229], v193 offset:20480
	ds_read_b128 v[230:233], v193 offset:21504
	ds_read_b128 v[234:237], v193 offset:22528
	ds_read_b128 v[238:241], v193 offset:23552
	global_load_lds_dwordx4 v[170:171], off
	s_add_i32 m0, s24, 0x2000
	s_add_u32 s24, s58, 0x40000
	v_lshl_add_u64 v[242:243], s[58:59], 0, v[146:147]
	s_addc_u32 s25, s59, 0
	s_add_i32 s45, s47, s29
	global_load_lds_dwordx4 v[242:243], off
	v_lshl_add_u64 v[244:245], s[24:25], 0, v[142:143]
	s_mov_b32 m0, s45
	v_lshl_add_u64 v[246:247], s[60:61], 0, v[144:145]
	global_load_lds_dwordx4 v[244:245], off
	v_lshl_add_u64 v[244:245], s[24:25], 0, v[146:147]
	s_add_i32 m0, s45, 0x2000
	s_nop 0
	global_load_lds_dwordx4 v[244:245], off
	v_lshl_add_u64 v[244:245], s[60:61], 0, v[140:141]
	s_mov_b32 m0, s73
	s_nop 0
	global_load_lds_dwordx4 v[244:245], off
	s_mov_b32 m0, s87
	s_nop 0
	global_load_lds_dwordx4 v[246:247], off
	s_waitcnt vmcnt(8)
	s_waitcnt lgkmcnt(0)
	s_barrier
; #define PG8_STAGE(bufoff, gbase, voff) do { _Pragma("unroll") for (int _i = 0; _i < 2; ++_i) \
;         __builtin_amdgcn_global_load_lds((const unsigned*)((const char*)(gbase) + (voff)[_i]), (PG8_LAS unsigned*)(lds + (bufoff) + ldsw + _i * 8192), 16, 0, 0); } while (0)
; #define PG8_LDA(dst, b, h) do { _Pragma("unroll") for (int m = 0; m < 4; ++m) _Pragma("unroll") for (int k = 0; k < 2; ++k) dst[m][k] = *(const PG8_LAS bf16x8*)(lds + PG8_SA(b, h) + aoff + m * 2048 + k * 1024); } while (0)
; #define PG8_LDB(dst, b, h) do { _Pragma("unroll") for (int n = 0; n < 2; ++n) _Pragma("unroll") for (int k = 0; k < 2; ++k) dst[n][k] = *(const PG8_LAS bf16x8*)(lds + PG8_SB(b, h) + boff + n * 2048 + k * 1024); } while (0)
; #define PG8_MMA(ai, bj, At, Bt) do { __builtin_amdgcn_s_setprio(1); _Pragma("unroll") for (int m = 0; m < 4; ++m) _Pragma("unroll") for (int n = 0; n < 2; ++n) _Pragma("unroll") for (int k = 0; k < 2; ++k) \
;         acc[ai][bj][m][n] = __builtin_amdgcn_mfma_f32_16x16x32_bf16(Bt[n][k], At[m][k], acc[ai][bj][m][n], 0, 0, 0); __builtin_amdgcn_s_setprio(0); } while (0)
; #define PG8_WAIT_V(n) asm volatile("s_waitcnt vmcnt(" #n ")" ::: "memory")
; #define PG8_WAIT_L(n) asm volatile("s_waitcnt lgkmcnt(" #n ")" ::: "memory")
; #define PG8_BAR __builtin_amdgcn_s_barrier()
; #define PG8_SCHED __builtin_amdgcn_sched_barrier(0)
; template <class Epi, class Sched, bool ALIGN_EPI = false, bool SP2 = false>
; __device__ __forceinline__ void gemm_phase(PG8_LAS unsigned char* lds, const Gemm g, const Sched& S, const Epi& E) {
;     ...
;             PG8_WAIT_V(8); PG8_WAIT_L(0); PG8_BAR; PG8_MMA(1, 0, At, B0); PG8_MMA(1, 1, At, B1); PG8_BAR; PG8_SCHED;
;             PG8_LDB(B0, 1, 0); PG8_LDB(B1, 1, 1); PG8_SCHED; PG8_LDA(At, 1, 0); PG8_STAGE(PG8_SA(0, 1), a2 + hstep, voffA);
;             PG8_WAIT_V(8); PG8_WAIT_L(0); PG8_BAR; PG8_MMA(0, 0, At, B0); PG8_MMA(0, 1, At, B1); PG8_BAR; PG8_SCHED;
	s_setprio 1
	s_waitcnt lgkmcnt(0)
	v_mfma_f32_16x16x32_bf16 v[60:63], v[128:131], v[210:213], 0
	v_mfma_f32_16x16x32_bf16 v[56:59], v[162:165], v[210:213], 0
	v_mfma_f32_16x16x32_bf16 v[44:47], v[128:131], v[218:221], 0
	v_mfma_f32_16x16x32_bf16 v[40:43], v[162:165], v[218:221], 0
	v_mfma_f32_16x16x32_bf16 v[28:31], v[128:131], v[226:229], 0
	v_mfma_f32_16x16x32_bf16 v[24:27], v[162:165], v[226:229], 0
	v_mfma_f32_16x16x32_bf16 v[12:15], v[128:131], v[234:237], 0
	v_mfma_f32_16x16x32_bf16 v[8:11], v[162:165], v[234:237], 0
	v_mfma_f32_16x16x32_bf16 v[60:63], v[158:161], v[214:217], v[60:63]
	v_mfma_f32_16x16x32_bf16 v[56:59], v[166:169], v[214:217], v[56:59]
	v_mfma_f32_16x16x32_bf16 v[44:47], v[158:161], v[222:225], v[44:47]
	v_mfma_f32_16x16x32_bf16 v[40:43], v[166:169], v[222:225], v[40:43]
	v_mfma_f32_16x16x32_bf16 v[28:31], v[158:161], v[230:233], v[28:31]
	v_mfma_f32_16x16x32_bf16 v[24:27], v[166:169], v[230:233], v[24:27]
	v_mfma_f32_16x16x32_bf16 v[12:15], v[158:161], v[238:241], v[12:15]
	v_mfma_f32_16x16x32_bf16 v[8:11], v[166:169], v[238:241], v[8:11]
	v_mfma_f32_16x16x32_bf16 v[52:55], v[194:197], v[210:213], 0
	v_mfma_f32_16x16x32_bf16 v[48:51], v[202:205], v[210:213], 0
	v_mfma_f32_16x16x32_bf16 v[36:39], v[194:197], v[218:221], 0
	v_mfma_f32_16x16x32_bf16 v[32:35], v[202:205], v[218:221], 0
	v_mfma_f32_16x16x32_bf16 v[20:23], v[194:197], v[226:229], 0
	v_mfma_f32_16x16x32_bf16 v[16:19], v[202:205], v[226:229], 0
	v_mfma_f32_16x16x32_bf16 v[4:7], v[194:197], v[234:237], 0
	v_mfma_f32_16x16x32_bf16 v[0:3], v[202:205], v[234:237], 0
	v_mfma_f32_16x16x32_bf16 v[52:55], v[198:201], v[214:217], v[52:55]
	v_mfma_f32_16x16x32_bf16 v[48:51], v[206:209], v[214:217], v[48:51]
	v_mfma_f32_16x16x32_bf16 v[36:39], v[198:201], v[222:225], v[36:39]
	v_mfma_f32_16x16x32_bf16 v[32:35], v[206:209], v[222:225], v[32:35]
	v_mfma_f32_16x16x32_bf16 v[20:23], v[198:201], v[230:233], v[20:23]
	v_mfma_f32_16x16x32_bf16 v[16:19], v[206:209], v[230:233], v[16:19]
	v_mfma_f32_16x16x32_bf16 v[4:7], v[198:201], v[238:241], v[4:7]
	v_mfma_f32_16x16x32_bf16 v[0:3], v[206:209], v[238:241], v[0:3]
	s_setprio 0
	s_barrier
	s_add_i32 s45, 0, 0x18000
	v_add_u32_e32 v132, s45, v192
	s_add_i32 s47, 0, 0x1c000
	ds_read_b128 v[128:131], v132
	ds_read_b128 v[158:161], v132 offset:1024
	ds_read_b128 v[162:165], v132 offset:2048
	ds_read_b128 v[166:169], v132 offset:3072
	v_add_u32_e32 v132, s47, v192
	ds_read_b128 v[194:197], v132
	ds_read_b128 v[198:201], v132 offset:1024
	ds_read_b128 v[202:205], v132 offset:2048
	ds_read_b128 v[206:209], v132 offset:3072
	s_add_u32 s24, s60, 0x40000
	s_addc_u32 s25, s61, 0
	s_mov_b32 m0, s88
	v_lshl_add_u64 v[248:249], s[24:25], 0, v[140:141]
	ds_read_b128 v[210:213], v193 offset:32768
	ds_read_b128 v[214:217], v193 offset:33792
	ds_read_b128 v[218:221], v193 offset:34816
	ds_read_b128 v[222:225], v193 offset:35840
	ds_read_b128 v[226:229], v193 offset:36864
	ds_read_b128 v[230:233], v193 offset:37888
	ds_read_b128 v[234:237], v193 offset:38912
	ds_read_b128 v[238:241], v193 offset:39936
	global_load_lds_dwordx4 v[248:249], off
	v_lshl_add_u64 v[248:249], s[24:25], 0, v[144:145]
	s_mov_b32 m0, s89
	s_nop 0
	global_load_lds_dwordx4 v[248:249], off
	s_waitcnt vmcnt(8)
	s_waitcnt lgkmcnt(0)
	s_barrier
	s_setprio 1
	s_waitcnt lgkmcnt(0)
	v_mfma_f32_16x16x32_bf16 v[124:127], v[128:131], v[210:213], v[124:127]
	v_mfma_f32_16x16x32_bf16 v[120:123], v[162:165], v[210:213], v[120:123]
	v_mfma_f32_16x16x32_bf16 v[108:111], v[128:131], v[218:221], v[108:111]
	v_mfma_f32_16x16x32_bf16 v[104:107], v[162:165], v[218:221], v[104:107]
	v_mfma_f32_16x16x32_bf16 v[92:95], v[128:131], v[226:229], v[92:95]
	v_mfma_f32_16x16x32_bf16 v[88:91], v[162:165], v[226:229], v[88:91]
	v_mfma_f32_16x16x32_bf16 v[76:79], v[128:131], v[234:237], v[76:79]
	v_mfma_f32_16x16x32_bf16 v[72:75], v[162:165], v[234:237], v[72:75]
	v_mfma_f32_16x16x32_bf16 v[124:127], v[158:161], v[214:217], v[124:127]
	v_mfma_f32_16x16x32_bf16 v[120:123], v[166:169], v[214:217], v[120:123]
	v_mfma_f32_16x16x32_bf16 v[108:111], v[158:161], v[222:225], v[108:111]
	v_mfma_f32_16x16x32_bf16 v[104:107], v[166:169], v[222:225], v[104:107]
	v_mfma_f32_16x16x32_bf16 v[92:95], v[158:161], v[230:233], v[92:95]
	v_mfma_f32_16x16x32_bf16 v[88:91], v[166:169], v[230:233], v[88:91]
	v_mfma_f32_16x16x32_bf16 v[76:79], v[158:161], v[238:241], v[76:79]
	v_mfma_f32_16x16x32_bf16 v[72:75], v[166:169], v[238:241], v[72:75]
	v_mfma_f32_16x16x32_bf16 v[116:119], v[194:197], v[210:213], v[116:119]
	v_mfma_f32_16x16x32_bf16 v[112:115], v[202:205], v[210:213], v[112:115]
	v_mfma_f32_16x16x32_bf16 v[100:103], v[194:197], v[218:221], v[100:103]
	v_mfma_f32_16x16x32_bf16 v[96:99], v[202:205], v[218:221], v[96:99]
	v_mfma_f32_16x16x32_bf16 v[84:87], v[194:197], v[226:229], v[84:87]
	v_mfma_f32_16x16x32_bf16 v[80:83], v[202:205], v[226:229], v[80:83]
	v_mfma_f32_16x16x32_bf16 v[68:71], v[194:197], v[234:237], v[68:71]
	v_mfma_f32_16x16x32_bf16 v[64:67], v[202:205], v[234:237], v[64:67]
	v_mfma_f32_16x16x32_bf16 v[116:119], v[198:201], v[214:217], v[116:119]
	v_mfma_f32_16x16x32_bf16 v[112:115], v[206:209], v[214:217], v[112:115]
	v_mfma_f32_16x16x32_bf16 v[100:103], v[198:201], v[222:225], v[100:103]
	v_mfma_f32_16x16x32_bf16 v[96:99], v[206:209], v[222:225], v[96:99]
	v_mfma_f32_16x16x32_bf16 v[84:87], v[198:201], v[230:233], v[84:87]
	v_mfma_f32_16x16x32_bf16 v[80:83], v[206:209], v[230:233], v[80:83]
	v_mfma_f32_16x16x32_bf16 v[68:71], v[198:201], v[238:241], v[68:71]
	v_mfma_f32_16x16x32_bf16 v[64:67], v[206:209], v[238:241], v[64:67]
	s_setprio 0
	s_barrier
; #define PG8_STAGE(bufoff, gbase, voff) do { _Pragma("unroll") for (int _i = 0; _i < 2; ++_i) \
;         __builtin_amdgcn_global_load_lds((const unsigned*)((const char*)(gbase) + (voff)[_i]), (PG8_LAS unsigned*)(lds + (bufoff) + ldsw + _i * 8192), 16, 0, 0); } while (0)
; #define PG8_LDA(dst, b, h) do { _Pragma("unroll") for (int m = 0; m < 4; ++m) _Pragma("unroll") for (int k = 0; k < 2; ++k) dst[m][k] = *(const PG8_LAS bf16x8*)(lds + PG8_SA(b, h) + aoff + m * 2048 + k * 1024); } while (0)
; #define PG8_LDB(dst, b, h) do { _Pragma("unroll") for (int n = 0; n < 2; ++n) _Pragma("unroll") for (int k = 0; k < 2; ++k) dst[n][k] = *(const PG8_LAS bf16x8*)(lds + PG8_SB(b, h) + boff + n * 2048 + k * 1024); } while (0)
; template <class Epi, class Sched, bool ALIGN_EPI = false, bool SP2 = false>
; __device__ __forceinline__ void gemm_phase(PG8_LAS unsigned char* lds, const Gemm g, const Sched& S, const Epi& E) {
;     ...
;         for (int t = 0; t < nt; t += 2) {
;             const bool last = (t == nt - 2);
;             const char* a1 = cA + (size_t)(t + 1) * kstep;
;             const char* a2 = last ? nA : cA + (size_t)(t + 2) * kstep; const char* b2 = last ? nB : cB + (size_t)(t + 2) * kstep;
;             const char* a3 = a2 + kstep; const char* b3 = b2 + kstep;
;             if (last && has_next) S.a_ready(nxt);
;             if constexpr (SP2) {
;             PG8_LDB(B0, 0, 0); PG8_LDB(B1, 0, 1); PG8_SCHED; PG8_LDA(At, 0, 0); PG8_STAGE(PG8_SA(1, 1), a1 + hstep, voffA);
;             PG8_WAIT_V(8); PG8_WAIT_L(0); PG8_BAR; PG8_MMA(0, 0, At, B0); PG8_MMA(0, 1, At, B1); PG8_BAR; PG8_SCHED;
;             PG8_LDA(At, 0, 1); PG8_STAGE(PG8_SB(0, 0), b2, voffB); PG8_STAGE(PG8_SB(0, 1), b2 + hstep, voffB); PG8_STAGE(PG8_SA(0, 0), a2, voffA);
;             PG8_WAIT_V(8); PG8_WAIT_L(0); PG8_BAR; PG8_MMA(1, 0, At, B0); PG8_MMA(1, 1, At, B1); PG8_BAR; PG8_SCHED;
;             PG8_LDB(B0, 1, 0); PG8_LDB(B1, 1, 1); PG8_SCHED; PG8_LDA(At, 1, 0); PG8_STAGE(PG8_SA(0, 1), a2 + hstep, voffA);
;             PG8_WAIT_V(8); PG8_WAIT_L(0); PG8_BAR; PG8_MMA(0, 0, At, B0); PG8_MMA(0, 1, At, B1); PG8_BAR; PG8_SCHED;
;             PG8_LDA(At, 1, 1); PG8_STAGE(PG8_SB(1, 0), b3, voffB); PG8_STAGE(PG8_SB(1, 1), b3 + hstep, voffB); PG8_STAGE(PG8_SA(1, 0), a3, voffA);
;             PG8_WAIT_V(8); PG8_WAIT_L(0); PG8_BAR; PG8_MMA(1, 0, At, B0); PG8_MMA(1, 1, At, B1); PG8_BAR; PG8_SCHED;
	s_add_i32 s24, s45, s29
	v_lshl_add_u64 v[170:171], v[170:171], 0, s[14:15]
	s_mov_b32 m0, s24
	ds_read_b128 v[210:213], v193 offset:49152
	ds_read_b128 v[214:217], v193 offset:50176
	ds_read_b128 v[218:221], v193 offset:51200
	ds_read_b128 v[222:225], v193 offset:52224
	ds_read_b128 v[226:229], v193 offset:53248
	ds_read_b128 v[230:233], v193 offset:54272
	ds_read_b128 v[234:237], v193 offset:55296
	ds_read_b128 v[238:241], v193 offset:56320
	global_load_lds_dwordx4 v[170:171], off
	s_add_i32 m0, s24, 0x2000
	s_add_u32 s24, s58, 0x40080
	v_lshl_add_u64 v[170:171], v[242:243], 0, s[14:15]
	s_addc_u32 s25, s59, 0
	s_add_i32 s45, s47, s29
	global_load_lds_dwordx4 v[170:171], off
	v_lshl_add_u64 v[170:171], s[24:25], 0, v[142:143]
	s_mov_b32 m0, s45
	s_nop 0
	global_load_lds_dwordx4 v[170:171], off
	v_lshl_add_u64 v[170:171], s[24:25], 0, v[146:147]
	s_add_i32 m0, s45, 0x2000
	s_nop 0
	global_load_lds_dwordx4 v[170:171], off
	v_lshl_add_u64 v[170:171], v[244:245], 0, s[14:15]
	s_mov_b32 m0, s90
	s_nop 0
	global_load_lds_dwordx4 v[170:171], off
	v_lshl_add_u64 v[170:171], v[246:247], 0, s[14:15]
	s_mov_b32 m0, s91
	s_nop 0
	global_load_lds_dwordx4 v[170:171], off
	s_waitcnt vmcnt(8)
	s_waitcnt lgkmcnt(0)
	s_barrier
	s_setprio 1
	s_waitcnt lgkmcnt(0)
	v_mfma_f32_16x16x32_bf16 v[60:63], v[128:131], v[210:213], v[60:63]
	v_mfma_f32_16x16x32_bf16 v[56:59], v[162:165], v[210:213], v[56:59]
	v_mfma_f32_16x16x32_bf16 v[44:47], v[128:131], v[218:221], v[44:47]
	v_mfma_f32_16x16x32_bf16 v[40:43], v[162:165], v[218:221], v[40:43]
	v_mfma_f32_16x16x32_bf16 v[28:31], v[128:131], v[226:229], v[28:31]
	v_mfma_f32_16x16x32_bf16 v[24:27], v[162:165], v[226:229], v[24:27]
	v_mfma_f32_16x16x32_bf16 v[12:15], v[128:131], v[234:237], v[12:15]
	v_mfma_f32_16x16x32_bf16 v[8:11], v[162:165], v[234:237], v[8:11]
	v_mfma_f32_16x16x32_bf16 v[60:63], v[158:161], v[214:217], v[60:63]
	v_mfma_f32_16x16x32_bf16 v[56:59], v[166:169], v[214:217], v[56:59]
	v_mfma_f32_16x16x32_bf16 v[44:47], v[158:161], v[222:225], v[44:47]
	v_mfma_f32_16x16x32_bf16 v[40:43], v[166:169], v[222:225], v[40:43]
	v_mfma_f32_16x16x32_bf16 v[28:31], v[158:161], v[230:233], v[28:31]
	v_mfma_f32_16x16x32_bf16 v[24:27], v[166:169], v[230:233], v[24:27]
	v_mfma_f32_16x16x32_bf16 v[12:15], v[158:161], v[238:241], v[12:15]
	v_mfma_f32_16x16x32_bf16 v[8:11], v[166:169], v[238:241], v[8:11]
	v_mfma_f32_16x16x32_bf16 v[52:55], v[194:197], v[210:213], v[52:55]
	v_mfma_f32_16x16x32_bf16 v[48:51], v[202:205], v[210:213], v[48:51]
	v_mfma_f32_16x16x32_bf16 v[36:39], v[194:197], v[218:221], v[36:39]
	v_mfma_f32_16x16x32_bf16 v[32:35], v[202:205], v[218:221], v[32:35]
	v_mfma_f32_16x16x32_bf16 v[20:23], v[194:197], v[226:229], v[20:23]
	v_mfma_f32_16x16x32_bf16 v[16:19], v[202:205], v[226:229], v[16:19]
	v_mfma_f32_16x16x32_bf16 v[4:7], v[194:197], v[234:237], v[4:7]
	v_mfma_f32_16x16x32_bf16 v[0:3], v[202:205], v[234:237], v[0:3]
	v_mfma_f32_16x16x32_bf16 v[52:55], v[198:201], v[214:217], v[52:55]
	v_mfma_f32_16x16x32_bf16 v[48:51], v[206:209], v[214:217], v[48:51]
	v_mfma_f32_16x16x32_bf16 v[36:39], v[198:201], v[222:225], v[36:39]
	v_mfma_f32_16x16x32_bf16 v[32:35], v[206:209], v[222:225], v[32:35]
	v_mfma_f32_16x16x32_bf16 v[20:23], v[198:201], v[230:233], v[20:23]
	v_mfma_f32_16x16x32_bf16 v[16:19], v[206:209], v[230:233], v[16:19]
	v_mfma_f32_16x16x32_bf16 v[4:7], v[198:201], v[238:241], v[4:7]
	v_mfma_f32_16x16x32_bf16 v[0:3], v[206:209], v[238:241], v[0:3]
	s_setprio 0
	s_barrier
	s_add_i32 s39, s39, 2
	s_add_u32 s56, s56, 0x100
	s_addc_u32 s57, s57, 0
	s_add_u32 s33, s33, 0x100
	s_addc_u32 s37, s37, 0
	s_cmp_gt_u32 s39, 13
.LBB0_175:
	s_add_u32 s24, s56, 0xfffc0080
	s_addc_u32 s25, s57, -1
	s_add_i32 s45, 0, 0x10000
	s_cmp_eq_u32 s39, 12
	s_cselect_b32 s61, s0, s25
	s_cselect_b32 s60, s1, s24
	v_add_u32_e32 v132, s45, v192
	s_cselect_b32 s59, s10, s37
	s_cselect_b32 s58, s22, s33
	s_add_i32 s47, 0, 0x14000
	ds_read_b128 v[128:131], v132
	ds_read_b128 v[158:161], v132 offset:1024
	ds_read_b128 v[162:165], v132 offset:2048
	ds_read_b128 v[166:169], v132 offset:3072
	v_add_u32_e32 v132, s47, v192
	ds_read_b128 v[194:197], v132
	ds_read_b128 v[198:201], v132 offset:1024
	ds_read_b128 v[202:205], v132 offset:2048
	ds_read_b128 v[206:209], v132 offset:3072
	v_lshl_add_u64 v[170:171], s[56:57], 0, v[154:155]
	s_add_i32 m0, s73, 0xc000
	ds_read_b128 v[210:213], v193
	ds_read_b128 v[214:217], v193 offset:1024
	ds_read_b128 v[218:221], v193 offset:2048
	ds_read_b128 v[222:225], v193 offset:3072
	ds_read_b128 v[226:229], v193 offset:4096
	ds_read_b128 v[230:233], v193 offset:5120
	ds_read_b128 v[234:237], v193 offset:6144
	ds_read_b128 v[238:241], v193 offset:7168
	global_load_lds_dwordx4 v[170:171], off
	v_lshl_add_u64 v[170:171], s[56:57], 0, v[156:157]
	s_add_i32 m0, s73, 0xe000
	s_nop 0
	global_load_lds_dwordx4 v[170:171], off
	s_waitcnt vmcnt(8)
	s_waitcnt lgkmcnt(0)
	s_barrier
; #define PG8_STAGE(bufoff, gbase, voff) do { _Pragma("unroll") for (int _i = 0; _i < 2; ++_i) \
;         __builtin_amdgcn_global_load_lds((const unsigned*)((const char*)(gbase) + (voff)[_i]), (PG8_LAS unsigned*)(lds + (bufoff) + ldsw + _i * 8192), 16, 0, 0); } while (0)
; #define PG8_LDA(dst, b, h) do { _Pragma("unroll") for (int m = 0; m < 4; ++m) _Pragma("unroll") for (int k = 0; k < 2; ++k) dst[m][k] = *(const PG8_LAS bf16x8*)(lds + PG8_SA(b, h) + aoff + m * 2048 + k * 1024); } while (0)
; #define PG8_MMA(ai, bj, At, Bt) do { __builtin_amdgcn_s_setprio(1); _Pragma("unroll") for (int m = 0; m < 4; ++m) _Pragma("unroll") for (int n = 0; n < 2; ++n) _Pragma("unroll") for (int k = 0; k < 2; ++k) \
;         acc[ai][bj][m][n] = __builtin_amdgcn_mfma_f32_16x16x32_bf16(Bt[n][k], At[m][k], acc[ai][bj][m][n], 0, 0, 0); __builtin_amdgcn_s_setprio(0); } while (0)
; #define PG8_WAIT_V(n) asm volatile("s_waitcnt vmcnt(" #n ")" ::: "memory")
; #define PG8_WAIT_L(n) asm volatile("s_waitcnt lgkmcnt(" #n ")" ::: "memory")
; #define PG8_BAR __builtin_amdgcn_s_barrier()
; #define PG8_SCHED __builtin_amdgcn_sched_barrier(0)
; template <class Epi, class Sched, bool ALIGN_EPI = false, bool SP2 = false>
; __device__ __forceinline__ void gemm_phase(PG8_LAS unsigned char* lds, const Gemm g, const Sched& S, const Epi& E) {
;     ...
;             PG8_WAIT_V(8); PG8_WAIT_L(0); PG8_BAR; PG8_MMA(0, 0, At, B0); PG8_MMA(0, 1, At, B1); PG8_BAR; PG8_SCHED;
;             PG8_LDA(At, 0, 1); PG8_STAGE(PG8_SB(0, 0), b2, voffB); PG8_STAGE(PG8_SB(0, 1), b2 + hstep, voffB); PG8_STAGE(PG8_SA(0, 0), a2, voffA);
;             PG8_WAIT_V(8); PG8_WAIT_L(0); PG8_BAR; PG8_MMA(1, 0, At, B0); PG8_MMA(1, 1, At, B1); PG8_BAR; PG8_SCHED;
	s_setprio 1
	s_waitcnt lgkmcnt(0)
	v_mfma_f32_16x16x32_bf16 v[124:127], v[128:131], v[210:213], v[124:127]
	v_mfma_f32_16x16x32_bf16 v[120:123], v[162:165], v[210:213], v[120:123]
	v_mfma_f32_16x16x32_bf16 v[108:111], v[128:131], v[218:221], v[108:111]
	v_mfma_f32_16x16x32_bf16 v[104:107], v[162:165], v[218:221], v[104:107]
	v_mfma_f32_16x16x32_bf16 v[92:95], v[128:131], v[226:229], v[92:95]
	v_mfma_f32_16x16x32_bf16 v[88:91], v[162:165], v[226:229], v[88:91]
	v_mfma_f32_16x16x32_bf16 v[76:79], v[128:131], v[234:237], v[76:79]
	v_mfma_f32_16x16x32_bf16 v[72:75], v[162:165], v[234:237], v[72:75]
	v_mfma_f32_16x16x32_bf16 v[124:127], v[158:161], v[214:217], v[124:127]
	v_mfma_f32_16x16x32_bf16 v[120:123], v[166:169], v[214:217], v[120:123]
	v_mfma_f32_16x16x32_bf16 v[108:111], v[158:161], v[222:225], v[108:111]
	v_mfma_f32_16x16x32_bf16 v[104:107], v[166:169], v[222:225], v[104:107]
	v_mfma_f32_16x16x32_bf16 v[92:95], v[158:161], v[230:233], v[92:95]
	v_mfma_f32_16x16x32_bf16 v[88:91], v[166:169], v[230:233], v[88:91]
	v_mfma_f32_16x16x32_bf16 v[76:79], v[158:161], v[238:241], v[76:79]
	v_mfma_f32_16x16x32_bf16 v[72:75], v[166:169], v[238:241], v[72:75]
	v_mfma_f32_16x16x32_bf16 v[116:119], v[194:197], v[210:213], v[116:119]
	v_mfma_f32_16x16x32_bf16 v[112:115], v[202:205], v[210:213], v[112:115]
	v_mfma_f32_16x16x32_bf16 v[100:103], v[194:197], v[218:221], v[100:103]
	v_mfma_f32_16x16x32_bf16 v[96:99], v[202:205], v[218:221], v[96:99]
	v_mfma_f32_16x16x32_bf16 v[84:87], v[194:197], v[226:229], v[84:87]
	v_mfma_f32_16x16x32_bf16 v[80:83], v[202:205], v[226:229], v[80:83]
	v_mfma_f32_16x16x32_bf16 v[68:71], v[194:197], v[234:237], v[68:71]
	v_mfma_f32_16x16x32_bf16 v[64:67], v[202:205], v[234:237], v[64:67]
	v_mfma_f32_16x16x32_bf16 v[116:119], v[198:201], v[214:217], v[116:119]
	v_mfma_f32_16x16x32_bf16 v[112:115], v[206:209], v[214:217], v[112:115]
	v_mfma_f32_16x16x32_bf16 v[100:103], v[198:201], v[222:225], v[100:103]
	v_mfma_f32_16x16x32_bf16 v[96:99], v[206:209], v[222:225], v[96:99]
	v_mfma_f32_16x16x32_bf16 v[84:87], v[198:201], v[230:233], v[84:87]
	v_mfma_f32_16x16x32_bf16 v[80:83], v[206:209], v[230:233], v[80:83]
	v_mfma_f32_16x16x32_bf16 v[68:71], v[198:201], v[238:241], v[68:71]
	v_mfma_f32_16x16x32_bf16 v[64:67], v[206:209], v[238:241], v[64:67]
	s_setprio 0
	s_barrier
	s_add_i32 s24, s45, s29
	v_lshl_add_u64 v[170:171], s[58:59], 0, v[142:143]
	s_mov_b32 m0, s24
	ds_read_b128 v[210:213], v193 offset:16384
	ds_read_b128 v[214:217], v193 offset:17408
	ds_read_b128 v[218:221], v193 offset:18432
	ds_read_b128 v[222:225], v193 offset:19456
	ds_read_b128 v[226:229], v193 offset:20480
	ds_read_b128 v[230:233], v193 offset:21504
	ds_read_b128 v[234:237], v193 offset:22528
	ds_read_b128 v[238:241], v193 offset:23552
	global_load_lds_dwordx4 v[170:171], off
	s_add_i32 m0, s24, 0x2000
	s_add_u32 s24, s58, 0x40000
	v_lshl_add_u64 v[242:243], s[58:59], 0, v[146:147]
	s_addc_u32 s25, s59, 0
	s_add_i32 s45, s47, s29
	global_load_lds_dwordx4 v[242:243], off
	v_lshl_add_u64 v[244:245], s[24:25], 0, v[142:143]
	s_mov_b32 m0, s45
	v_lshl_add_u64 v[246:247], s[60:61], 0, v[144:145]
	global_load_lds_dwordx4 v[244:245], off
	v_lshl_add_u64 v[244:245], s[24:25], 0, v[146:147]
	s_add_i32 m0, s45, 0x2000
	s_nop 0
	global_load_lds_dwordx4 v[244:245], off
	v_lshl_add_u64 v[244:245], s[60:61], 0, v[140:141]
	s_mov_b32 m0, s73
	s_nop 0
	global_load_lds_dwordx4 v[244:245], off
	s_mov_b32 m0, s87
	s_nop 0
	global_load_lds_dwordx4 v[246:247], off
	s_waitcnt vmcnt(8)
	s_waitcnt lgkmcnt(0)
	s_barrier
	s_setprio 1
	s_waitcnt lgkmcnt(0)
	v_mfma_f32_16x16x32_bf16 v[60:63], v[128:131], v[210:213], v[60:63]
	v_mfma_f32_16x16x32_bf16 v[56:59], v[162:165], v[210:213], v[56:59]
	v_mfma_f32_16x16x32_bf16 v[44:47], v[128:131], v[218:221], v[44:47]
	v_mfma_f32_16x16x32_bf16 v[40:43], v[162:165], v[218:221], v[40:43]
	v_mfma_f32_16x16x32_bf16 v[28:31], v[128:131], v[226:229], v[28:31]
	v_mfma_f32_16x16x32_bf16 v[24:27], v[162:165], v[226:229], v[24:27]
	v_mfma_f32_16x16x32_bf16 v[12:15], v[128:131], v[234:237], v[12:15]
	v_mfma_f32_16x16x32_bf16 v[8:11], v[162:165], v[234:237], v[8:11]
	v_mfma_f32_16x16x32_bf16 v[60:63], v[158:161], v[214:217], v[60:63]
	v_mfma_f32_16x16x32_bf16 v[56:59], v[166:169], v[214:217], v[56:59]
	v_mfma_f32_16x16x32_bf16 v[44:47], v[158:161], v[222:225], v[44:47]
	v_mfma_f32_16x16x32_bf16 v[40:43], v[166:169], v[222:225], v[40:43]
	v_mfma_f32_16x16x32_bf16 v[28:31], v[158:161], v[230:233], v[28:31]
	v_mfma_f32_16x16x32_bf16 v[24:27], v[166:169], v[230:233], v[24:27]
	v_mfma_f32_16x16x32_bf16 v[12:15], v[158:161], v[238:241], v[12:15]
	v_mfma_f32_16x16x32_bf16 v[8:11], v[166:169], v[238:241], v[8:11]
	v_mfma_f32_16x16x32_bf16 v[52:55], v[194:197], v[210:213], v[52:55]
	v_mfma_f32_16x16x32_bf16 v[48:51], v[202:205], v[210:213], v[48:51]
	v_mfma_f32_16x16x32_bf16 v[36:39], v[194:197], v[218:221], v[36:39]
	v_mfma_f32_16x16x32_bf16 v[32:35], v[202:205], v[218:221], v[32:35]
	v_mfma_f32_16x16x32_bf16 v[20:23], v[194:197], v[226:229], v[20:23]
	v_mfma_f32_16x16x32_bf16 v[16:19], v[202:205], v[226:229], v[16:19]
	v_mfma_f32_16x16x32_bf16 v[4:7], v[194:197], v[234:237], v[4:7]
	v_mfma_f32_16x16x32_bf16 v[0:3], v[202:205], v[234:237], v[0:3]
	v_mfma_f32_16x16x32_bf16 v[52:55], v[198:201], v[214:217], v[52:55]
	v_mfma_f32_16x16x32_bf16 v[48:51], v[206:209], v[214:217], v[48:51]
	v_mfma_f32_16x16x32_bf16 v[36:39], v[198:201], v[222:225], v[36:39]
	v_mfma_f32_16x16x32_bf16 v[32:35], v[206:209], v[222:225], v[32:35]
	v_mfma_f32_16x16x32_bf16 v[20:23], v[198:201], v[230:233], v[20:23]
	v_mfma_f32_16x16x32_bf16 v[16:19], v[206:209], v[230:233], v[16:19]
	v_mfma_f32_16x16x32_bf16 v[4:7], v[198:201], v[238:241], v[4:7]
	v_mfma_f32_16x16x32_bf16 v[0:3], v[206:209], v[238:241], v[0:3]
	s_setprio 0
	s_barrier
; #define PG8_STAGE(bufoff, gbase, voff) do { _Pragma("unroll") for (int _i = 0; _i < 2; ++_i) \
;         __builtin_amdgcn_global_load_lds((const unsigned*)((const char*)(gbase) + (voff)[_i]), (PG8_LAS unsigned*)(lds + (bufoff) + ldsw + _i * 8192), 16, 0, 0); } while (0)
; #define PG8_LDA(dst, b, h) do { _Pragma("unroll") for (int m = 0; m < 4; ++m) _Pragma("unroll") for (int k = 0; k < 2; ++k) dst[m][k] = *(const PG8_LAS bf16x8*)(lds + PG8_SA(b, h) + aoff + m * 2048 + k * 1024); } while (0)
; #define PG8_LDB(dst, b, h) do { _Pragma("unroll") for (int n = 0; n < 2; ++n) _Pragma("unroll") for (int k = 0; k < 2; ++k) dst[n][k] = *(const PG8_LAS bf16x8*)(lds + PG8_SB(b, h) + boff + n * 2048 + k * 1024); } while (0)
; #define PG8_MMA(ai, bj, At, Bt) do { __builtin_amdgcn_s_setprio(1); _Pragma("unroll") for (int m = 0; m < 4; ++m) _Pragma("unroll") for (int n = 0; n < 2; ++n) _Pragma("unroll") for (int k = 0; k < 2; ++k) \
;         acc[ai][bj][m][n] = __builtin_amdgcn_mfma_f32_16x16x32_bf16(Bt[n][k], At[m][k], acc[ai][bj][m][n], 0, 0, 0); __builtin_amdgcn_s_setprio(0); } while (0)
; #define PG8_WAIT_V(n) asm volatile("s_waitcnt vmcnt(" #n ")" ::: "memory")
; #define PG8_WAIT_L(n) asm volatile("s_waitcnt lgkmcnt(" #n ")" ::: "memory")
; #define PG8_BAR __builtin_amdgcn_s_barrier()
; #define PG8_SCHED __builtin_amdgcn_sched_barrier(0)
; template <class Epi, class Sched, bool ALIGN_EPI = false, bool SP2 = false>
; __device__ __forceinline__ void gemm_phase(PG8_LAS unsigned char* lds, const Gemm g, const Sched& S, const Epi& E) {
;     ...
;             PG8_LDB(B0, 1, 0); PG8_LDB(B1, 1, 1); PG8_SCHED; PG8_LDA(At, 1, 0); PG8_STAGE(PG8_SA(0, 1), a2 + hstep, voffA);
;             PG8_WAIT_V(8); PG8_WAIT_L(0); PG8_BAR; PG8_MMA(0, 0, At, B0); PG8_MMA(0, 1, At, B1); PG8_BAR; PG8_SCHED;
	s_add_i32 s45, 0, 0x18000
	v_add_u32_e32 v132, s45, v192
	s_add_i32 s47, 0, 0x1c000
	ds_read_b128 v[128:131], v132
	ds_read_b128 v[158:161], v132 offset:1024
	ds_read_b128 v[162:165], v132 offset:2048
	ds_read_b128 v[166:169], v132 offset:3072
	v_add_u32_e32 v132, s47, v192
	ds_read_b128 v[194:197], v132
	ds_read_b128 v[198:201], v132 offset:1024
	ds_read_b128 v[202:205], v132 offset:2048
	ds_read_b128 v[206:209], v132 offset:3072
	s_add_u32 s24, s60, 0x40000
	s_addc_u32 s25, s61, 0
	s_mov_b32 m0, s88
	v_lshl_add_u64 v[248:249], s[24:25], 0, v[140:141]
	ds_read_b128 v[210:213], v193 offset:32768
	ds_read_b128 v[214:217], v193 offset:33792
	ds_read_b128 v[218:221], v193 offset:34816
	ds_read_b128 v[222:225], v193 offset:35840
	ds_read_b128 v[226:229], v193 offset:36864
	ds_read_b128 v[230:233], v193 offset:37888
	ds_read_b128 v[234:237], v193 offset:38912
	ds_read_b128 v[238:241], v193 offset:39936
	global_load_lds_dwordx4 v[248:249], off
	v_lshl_add_u64 v[248:249], s[24:25], 0, v[144:145]
	s_mov_b32 m0, s89
	s_nop 0
	global_load_lds_dwordx4 v[248:249], off
	s_waitcnt vmcnt(8)
	s_waitcnt lgkmcnt(0)
	s_barrier
	s_setprio 1
	s_waitcnt lgkmcnt(0)
	v_mfma_f32_16x16x32_bf16 v[124:127], v[128:131], v[210:213], v[124:127]
	v_mfma_f32_16x16x32_bf16 v[120:123], v[162:165], v[210:213], v[120:123]
	v_mfma_f32_16x16x32_bf16 v[108:111], v[128:131], v[218:221], v[108:111]
	v_mfma_f32_16x16x32_bf16 v[104:107], v[162:165], v[218:221], v[104:107]
	v_mfma_f32_16x16x32_bf16 v[92:95], v[128:131], v[226:229], v[92:95]
	v_mfma_f32_16x16x32_bf16 v[88:91], v[162:165], v[226:229], v[88:91]
	v_mfma_f32_16x16x32_bf16 v[76:79], v[128:131], v[234:237], v[76:79]
	v_mfma_f32_16x16x32_bf16 v[72:75], v[162:165], v[234:237], v[72:75]
	v_mfma_f32_16x16x32_bf16 v[124:127], v[158:161], v[214:217], v[124:127]
	v_mfma_f32_16x16x32_bf16 v[120:123], v[166:169], v[214:217], v[120:123]
	v_mfma_f32_16x16x32_bf16 v[108:111], v[158:161], v[222:225], v[108:111]
	v_mfma_f32_16x16x32_bf16 v[104:107], v[166:169], v[222:225], v[104:107]
	v_mfma_f32_16x16x32_bf16 v[92:95], v[158:161], v[230:233], v[92:95]
	v_mfma_f32_16x16x32_bf16 v[88:91], v[166:169], v[230:233], v[88:91]
	v_mfma_f32_16x16x32_bf16 v[76:79], v[158:161], v[238:241], v[76:79]
	v_mfma_f32_16x16x32_bf16 v[72:75], v[166:169], v[238:241], v[72:75]
	v_mfma_f32_16x16x32_bf16 v[116:119], v[194:197], v[210:213], v[116:119]
	v_mfma_f32_16x16x32_bf16 v[112:115], v[202:205], v[210:213], v[112:115]
	v_mfma_f32_16x16x32_bf16 v[100:103], v[194:197], v[218:221], v[100:103]
	v_mfma_f32_16x16x32_bf16 v[96:99], v[202:205], v[218:221], v[96:99]
	v_mfma_f32_16x16x32_bf16 v[84:87], v[194:197], v[226:229], v[84:87]
	v_mfma_f32_16x16x32_bf16 v[80:83], v[202:205], v[226:229], v[80:83]
	v_mfma_f32_16x16x32_bf16 v[68:71], v[194:197], v[234:237], v[68:71]
	v_mfma_f32_16x16x32_bf16 v[64:67], v[202:205], v[234:237], v[64:67]
	v_mfma_f32_16x16x32_bf16 v[116:119], v[198:201], v[214:217], v[116:119]
	v_mfma_f32_16x16x32_bf16 v[112:115], v[206:209], v[214:217], v[112:115]
	v_mfma_f32_16x16x32_bf16 v[100:103], v[198:201], v[222:225], v[100:103]
	v_mfma_f32_16x16x32_bf16 v[96:99], v[206:209], v[222:225], v[96:99]
	v_mfma_f32_16x16x32_bf16 v[84:87], v[198:201], v[230:233], v[84:87]
	v_mfma_f32_16x16x32_bf16 v[80:83], v[206:209], v[230:233], v[80:83]
	v_mfma_f32_16x16x32_bf16 v[68:71], v[198:201], v[238:241], v[68:71]
	v_mfma_f32_16x16x32_bf16 v[64:67], v[206:209], v[238:241], v[64:67]
	s_setprio 0
	s_barrier
; #define PG8_STAGE(bufoff, gbase, voff) do { _Pragma("unroll") for (int _i = 0; _i < 2; ++_i) \
;         __builtin_amdgcn_global_load_lds((const unsigned*)((const char*)(gbase) + (voff)[_i]), (PG8_LAS unsigned*)(lds + (bufoff) + ldsw + _i * 8192), 16, 0, 0); } while (0)
; #define PG8_LDA(dst, b, h) do { _Pragma("unroll") for (int m = 0; m < 4; ++m) _Pragma("unroll") for (int k = 0; k < 2; ++k) dst[m][k] = *(const PG8_LAS bf16x8*)(lds + PG8_SA(b, h) + aoff + m * 2048 + k * 1024); } while (0)
; #define PG8_MMA(ai, bj, At, Bt) do { __builtin_amdgcn_s_setprio(1); _Pragma("unroll") for (int m = 0; m < 4; ++m) _Pragma("unroll") for (int n = 0; n < 2; ++n) _Pragma("unroll") for (int k = 0; k < 2; ++k) \
;         acc[ai][bj][m][n] = __builtin_amdgcn_mfma_f32_16x16x32_bf16(Bt[n][k], At[m][k], acc[ai][bj][m][n], 0, 0, 0); __builtin_amdgcn_s_setprio(0); } while (0)
; #define PG8_WAIT_V(n) asm volatile("s_waitcnt vmcnt(" #n ")" ::: "memory")
; #define PG8_WAIT_L(n) asm volatile("s_waitcnt lgkmcnt(" #n ")" ::: "memory")
; #define PG8_BAR __builtin_amdgcn_s_barrier()
; #define PG8_SCHED __builtin_amdgcn_sched_barrier(0)
; template <class Epi, class Sched, bool ALIGN_EPI = false, bool SP2 = false>
; __device__ __forceinline__ void gemm_phase(PG8_LAS unsigned char* lds, const Gemm g, const Sched& S, const Epi& E) {
;     ...
;             PG8_LDA(At, 1, 1); PG8_STAGE(PG8_SB(1, 0), b3, voffB); PG8_STAGE(PG8_SB(1, 1), b3 + hstep, voffB); PG8_STAGE(PG8_SA(1, 0), a3, voffA);
;             PG8_WAIT_V(8); PG8_WAIT_L(0); PG8_BAR; PG8_MMA(1, 0, At, B0); PG8_MMA(1, 1, At, B1); PG8_BAR; PG8_SCHED;
;     ...
;         if constexpr (ALIGN_EPI) { if (wr == 0) PG8_BAR; }
	s_add_i32 s24, s45, s29
	v_lshl_add_u64 v[170:171], v[170:171], 0, s[14:15]
	s_mov_b32 m0, s24
	ds_read_b128 v[210:213], v193 offset:49152
	ds_read_b128 v[214:217], v193 offset:50176
	ds_read_b128 v[218:221], v193 offset:51200
	ds_read_b128 v[222:225], v193 offset:52224
	ds_read_b128 v[226:229], v193 offset:53248
	ds_read_b128 v[230:233], v193 offset:54272
	ds_read_b128 v[234:237], v193 offset:55296
	ds_read_b128 v[238:241], v193 offset:56320
	global_load_lds_dwordx4 v[170:171], off
	s_add_i32 m0, s24, 0x2000
	s_add_u32 s24, s58, 0x40080
	v_lshl_add_u64 v[170:171], v[242:243], 0, s[14:15]
	s_addc_u32 s25, s59, 0
	s_add_i32 s45, s47, s29
	global_load_lds_dwordx4 v[170:171], off
	v_lshl_add_u64 v[170:171], s[24:25], 0, v[142:143]
	s_mov_b32 m0, s45
	s_nop 0
	global_load_lds_dwordx4 v[170:171], off
	v_lshl_add_u64 v[170:171], s[24:25], 0, v[146:147]
	s_add_i32 m0, s45, 0x2000
	s_nop 0
	global_load_lds_dwordx4 v[170:171], off
	v_lshl_add_u64 v[170:171], v[244:245], 0, s[14:15]
	s_mov_b32 m0, s90
	s_nop 0
	global_load_lds_dwordx4 v[170:171], off
	v_lshl_add_u64 v[170:171], v[246:247], 0, s[14:15]
	s_mov_b32 m0, s91
	s_nop 0
	global_load_lds_dwordx4 v[170:171], off
	s_waitcnt vmcnt(8)
	s_waitcnt lgkmcnt(0)
	s_barrier
	s_setprio 1
	s_waitcnt lgkmcnt(0)
	v_mfma_f32_16x16x32_bf16 v[60:63], v[128:131], v[210:213], v[60:63]
	v_mfma_f32_16x16x32_bf16 v[56:59], v[162:165], v[210:213], v[56:59]
	v_mfma_f32_16x16x32_bf16 v[44:47], v[128:131], v[218:221], v[44:47]
	v_mfma_f32_16x16x32_bf16 v[40:43], v[162:165], v[218:221], v[40:43]
	v_mfma_f32_16x16x32_bf16 v[28:31], v[128:131], v[226:229], v[28:31]
	v_mfma_f32_16x16x32_bf16 v[24:27], v[162:165], v[226:229], v[24:27]
	v_mfma_f32_16x16x32_bf16 v[12:15], v[128:131], v[234:237], v[12:15]
	v_mfma_f32_16x16x32_bf16 v[8:11], v[162:165], v[234:237], v[8:11]
	v_mfma_f32_16x16x32_bf16 v[60:63], v[158:161], v[214:217], v[60:63]
	v_mfma_f32_16x16x32_bf16 v[56:59], v[166:169], v[214:217], v[56:59]
	v_mfma_f32_16x16x32_bf16 v[44:47], v[158:161], v[222:225], v[44:47]
	v_mfma_f32_16x16x32_bf16 v[40:43], v[166:169], v[222:225], v[40:43]
	v_mfma_f32_16x16x32_bf16 v[28:31], v[158:161], v[230:233], v[28:31]
	v_mfma_f32_16x16x32_bf16 v[24:27], v[166:169], v[230:233], v[24:27]
	v_mfma_f32_16x16x32_bf16 v[12:15], v[158:161], v[238:241], v[12:15]
	v_mfma_f32_16x16x32_bf16 v[8:11], v[166:169], v[238:241], v[8:11]
	v_mfma_f32_16x16x32_bf16 v[52:55], v[194:197], v[210:213], v[52:55]
	v_mfma_f32_16x16x32_bf16 v[48:51], v[202:205], v[210:213], v[48:51]
	v_mfma_f32_16x16x32_bf16 v[36:39], v[194:197], v[218:221], v[36:39]
	v_mfma_f32_16x16x32_bf16 v[32:35], v[202:205], v[218:221], v[32:35]
	v_mfma_f32_16x16x32_bf16 v[20:23], v[194:197], v[226:229], v[20:23]
	v_mfma_f32_16x16x32_bf16 v[16:19], v[202:205], v[226:229], v[16:19]
	v_mfma_f32_16x16x32_bf16 v[4:7], v[194:197], v[234:237], v[4:7]
	v_mfma_f32_16x16x32_bf16 v[0:3], v[202:205], v[234:237], v[0:3]
	v_mfma_f32_16x16x32_bf16 v[52:55], v[198:201], v[214:217], v[52:55]
	v_mfma_f32_16x16x32_bf16 v[48:51], v[206:209], v[214:217], v[48:51]
	v_mfma_f32_16x16x32_bf16 v[36:39], v[198:201], v[222:225], v[36:39]
	v_mfma_f32_16x16x32_bf16 v[32:35], v[206:209], v[222:225], v[32:35]
	v_mfma_f32_16x16x32_bf16 v[20:23], v[198:201], v[230:233], v[20:23]
	v_mfma_f32_16x16x32_bf16 v[16:19], v[206:209], v[230:233], v[16:19]
	v_mfma_f32_16x16x32_bf16 v[4:7], v[198:201], v[238:241], v[4:7]
	v_mfma_f32_16x16x32_bf16 v[0:3], v[206:209], v[238:241], v[0:3]
	s_setprio 0
	s_barrier
	s_add_i32 s39, s39, 2
	s_add_u32 s56, s56, 0x100
	s_addc_u32 s57, s57, 0
	s_add_u32 s33, s33, 0x100
	s_addc_u32 s37, s37, 0
	s_cmp_gt_u32 s39, 13
	s_cbranch_scc0 .LBB0_175
	s_and_b64 vcc, exec, s[4:5]
	s_cbranch_vccz .LBB0_178
	s_barrier

; #define PG8_STAGE(bufoff, gbase, voff) do { _Pragma("unroll") for (int _i = 0; _i < 2; ++_i) \
;         __builtin_amdgcn_global_load_lds((const unsigned*)((const char*)(gbase) + (voff)[_i]), (PG8_LAS unsigned*)(lds + (bufoff) + ldsw + _i * 8192), 16, 0, 0); } while (0)
; #define PG8_LDA(dst, b, h) do { _Pragma("unroll") for (int m = 0; m < 4; ++m) _Pragma("unroll") for (int k = 0; k < 2; ++k) dst[m][k] = *(const PG8_LAS bf16x8*)(lds + PG8_SA(b, h) + aoff + m * 2048 + k * 1024); } while (0)
; #define PG8_LDB(dst, b, h) do { _Pragma("unroll") for (int n = 0; n < 2; ++n) _Pragma("unroll") for (int k = 0; k < 2; ++k) dst[n][k] = *(const PG8_LAS bf16x8*)(lds + PG8_SB(b, h) + boff + n * 2048 + k * 1024); } while (0)
; #define PG8_MMA(ai, bj, At, Bt) do { __builtin_amdgcn_s_setprio(1); _Pragma("unroll") for (int m = 0; m < 4; ++m) _Pragma("unroll") for (int n = 0; n < 2; ++n) _Pragma("unroll") for (int k = 0; k < 2; ++k) \
;         acc[ai][bj][m][n] = __builtin_amdgcn_mfma_f32_16x16x32_bf16(Bt[n][k], At[m][k], acc[ai][bj][m][n], 0, 0, 0); __builtin_amdgcn_s_setprio(0); } while (0)
; #define PG8_BAR __builtin_amdgcn_s_barrier()
; template <class Epi, class Sched, bool ALIGN_EPI = false, bool SP2 = false>
; __device__ __forceinline__ void gemm_phase(PG8_LAS unsigned char* lds, const Gemm g, const Sched& S, const Epi& E) {
;     ...
;         const bool has_next = S.next(ui + 1, nxt);
;         const char* nA = has_next ? (const char*)g.A + (size_t)nxt.pm * tstep : cA; const char* nB = has_next ? (const char*)g.Bt + (size_t)nxt.pn * tstep : cB;
;         for (int t = 0; t < nt; t += 2) {
;             const bool last = (t == nt - 2);
;             const char* a1 = cA + (size_t)(t + 1) * kstep;
;             const char* a2 = last ? nA : cA + (size_t)(t + 2) * kstep; const char* b2 = last ? nB : cB + (size_t)(t + 2) * kstep;
;             const char* a3 = a2 + kstep; const char* b3 = b2 + kstep;
;             if (last && has_next) S.a_ready(nxt);
;             if constexpr (SP2) {
;             PG8_LDB(B0, 0, 0); PG8_LDB(B1, 0, 1); PG8_SCHED; PG8_LDA(At, 0, 0); PG8_STAGE(PG8_SA(1, 1), a1 + hstep, voffA);
;             PG8_WAIT_V(8); PG8_WAIT_L(0); PG8_BAR; PG8_MMA(0, 0, At, B0); PG8_MMA(0, 1, At, B1); PG8_BAR; PG8_SCHED;
;             PG8_LDA(At, 0, 1); PG8_STAGE(PG8_SB(0, 0), b2, voffB); PG8_STAGE(PG8_SB(0, 1), b2 + hstep, voffB); PG8_STAGE(PG8_SA(0, 0), a2, voffA);
.LBB0_553:
	s_ashr_i32 s21, s20, 31
	s_lshl_b64 s[0:1], s[20:21], 19
	s_add_u32 s38, s26, s0
	s_addc_u32 s39, s27, s1
	s_and_b64 s[0:1], s[42:43], exec
	s_cselect_b32 s0, s39, s57
	s_cselect_b32 s1, s38, s56
	s_ashr_i32 s17, s16, 31
	s_lshl_b64 s[24:25], s[16:17], 19
	s_add_u32 s48, s10, s24
	s_addc_u32 s49, s12, s25
	s_and_b64 s[24:25], s[42:43], exec
	s_cselect_b32 s17, s49, s59
	s_cselect_b32 s21, s48, s58
	s_add_u32 s56, s56, 0x40080
	s_addc_u32 s57, s57, 0
	s_add_u32 s22, s58, 0x100
	s_addc_u32 s33, s59, 0
	s_mov_b32 s45, -2
	s_add_u32 s24, s56, 0xfffc0080
	s_addc_u32 s25, s57, -1
	s_add_i32 s47, 0, 0x10000
	s_cmp_eq_u32 s45, 12
	s_cselect_b32 s61, s0, s25
	s_cselect_b32 s60, s1, s24
	s_cselect_b32 s59, s17, s33
	s_cselect_b32 s58, s21, s22
	s_add_i32 s50, 0, 0x14000
	v_add_u32_e32 v162, s47, v159
	v_add_u32_e32 v170, s50, v159
	ds_read_b128 v[146:149], v162
	ds_read_b128 v[150:153], v162 offset:1024
	ds_read_b128 v[154:157], v162 offset:2048
	ds_read_b128 v[162:165], v162 offset:3072
	ds_read_b128 v[166:169], v170
	ds_read_b128 v[192:195], v170 offset:1024
	ds_read_b128 v[196:199], v170 offset:2048
	ds_read_b128 v[200:203], v170 offset:3072
	v_lshl_add_u64 v[170:171], s[56:57], 0, v[142:143]
	s_add_i32 m0, s29, 0xc000
	ds_read_b128 v[204:207], v161
	ds_read_b128 v[208:211], v161 offset:1024
	ds_read_b128 v[212:215], v161 offset:2048
	ds_read_b128 v[216:219], v161 offset:3072
	ds_read_b128 v[220:223], v161 offset:4096
	ds_read_b128 v[224:227], v161 offset:5120
	ds_read_b128 v[228:231], v161 offset:6144
	ds_read_b128 v[232:235], v161 offset:7168
	global_load_lds_dwordx4 v[170:171], off
	v_lshl_add_u64 v[170:171], s[56:57], 0, v[144:145]
	s_add_i32 m0, s29, 0xe000
	s_nop 0
	global_load_lds_dwordx4 v[170:171], off
	s_waitcnt vmcnt(8)
	s_waitcnt lgkmcnt(0)
	s_barrier
	s_setprio 1
	s_waitcnt lgkmcnt(0)
	v_mfma_f32_16x16x32_bf16 v[124:127], v[146:149], v[204:207], 0
	v_mfma_f32_16x16x32_bf16 v[120:123], v[154:157], v[204:207], 0
	v_mfma_f32_16x16x32_bf16 v[108:111], v[146:149], v[212:215], 0
	v_mfma_f32_16x16x32_bf16 v[104:107], v[154:157], v[212:215], 0
	v_mfma_f32_16x16x32_bf16 v[92:95], v[146:149], v[220:223], 0
	v_mfma_f32_16x16x32_bf16 v[88:91], v[154:157], v[220:223], 0
	v_mfma_f32_16x16x32_bf16 v[76:79], v[146:149], v[228:231], 0
	v_mfma_f32_16x16x32_bf16 v[72:75], v[154:157], v[228:231], 0
	v_mfma_f32_16x16x32_bf16 v[124:127], v[150:153], v[208:211], v[124:127]
	v_mfma_f32_16x16x32_bf16 v[120:123], v[162:165], v[208:211], v[120:123]
	v_mfma_f32_16x16x32_bf16 v[108:111], v[150:153], v[216:219], v[108:111]
	v_mfma_f32_16x16x32_bf16 v[104:107], v[162:165], v[216:219], v[104:107]
	v_mfma_f32_16x16x32_bf16 v[92:95], v[150:153], v[224:227], v[92:95]
	v_mfma_f32_16x16x32_bf16 v[88:91], v[162:165], v[224:227], v[88:91]
	v_mfma_f32_16x16x32_bf16 v[76:79], v[150:153], v[232:235], v[76:79]
	v_mfma_f32_16x16x32_bf16 v[72:75], v[162:165], v[232:235], v[72:75]
	v_mfma_f32_16x16x32_bf16 v[116:119], v[166:169], v[204:207], 0
	v_mfma_f32_16x16x32_bf16 v[112:115], v[196:199], v[204:207], 0
	v_mfma_f32_16x16x32_bf16 v[100:103], v[166:169], v[212:215], 0
	v_mfma_f32_16x16x32_bf16 v[96:99], v[196:199], v[212:215], 0
	v_mfma_f32_16x16x32_bf16 v[84:87], v[166:169], v[220:223], 0
	v_mfma_f32_16x16x32_bf16 v[80:83], v[196:199], v[220:223], 0
	v_mfma_f32_16x16x32_bf16 v[68:71], v[166:169], v[228:231], 0
	v_mfma_f32_16x16x32_bf16 v[64:67], v[196:199], v[228:231], 0
	v_mfma_f32_16x16x32_bf16 v[116:119], v[192:195], v[208:211], v[116:119]
	v_mfma_f32_16x16x32_bf16 v[112:115], v[200:203], v[208:211], v[112:115]
	v_mfma_f32_16x16x32_bf16 v[100:103], v[192:195], v[216:219], v[100:103]
	v_mfma_f32_16x16x32_bf16 v[96:99], v[200:203], v[216:219], v[96:99]
	v_mfma_f32_16x16x32_bf16 v[84:87], v[192:195], v[224:227], v[84:87]
	v_mfma_f32_16x16x32_bf16 v[80:83], v[200:203], v[224:227], v[80:83]
	v_mfma_f32_16x16x32_bf16 v[68:71], v[192:195], v[232:235], v[68:71]
	v_mfma_f32_16x16x32_bf16 v[64:67], v[200:203], v[232:235], v[64:67]
	s_setprio 0
	s_barrier
	s_add_i32 s24, s47, s23
	v_lshl_add_u64 v[170:171], s[58:59], 0, v[132:133]
	s_mov_b32 m0, s24
	ds_read_b128 v[204:207], v161 offset:16384
	ds_read_b128 v[208:211], v161 offset:17408
	ds_read_b128 v[212:215], v161 offset:18432
	ds_read_b128 v[216:219], v161 offset:19456
	ds_read_b128 v[220:223], v161 offset:20480
	ds_read_b128 v[224:227], v161 offset:21504
	ds_read_b128 v[228:231], v161 offset:22528
	ds_read_b128 v[232:235], v161 offset:23552
	global_load_lds_dwordx4 v[170:171], off
	s_add_i32 m0, s24, 0x2000
	s_add_u32 s24, s58, 0x40000
	v_lshl_add_u64 v[236:237], s[58:59], 0, v[140:141]
	s_addc_u32 s25, s59, 0
	s_add_i32 s47, s50, s23
	global_load_lds_dwordx4 v[236:237], off
	v_lshl_add_u64 v[238:239], s[24:25], 0, v[132:133]
	s_mov_b32 m0, s47
	v_lshl_add_u64 v[240:241], s[60:61], 0, v[130:131]
	global_load_lds_dwordx4 v[238:239], off
	v_lshl_add_u64 v[238:239], s[24:25], 0, v[140:141]
	s_add_i32 m0, s47, 0x2000
	s_nop 0
	global_load_lds_dwordx4 v[238:239], off
	v_lshl_add_u64 v[238:239], s[60:61], 0, v[128:129]
	s_mov_b32 m0, s29
	s_nop 0
	global_load_lds_dwordx4 v[238:239], off
	s_mov_b32 m0, s62
	s_nop 0
	global_load_lds_dwordx4 v[240:241], off
	s_waitcnt vmcnt(8)
	s_waitcnt lgkmcnt(0)
	s_barrier
; #define PG8_STAGE(bufoff, gbase, voff) do { _Pragma("unroll") for (int _i = 0; _i < 2; ++_i) \
;         __builtin_amdgcn_global_load_lds((const unsigned*)((const char*)(gbase) + (voff)[_i]), (PG8_LAS unsigned*)(lds + (bufoff) + ldsw + _i * 8192), 16, 0, 0); } while (0)
; #define PG8_LDA(dst, b, h) do { _Pragma("unroll") for (int m = 0; m < 4; ++m) _Pragma("unroll") for (int k = 0; k < 2; ++k) dst[m][k] = *(const PG8_LAS bf16x8*)(lds + PG8_SA(b, h) + aoff + m * 2048 + k * 1024); } while (0)
; #define PG8_LDB(dst, b, h) do { _Pragma("unroll") for (int n = 0; n < 2; ++n) _Pragma("unroll") for (int k = 0; k < 2; ++k) dst[n][k] = *(const PG8_LAS bf16x8*)(lds + PG8_SB(b, h) + boff + n * 2048 + k * 1024); } while (0)
; #define PG8_MMA(ai, bj, At, Bt) do { __builtin_amdgcn_s_setprio(1); _Pragma("unroll") for (int m = 0; m < 4; ++m) _Pragma("unroll") for (int n = 0; n < 2; ++n) _Pragma("unroll") for (int k = 0; k < 2; ++k) \
;         acc[ai][bj][m][n] = __builtin_amdgcn_mfma_f32_16x16x32_bf16(Bt[n][k], At[m][k], acc[ai][bj][m][n], 0, 0, 0); __builtin_amdgcn_s_setprio(0); } while (0)
; #define PG8_WAIT_V(n) asm volatile("s_waitcnt vmcnt(" #n ")" ::: "memory")
; #define PG8_WAIT_L(n) asm volatile("s_waitcnt lgkmcnt(" #n ")" ::: "memory")
; #define PG8_BAR __builtin_amdgcn_s_barrier()
; #define PG8_SCHED __builtin_amdgcn_sched_barrier(0)
; template <class Epi, class Sched, bool ALIGN_EPI = false, bool SP2 = false>
; __device__ __forceinline__ void gemm_phase(PG8_LAS unsigned char* lds, const Gemm g, const Sched& S, const Epi& E) {
;     ...
;             PG8_WAIT_V(8); PG8_WAIT_L(0); PG8_BAR; PG8_MMA(1, 0, At, B0); PG8_MMA(1, 1, At, B1); PG8_BAR; PG8_SCHED;
;             PG8_LDB(B0, 1, 0); PG8_LDB(B1, 1, 1); PG8_SCHED; PG8_LDA(At, 1, 0); PG8_STAGE(PG8_SA(0, 1), a2 + hstep, voffA);
;             PG8_WAIT_V(8); PG8_WAIT_L(0); PG8_BAR; PG8_MMA(0, 0, At, B0); PG8_MMA(0, 1, At, B1); PG8_BAR; PG8_SCHED;
	s_setprio 1
	s_waitcnt lgkmcnt(0)
	v_mfma_f32_16x16x32_bf16 v[60:63], v[146:149], v[204:207], 0
	v_mfma_f32_16x16x32_bf16 v[56:59], v[154:157], v[204:207], 0
	v_mfma_f32_16x16x32_bf16 v[44:47], v[146:149], v[212:215], 0
	v_mfma_f32_16x16x32_bf16 v[40:43], v[154:157], v[212:215], 0
	v_mfma_f32_16x16x32_bf16 v[28:31], v[146:149], v[220:223], 0
	v_mfma_f32_16x16x32_bf16 v[24:27], v[154:157], v[220:223], 0
	v_mfma_f32_16x16x32_bf16 v[12:15], v[146:149], v[228:231], 0
	v_mfma_f32_16x16x32_bf16 v[8:11], v[154:157], v[228:231], 0
	v_mfma_f32_16x16x32_bf16 v[60:63], v[150:153], v[208:211], v[60:63]
	v_mfma_f32_16x16x32_bf16 v[56:59], v[162:165], v[208:211], v[56:59]
	v_mfma_f32_16x16x32_bf16 v[44:47], v[150:153], v[216:219], v[44:47]
	v_mfma_f32_16x16x32_bf16 v[40:43], v[162:165], v[216:219], v[40:43]
	v_mfma_f32_16x16x32_bf16 v[28:31], v[150:153], v[224:227], v[28:31]
	v_mfma_f32_16x16x32_bf16 v[24:27], v[162:165], v[224:227], v[24:27]
	v_mfma_f32_16x16x32_bf16 v[12:15], v[150:153], v[232:235], v[12:15]
	v_mfma_f32_16x16x32_bf16 v[8:11], v[162:165], v[232:235], v[8:11]
	v_mfma_f32_16x16x32_bf16 v[52:55], v[166:169], v[204:207], 0
	v_mfma_f32_16x16x32_bf16 v[48:51], v[196:199], v[204:207], 0
	v_mfma_f32_16x16x32_bf16 v[36:39], v[166:169], v[212:215], 0
	v_mfma_f32_16x16x32_bf16 v[32:35], v[196:199], v[212:215], 0
	v_mfma_f32_16x16x32_bf16 v[20:23], v[166:169], v[220:223], 0
	v_mfma_f32_16x16x32_bf16 v[16:19], v[196:199], v[220:223], 0
	v_mfma_f32_16x16x32_bf16 v[4:7], v[166:169], v[228:231], 0
	v_mfma_f32_16x16x32_bf16 v[0:3], v[196:199], v[228:231], 0
	v_mfma_f32_16x16x32_bf16 v[52:55], v[192:195], v[208:211], v[52:55]
	v_mfma_f32_16x16x32_bf16 v[48:51], v[200:203], v[208:211], v[48:51]
	v_mfma_f32_16x16x32_bf16 v[36:39], v[192:195], v[216:219], v[36:39]
	v_mfma_f32_16x16x32_bf16 v[32:35], v[200:203], v[216:219], v[32:35]
	v_mfma_f32_16x16x32_bf16 v[20:23], v[192:195], v[224:227], v[20:23]
	v_mfma_f32_16x16x32_bf16 v[16:19], v[200:203], v[224:227], v[16:19]
	v_mfma_f32_16x16x32_bf16 v[4:7], v[192:195], v[232:235], v[4:7]
	v_mfma_f32_16x16x32_bf16 v[0:3], v[200:203], v[232:235], v[0:3]
	s_setprio 0
	s_barrier
	s_add_i32 s47, 0, 0x18000
	s_add_i32 s50, 0, 0x1c000
	v_add_u32_e32 v162, s47, v159
	v_add_u32_e32 v184, s50, v159
	ds_read_b128 v[146:149], v162
	ds_read_b128 v[150:153], v162 offset:1024
	ds_read_b128 v[154:157], v162 offset:2048
	ds_read_b128 v[162:165], v162 offset:3072
	ds_read_b128 v[166:169], v184
	ds_read_b128 v[192:195], v184 offset:1024
	ds_read_b128 v[196:199], v184 offset:2048
	ds_read_b128 v[200:203], v184 offset:3072
	s_add_u32 s24, s60, 0x40000
	s_addc_u32 s25, s61, 0
	s_mov_b32 m0, s63
	v_lshl_add_u64 v[242:243], s[24:25], 0, v[128:129]
	ds_read_b128 v[204:207], v161 offset:32768
	ds_read_b128 v[208:211], v161 offset:33792
	ds_read_b128 v[212:215], v161 offset:34816
	ds_read_b128 v[216:219], v161 offset:35840
	ds_read_b128 v[220:223], v161 offset:36864
	ds_read_b128 v[224:227], v161 offset:37888
	ds_read_b128 v[228:231], v161 offset:38912
	ds_read_b128 v[232:235], v161 offset:39936
	global_load_lds_dwordx4 v[242:243], off
	v_lshl_add_u64 v[242:243], s[24:25], 0, v[130:131]
	s_mov_b32 m0, s64
	s_nop 0
	global_load_lds_dwordx4 v[242:243], off
	s_waitcnt vmcnt(8)
	s_waitcnt lgkmcnt(0)
	s_barrier
	s_setprio 1
	s_waitcnt lgkmcnt(0)
	v_mfma_f32_16x16x32_bf16 v[124:127], v[146:149], v[204:207], v[124:127]
	v_mfma_f32_16x16x32_bf16 v[120:123], v[154:157], v[204:207], v[120:123]
	v_mfma_f32_16x16x32_bf16 v[108:111], v[146:149], v[212:215], v[108:111]
	v_mfma_f32_16x16x32_bf16 v[104:107], v[154:157], v[212:215], v[104:107]
	v_mfma_f32_16x16x32_bf16 v[92:95], v[146:149], v[220:223], v[92:95]
	v_mfma_f32_16x16x32_bf16 v[88:91], v[154:157], v[220:223], v[88:91]
	v_mfma_f32_16x16x32_bf16 v[76:79], v[146:149], v[228:231], v[76:79]
	v_mfma_f32_16x16x32_bf16 v[72:75], v[154:157], v[228:231], v[72:75]
	v_mfma_f32_16x16x32_bf16 v[124:127], v[150:153], v[208:211], v[124:127]
	v_mfma_f32_16x16x32_bf16 v[120:123], v[162:165], v[208:211], v[120:123]
	v_mfma_f32_16x16x32_bf16 v[108:111], v[150:153], v[216:219], v[108:111]
	v_mfma_f32_16x16x32_bf16 v[104:107], v[162:165], v[216:219], v[104:107]
	v_mfma_f32_16x16x32_bf16 v[92:95], v[150:153], v[224:227], v[92:95]
	v_mfma_f32_16x16x32_bf16 v[88:91], v[162:165], v[224:227], v[88:91]
	v_mfma_f32_16x16x32_bf16 v[76:79], v[150:153], v[232:235], v[76:79]
	v_mfma_f32_16x16x32_bf16 v[72:75], v[162:165], v[232:235], v[72:75]
	v_mfma_f32_16x16x32_bf16 v[116:119], v[166:169], v[204:207], v[116:119]
	v_mfma_f32_16x16x32_bf16 v[112:115], v[196:199], v[204:207], v[112:115]
	v_mfma_f32_16x16x32_bf16 v[100:103], v[166:169], v[212:215], v[100:103]
	v_mfma_f32_16x16x32_bf16 v[96:99], v[196:199], v[212:215], v[96:99]
	v_mfma_f32_16x16x32_bf16 v[84:87], v[166:169], v[220:223], v[84:87]
	v_mfma_f32_16x16x32_bf16 v[80:83], v[196:199], v[220:223], v[80:83]
	v_mfma_f32_16x16x32_bf16 v[68:71], v[166:169], v[228:231], v[68:71]
	v_mfma_f32_16x16x32_bf16 v[64:67], v[196:199], v[228:231], v[64:67]
	v_mfma_f32_16x16x32_bf16 v[116:119], v[192:195], v[208:211], v[116:119]
	v_mfma_f32_16x16x32_bf16 v[112:115], v[200:203], v[208:211], v[112:115]
	v_mfma_f32_16x16x32_bf16 v[100:103], v[192:195], v[216:219], v[100:103]
	v_mfma_f32_16x16x32_bf16 v[96:99], v[200:203], v[216:219], v[96:99]
	v_mfma_f32_16x16x32_bf16 v[84:87], v[192:195], v[224:227], v[84:87]
	v_mfma_f32_16x16x32_bf16 v[80:83], v[200:203], v[224:227], v[80:83]
	v_mfma_f32_16x16x32_bf16 v[68:71], v[192:195], v[232:235], v[68:71]
	v_mfma_f32_16x16x32_bf16 v[64:67], v[200:203], v[232:235], v[64:67]
	s_setprio 0
	s_barrier
; #define PG8_STAGE(bufoff, gbase, voff) do { _Pragma("unroll") for (int _i = 0; _i < 2; ++_i) \
;         __builtin_amdgcn_global_load_lds((const unsigned*)((const char*)(gbase) + (voff)[_i]), (PG8_LAS unsigned*)(lds + (bufoff) + ldsw + _i * 8192), 16, 0, 0); } while (0)
; #define PG8_LDA(dst, b, h) do { _Pragma("unroll") for (int m = 0; m < 4; ++m) _Pragma("unroll") for (int k = 0; k < 2; ++k) dst[m][k] = *(const PG8_LAS bf16x8*)(lds + PG8_SA(b, h) + aoff + m * 2048 + k * 1024); } while (0)
; #define PG8_LDB(dst, b, h) do { _Pragma("unroll") for (int n = 0; n < 2; ++n) _Pragma("unroll") for (int k = 0; k < 2; ++k) dst[n][k] = *(const PG8_LAS bf16x8*)(lds + PG8_SB(b, h) + boff + n * 2048 + k * 1024); } while (0)
; template <class Epi, class Sched, bool ALIGN_EPI = false, bool SP2 = false>
; __device__ __forceinline__ void gemm_phase(PG8_LAS unsigned char* lds, const Gemm g, const Sched& S, const Epi& E) {
;     ...
;         for (int t = 0; t < nt; t += 2) {
;             const bool last = (t == nt - 2);
;             const char* a1 = cA + (size_t)(t + 1) * kstep;
;             const char* a2 = last ? nA : cA + (size_t)(t + 2) * kstep; const char* b2 = last ? nB : cB + (size_t)(t + 2) * kstep;
;             const char* a3 = a2 + kstep; const char* b3 = b2 + kstep;
;             if (last && has_next) S.a_ready(nxt);
;             if constexpr (SP2) {
;             PG8_LDB(B0, 0, 0); PG8_LDB(B1, 0, 1); PG8_SCHED; PG8_LDA(At, 0, 0); PG8_STAGE(PG8_SA(1, 1), a1 + hstep, voffA);
;             PG8_WAIT_V(8); PG8_WAIT_L(0); PG8_BAR; PG8_MMA(0, 0, At, B0); PG8_MMA(0, 1, At, B1); PG8_BAR; PG8_SCHED;
;             PG8_LDA(At, 0, 1); PG8_STAGE(PG8_SB(0, 0), b2, voffB); PG8_STAGE(PG8_SB(0, 1), b2 + hstep, voffB); PG8_STAGE(PG8_SA(0, 0), a2, voffA);
;             PG8_WAIT_V(8); PG8_WAIT_L(0); PG8_BAR; PG8_MMA(1, 0, At, B0); PG8_MMA(1, 1, At, B1); PG8_BAR; PG8_SCHED;
;             PG8_LDB(B0, 1, 0); PG8_LDB(B1, 1, 1); PG8_SCHED; PG8_LDA(At, 1, 0); PG8_STAGE(PG8_SA(0, 1), a2 + hstep, voffA);
;             PG8_WAIT_V(8); PG8_WAIT_L(0); PG8_BAR; PG8_MMA(0, 0, At, B0); PG8_MMA(0, 1, At, B1); PG8_BAR; PG8_SCHED;
;             PG8_LDA(At, 1, 1); PG8_STAGE(PG8_SB(1, 0), b3, voffB); PG8_STAGE(PG8_SB(1, 1), b3 + hstep, voffB); PG8_STAGE(PG8_SA(1, 0), a3, voffA);
;             PG8_WAIT_V(8); PG8_WAIT_L(0); PG8_BAR; PG8_MMA(1, 0, At, B0); PG8_MMA(1, 1, At, B1); PG8_BAR; PG8_SCHED;
	s_add_i32 s24, s47, s23
	v_lshl_add_u64 v[170:171], v[170:171], 0, s[14:15]
	s_mov_b32 m0, s24
	ds_read_b128 v[204:207], v161 offset:49152
	ds_read_b128 v[208:211], v161 offset:50176
	ds_read_b128 v[212:215], v161 offset:51200
	ds_read_b128 v[216:219], v161 offset:52224
	ds_read_b128 v[220:223], v161 offset:53248
	ds_read_b128 v[224:227], v161 offset:54272
	ds_read_b128 v[228:231], v161 offset:55296
	ds_read_b128 v[232:235], v161 offset:56320
	global_load_lds_dwordx4 v[170:171], off
	s_add_i32 m0, s24, 0x2000
	s_add_u32 s24, s58, 0x40080
	v_lshl_add_u64 v[170:171], v[236:237], 0, s[14:15]
	s_addc_u32 s25, s59, 0
	s_add_i32 s47, s50, s23
	global_load_lds_dwordx4 v[170:171], off
	v_lshl_add_u64 v[170:171], s[24:25], 0, v[132:133]
	s_mov_b32 m0, s47
	s_nop 0
	global_load_lds_dwordx4 v[170:171], off
	v_lshl_add_u64 v[170:171], s[24:25], 0, v[140:141]
	s_add_i32 m0, s47, 0x2000
	s_nop 0
	global_load_lds_dwordx4 v[170:171], off
	v_lshl_add_u64 v[170:171], v[238:239], 0, s[14:15]
	s_mov_b32 m0, s65
	s_nop 0
	global_load_lds_dwordx4 v[170:171], off
	v_lshl_add_u64 v[170:171], v[240:241], 0, s[14:15]
	s_mov_b32 m0, s66
	s_nop 0
	global_load_lds_dwordx4 v[170:171], off
	s_waitcnt vmcnt(8)
	s_waitcnt lgkmcnt(0)
	s_barrier
	s_setprio 1
	s_waitcnt lgkmcnt(0)
	v_mfma_f32_16x16x32_bf16 v[60:63], v[146:149], v[204:207], v[60:63]
	v_mfma_f32_16x16x32_bf16 v[56:59], v[154:157], v[204:207], v[56:59]
	v_mfma_f32_16x16x32_bf16 v[44:47], v[146:149], v[212:215], v[44:47]
	v_mfma_f32_16x16x32_bf16 v[40:43], v[154:157], v[212:215], v[40:43]
	v_mfma_f32_16x16x32_bf16 v[28:31], v[146:149], v[220:223], v[28:31]
	v_mfma_f32_16x16x32_bf16 v[24:27], v[154:157], v[220:223], v[24:27]
	v_mfma_f32_16x16x32_bf16 v[12:15], v[146:149], v[228:231], v[12:15]
	v_mfma_f32_16x16x32_bf16 v[8:11], v[154:157], v[228:231], v[8:11]
	v_mfma_f32_16x16x32_bf16 v[60:63], v[150:153], v[208:211], v[60:63]
	v_mfma_f32_16x16x32_bf16 v[56:59], v[162:165], v[208:211], v[56:59]
	v_mfma_f32_16x16x32_bf16 v[44:47], v[150:153], v[216:219], v[44:47]
	v_mfma_f32_16x16x32_bf16 v[40:43], v[162:165], v[216:219], v[40:43]
	v_mfma_f32_16x16x32_bf16 v[28:31], v[150:153], v[224:227], v[28:31]
	v_mfma_f32_16x16x32_bf16 v[24:27], v[162:165], v[224:227], v[24:27]
	v_mfma_f32_16x16x32_bf16 v[12:15], v[150:153], v[232:235], v[12:15]
	v_mfma_f32_16x16x32_bf16 v[8:11], v[162:165], v[232:235], v[8:11]
	v_mfma_f32_16x16x32_bf16 v[52:55], v[166:169], v[204:207], v[52:55]
	v_mfma_f32_16x16x32_bf16 v[48:51], v[196:199], v[204:207], v[48:51]
	v_mfma_f32_16x16x32_bf16 v[36:39], v[166:169], v[212:215], v[36:39]
	v_mfma_f32_16x16x32_bf16 v[32:35], v[196:199], v[212:215], v[32:35]
	v_mfma_f32_16x16x32_bf16 v[20:23], v[166:169], v[220:223], v[20:23]
	v_mfma_f32_16x16x32_bf16 v[16:19], v[196:199], v[220:223], v[16:19]
	v_mfma_f32_16x16x32_bf16 v[4:7], v[166:169], v[228:231], v[4:7]
	v_mfma_f32_16x16x32_bf16 v[0:3], v[196:199], v[228:231], v[0:3]
	v_mfma_f32_16x16x32_bf16 v[52:55], v[192:195], v[208:211], v[52:55]
	v_mfma_f32_16x16x32_bf16 v[48:51], v[200:203], v[208:211], v[48:51]
	v_mfma_f32_16x16x32_bf16 v[36:39], v[192:195], v[216:219], v[36:39]
	v_mfma_f32_16x16x32_bf16 v[32:35], v[200:203], v[216:219], v[32:35]
	v_mfma_f32_16x16x32_bf16 v[20:23], v[192:195], v[224:227], v[20:23]
	v_mfma_f32_16x16x32_bf16 v[16:19], v[200:203], v[224:227], v[16:19]
	v_mfma_f32_16x16x32_bf16 v[4:7], v[192:195], v[232:235], v[4:7]
	v_mfma_f32_16x16x32_bf16 v[0:3], v[200:203], v[232:235], v[0:3]
	s_setprio 0
	s_barrier
	s_add_i32 s45, s45, 2
	s_add_u32 s56, s56, 0x100
	s_addc_u32 s57, s57, 0
	s_add_u32 s22, s22, 0x100
	s_addc_u32 s33, s33, 0
	s_cmp_gt_u32 s45, 13
.LBB0_554:
	s_add_u32 s24, s56, 0xfffc0080
	s_addc_u32 s25, s57, -1
	s_add_i32 s47, 0, 0x10000
	s_cmp_eq_u32 s45, 12
	s_cselect_b32 s61, s0, s25
	s_cselect_b32 s60, s1, s24
	s_cselect_b32 s59, s17, s33
	s_cselect_b32 s58, s21, s22
	s_add_i32 s50, 0, 0x14000
	v_add_u32_e32 v162, s47, v159
	v_add_u32_e32 v170, s50, v159
	ds_read_b128 v[146:149], v162
	ds_read_b128 v[150:153], v162 offset:1024
	ds_read_b128 v[154:157], v162 offset:2048
	ds_read_b128 v[162:165], v162 offset:3072
	ds_read_b128 v[166:169], v170
	ds_read_b128 v[192:195], v170 offset:1024
	ds_read_b128 v[196:199], v170 offset:2048
	ds_read_b128 v[200:203], v170 offset:3072
	v_lshl_add_u64 v[170:171], s[56:57], 0, v[142:143]
	s_add_i32 m0, s29, 0xc000
	ds_read_b128 v[204:207], v161
	ds_read_b128 v[208:211], v161 offset:1024
	ds_read_b128 v[212:215], v161 offset:2048
	ds_read_b128 v[216:219], v161 offset:3072
	ds_read_b128 v[220:223], v161 offset:4096
	ds_read_b128 v[224:227], v161 offset:5120
	ds_read_b128 v[228:231], v161 offset:6144
	ds_read_b128 v[232:235], v161 offset:7168
	global_load_lds_dwordx4 v[170:171], off
	v_lshl_add_u64 v[170:171], s[56:57], 0, v[144:145]
	s_add_i32 m0, s29, 0xe000
	s_nop 0
	global_load_lds_dwordx4 v[170:171], off
	s_waitcnt vmcnt(8)
	s_waitcnt lgkmcnt(0)
	s_barrier
; #define PG8_STAGE(bufoff, gbase, voff) do { _Pragma("unroll") for (int _i = 0; _i < 2; ++_i) \
;         __builtin_amdgcn_global_load_lds((const unsigned*)((const char*)(gbase) + (voff)[_i]), (PG8_LAS unsigned*)(lds + (bufoff) + ldsw + _i * 8192), 16, 0, 0); } while (0)
; #define PG8_LDA(dst, b, h) do { _Pragma("unroll") for (int m = 0; m < 4; ++m) _Pragma("unroll") for (int k = 0; k < 2; ++k) dst[m][k] = *(const PG8_LAS bf16x8*)(lds + PG8_SA(b, h) + aoff + m * 2048 + k * 1024); } while (0)
; #define PG8_MMA(ai, bj, At, Bt) do { __builtin_amdgcn_s_setprio(1); _Pragma("unroll") for (int m = 0; m < 4; ++m) _Pragma("unroll") for (int n = 0; n < 2; ++n) _Pragma("unroll") for (int k = 0; k < 2; ++k) \
;         acc[ai][bj][m][n] = __builtin_amdgcn_mfma_f32_16x16x32_bf16(Bt[n][k], At[m][k], acc[ai][bj][m][n], 0, 0, 0); __builtin_amdgcn_s_setprio(0); } while (0)
; #define PG8_WAIT_V(n) asm volatile("s_waitcnt vmcnt(" #n ")" ::: "memory")
; #define PG8_WAIT_L(n) asm volatile("s_waitcnt lgkmcnt(" #n ")" ::: "memory")
; #define PG8_BAR __builtin_amdgcn_s_barrier()
; #define PG8_SCHED __builtin_amdgcn_sched_barrier(0)
; template <class Epi, class Sched, bool ALIGN_EPI = false, bool SP2 = false>
; __device__ __forceinline__ void gemm_phase(PG8_LAS unsigned char* lds, const Gemm g, const Sched& S, const Epi& E) {
;     ...
;             PG8_WAIT_V(8); PG8_WAIT_L(0); PG8_BAR; PG8_MMA(0, 0, At, B0); PG8_MMA(0, 1, At, B1); PG8_BAR; PG8_SCHED;
;             PG8_LDA(At, 0, 1); PG8_STAGE(PG8_SB(0, 0), b2, voffB); PG8_STAGE(PG8_SB(0, 1), b2 + hstep, voffB); PG8_STAGE(PG8_SA(0, 0), a2, voffA);
;             PG8_WAIT_V(8); PG8_WAIT_L(0); PG8_BAR; PG8_MMA(1, 0, At, B0); PG8_MMA(1, 1, At, B1); PG8_BAR; PG8_SCHED;
	s_setprio 1
	s_waitcnt lgkmcnt(0)
	v_mfma_f32_16x16x32_bf16 v[124:127], v[146:149], v[204:207], v[124:127]
	v_mfma_f32_16x16x32_bf16 v[120:123], v[154:157], v[204:207], v[120:123]
	v_mfma_f32_16x16x32_bf16 v[108:111], v[146:149], v[212:215], v[108:111]
	v_mfma_f32_16x16x32_bf16 v[104:107], v[154:157], v[212:215], v[104:107]
	v_mfma_f32_16x16x32_bf16 v[92:95], v[146:149], v[220:223], v[92:95]
	v_mfma_f32_16x16x32_bf16 v[88:91], v[154:157], v[220:223], v[88:91]
	v_mfma_f32_16x16x32_bf16 v[76:79], v[146:149], v[228:231], v[76:79]
	v_mfma_f32_16x16x32_bf16 v[72:75], v[154:157], v[228:231], v[72:75]
	v_mfma_f32_16x16x32_bf16 v[124:127], v[150:153], v[208:211], v[124:127]
	v_mfma_f32_16x16x32_bf16 v[120:123], v[162:165], v[208:211], v[120:123]
	v_mfma_f32_16x16x32_bf16 v[108:111], v[150:153], v[216:219], v[108:111]
	v_mfma_f32_16x16x32_bf16 v[104:107], v[162:165], v[216:219], v[104:107]
	v_mfma_f32_16x16x32_bf16 v[92:95], v[150:153], v[224:227], v[92:95]
	v_mfma_f32_16x16x32_bf16 v[88:91], v[162:165], v[224:227], v[88:91]
	v_mfma_f32_16x16x32_bf16 v[76:79], v[150:153], v[232:235], v[76:79]
	v_mfma_f32_16x16x32_bf16 v[72:75], v[162:165], v[232:235], v[72:75]
	v_mfma_f32_16x16x32_bf16 v[116:119], v[166:169], v[204:207], v[116:119]
	v_mfma_f32_16x16x32_bf16 v[112:115], v[196:199], v[204:207], v[112:115]
	v_mfma_f32_16x16x32_bf16 v[100:103], v[166:169], v[212:215], v[100:103]
	v_mfma_f32_16x16x32_bf16 v[96:99], v[196:199], v[212:215], v[96:99]
	v_mfma_f32_16x16x32_bf16 v[84:87], v[166:169], v[220:223], v[84:87]
	v_mfma_f32_16x16x32_bf16 v[80:83], v[196:199], v[220:223], v[80:83]
	v_mfma_f32_16x16x32_bf16 v[68:71], v[166:169], v[228:231], v[68:71]
	v_mfma_f32_16x16x32_bf16 v[64:67], v[196:199], v[228:231], v[64:67]
	v_mfma_f32_16x16x32_bf16 v[116:119], v[192:195], v[208:211], v[116:119]
	v_mfma_f32_16x16x32_bf16 v[112:115], v[200:203], v[208:211], v[112:115]
	v_mfma_f32_16x16x32_bf16 v[100:103], v[192:195], v[216:219], v[100:103]
	v_mfma_f32_16x16x32_bf16 v[96:99], v[200:203], v[216:219], v[96:99]
	v_mfma_f32_16x16x32_bf16 v[84:87], v[192:195], v[224:227], v[84:87]
	v_mfma_f32_16x16x32_bf16 v[80:83], v[200:203], v[224:227], v[80:83]
	v_mfma_f32_16x16x32_bf16 v[68:71], v[192:195], v[232:235], v[68:71]
	v_mfma_f32_16x16x32_bf16 v[64:67], v[200:203], v[232:235], v[64:67]
	s_setprio 0
	s_barrier
	s_add_i32 s24, s47, s23
	v_lshl_add_u64 v[170:171], s[58:59], 0, v[132:133]
	s_mov_b32 m0, s24
	ds_read_b128 v[204:207], v161 offset:16384
	ds_read_b128 v[208:211], v161 offset:17408
	ds_read_b128 v[212:215], v161 offset:18432
	ds_read_b128 v[216:219], v161 offset:19456
	ds_read_b128 v[220:223], v161 offset:20480
	ds_read_b128 v[224:227], v161 offset:21504
	ds_read_b128 v[228:231], v161 offset:22528
	ds_read_b128 v[232:235], v161 offset:23552
	global_load_lds_dwordx4 v[170:171], off
	s_add_i32 m0, s24, 0x2000
	s_add_u32 s24, s58, 0x40000
	v_lshl_add_u64 v[236:237], s[58:59], 0, v[140:141]
	s_addc_u32 s25, s59, 0
	s_add_i32 s47, s50, s23
	global_load_lds_dwordx4 v[236:237], off
	v_lshl_add_u64 v[238:239], s[24:25], 0, v[132:133]
	s_mov_b32 m0, s47
	v_lshl_add_u64 v[240:241], s[60:61], 0, v[130:131]
	global_load_lds_dwordx4 v[238:239], off
	v_lshl_add_u64 v[238:239], s[24:25], 0, v[140:141]
	s_add_i32 m0, s47, 0x2000
	s_nop 0
	global_load_lds_dwordx4 v[238:239], off
	v_lshl_add_u64 v[238:239], s[60:61], 0, v[128:129]
	s_mov_b32 m0, s29
	s_nop 0
	global_load_lds_dwordx4 v[238:239], off
	s_mov_b32 m0, s62
	s_nop 0
	global_load_lds_dwordx4 v[240:241], off
	s_waitcnt vmcnt(8)
	s_waitcnt lgkmcnt(0)
	s_barrier
	s_setprio 1
	s_waitcnt lgkmcnt(0)
	v_mfma_f32_16x16x32_bf16 v[60:63], v[146:149], v[204:207], v[60:63]
	v_mfma_f32_16x16x32_bf16 v[56:59], v[154:157], v[204:207], v[56:59]
	v_mfma_f32_16x16x32_bf16 v[44:47], v[146:149], v[212:215], v[44:47]
	v_mfma_f32_16x16x32_bf16 v[40:43], v[154:157], v[212:215], v[40:43]
	v_mfma_f32_16x16x32_bf16 v[28:31], v[146:149], v[220:223], v[28:31]
	v_mfma_f32_16x16x32_bf16 v[24:27], v[154:157], v[220:223], v[24:27]
	v_mfma_f32_16x16x32_bf16 v[12:15], v[146:149], v[228:231], v[12:15]
	v_mfma_f32_16x16x32_bf16 v[8:11], v[154:157], v[228:231], v[8:11]
	v_mfma_f32_16x16x32_bf16 v[60:63], v[150:153], v[208:211], v[60:63]
	v_mfma_f32_16x16x32_bf16 v[56:59], v[162:165], v[208:211], v[56:59]
	v_mfma_f32_16x16x32_bf16 v[44:47], v[150:153], v[216:219], v[44:47]
	v_mfma_f32_16x16x32_bf16 v[40:43], v[162:165], v[216:219], v[40:43]
	v_mfma_f32_16x16x32_bf16 v[28:31], v[150:153], v[224:227], v[28:31]
	v_mfma_f32_16x16x32_bf16 v[24:27], v[162:165], v[224:227], v[24:27]
	v_mfma_f32_16x16x32_bf16 v[12:15], v[150:153], v[232:235], v[12:15]
	v_mfma_f32_16x16x32_bf16 v[8:11], v[162:165], v[232:235], v[8:11]
	v_mfma_f32_16x16x32_bf16 v[52:55], v[166:169], v[204:207], v[52:55]
	v_mfma_f32_16x16x32_bf16 v[48:51], v[196:199], v[204:207], v[48:51]
	v_mfma_f32_16x16x32_bf16 v[36:39], v[166:169], v[212:215], v[36:39]
	v_mfma_f32_16x16x32_bf16 v[32:35], v[196:199], v[212:215], v[32:35]
	v_mfma_f32_16x16x32_bf16 v[20:23], v[166:169], v[220:223], v[20:23]
	v_mfma_f32_16x16x32_bf16 v[16:19], v[196:199], v[220:223], v[16:19]
	v_mfma_f32_16x16x32_bf16 v[4:7], v[166:169], v[228:231], v[4:7]
	v_mfma_f32_16x16x32_bf16 v[0:3], v[196:199], v[228:231], v[0:3]
	v_mfma_f32_16x16x32_bf16 v[52:55], v[192:195], v[208:211], v[52:55]
	v_mfma_f32_16x16x32_bf16 v[48:51], v[200:203], v[208:211], v[48:51]
	v_mfma_f32_16x16x32_bf16 v[36:39], v[192:195], v[216:219], v[36:39]
	v_mfma_f32_16x16x32_bf16 v[32:35], v[200:203], v[216:219], v[32:35]
	v_mfma_f32_16x16x32_bf16 v[20:23], v[192:195], v[224:227], v[20:23]
	v_mfma_f32_16x16x32_bf16 v[16:19], v[200:203], v[224:227], v[16:19]
	v_mfma_f32_16x16x32_bf16 v[4:7], v[192:195], v[232:235], v[4:7]
	v_mfma_f32_16x16x32_bf16 v[0:3], v[200:203], v[232:235], v[0:3]
	s_setprio 0
	s_barrier
; #define PG8_STAGE(bufoff, gbase, voff) do { _Pragma("unroll") for (int _i = 0; _i < 2; ++_i) \
;         __builtin_amdgcn_global_load_lds((const unsigned*)((const char*)(gbase) + (voff)[_i]), (PG8_LAS unsigned*)(lds + (bufoff) + ldsw + _i * 8192), 16, 0, 0); } while (0)
; #define PG8_LDA(dst, b, h) do { _Pragma("unroll") for (int m = 0; m < 4; ++m) _Pragma("unroll") for (int k = 0; k < 2; ++k) dst[m][k] = *(const PG8_LAS bf16x8*)(lds + PG8_SA(b, h) + aoff + m * 2048 + k * 1024); } while (0)
; #define PG8_LDB(dst, b, h) do { _Pragma("unroll") for (int n = 0; n < 2; ++n) _Pragma("unroll") for (int k = 0; k < 2; ++k) dst[n][k] = *(const PG8_LAS bf16x8*)(lds + PG8_SB(b, h) + boff + n * 2048 + k * 1024); } while (0)
; #define PG8_MMA(ai, bj, At, Bt) do { __builtin_amdgcn_s_setprio(1); _Pragma("unroll") for (int m = 0; m < 4; ++m) _Pragma("unroll") for (int n = 0; n < 2; ++n) _Pragma("unroll") for (int k = 0; k < 2; ++k) \
;         acc[ai][bj][m][n] = __builtin_amdgcn_mfma_f32_16x16x32_bf16(Bt[n][k], At[m][k], acc[ai][bj][m][n], 0, 0, 0); __builtin_amdgcn_s_setprio(0); } while (0)
; #define PG8_WAIT_V(n) asm volatile("s_waitcnt vmcnt(" #n ")" ::: "memory")
; #define PG8_WAIT_L(n) asm volatile("s_waitcnt lgkmcnt(" #n ")" ::: "memory")
; #define PG8_BAR __builtin_amdgcn_s_barrier()
; #define PG8_SCHED __builtin_amdgcn_sched_barrier(0)
; template <class Epi, class Sched, bool ALIGN_EPI = false, bool SP2 = false>
; __device__ __forceinline__ void gemm_phase(PG8_LAS unsigned char* lds, const Gemm g, const Sched& S, const Epi& E) {
;     ...
;             PG8_LDB(B0, 1, 0); PG8_LDB(B1, 1, 1); PG8_SCHED; PG8_LDA(At, 1, 0); PG8_STAGE(PG8_SA(0, 1), a2 + hstep, voffA);
;             PG8_WAIT_V(8); PG8_WAIT_L(0); PG8_BAR; PG8_MMA(0, 0, At, B0); PG8_MMA(0, 1, At, B1); PG8_BAR; PG8_SCHED;
	s_add_i32 s47, 0, 0x18000
	s_add_i32 s50, 0, 0x1c000
	v_add_u32_e32 v162, s47, v159
	v_add_u32_e32 v184, s50, v159
	ds_read_b128 v[146:149], v162
	ds_read_b128 v[150:153], v162 offset:1024
	ds_read_b128 v[154:157], v162 offset:2048
	ds_read_b128 v[162:165], v162 offset:3072
	ds_read_b128 v[166:169], v184
	ds_read_b128 v[192:195], v184 offset:1024
	ds_read_b128 v[196:199], v184 offset:2048
	ds_read_b128 v[200:203], v184 offset:3072
	s_add_u32 s24, s60, 0x40000
	s_addc_u32 s25, s61, 0
	s_mov_b32 m0, s63
	v_lshl_add_u64 v[242:243], s[24:25], 0, v[128:129]
	ds_read_b128 v[204:207], v161 offset:32768
	ds_read_b128 v[208:211], v161 offset:33792
	ds_read_b128 v[212:215], v161 offset:34816
	ds_read_b128 v[216:219], v161 offset:35840
	ds_read_b128 v[220:223], v161 offset:36864
	ds_read_b128 v[224:227], v161 offset:37888
	ds_read_b128 v[228:231], v161 offset:38912
	ds_read_b128 v[232:235], v161 offset:39936
	global_load_lds_dwordx4 v[242:243], off
	v_lshl_add_u64 v[242:243], s[24:25], 0, v[130:131]
	s_mov_b32 m0, s64
	s_nop 0
	global_load_lds_dwordx4 v[242:243], off
	s_waitcnt vmcnt(8)
	s_waitcnt lgkmcnt(0)
	s_barrier
	s_setprio 1
	s_waitcnt lgkmcnt(0)
	v_mfma_f32_16x16x32_bf16 v[124:127], v[146:149], v[204:207], v[124:127]
	v_mfma_f32_16x16x32_bf16 v[120:123], v[154:157], v[204:207], v[120:123]
	v_mfma_f32_16x16x32_bf16 v[108:111], v[146:149], v[212:215], v[108:111]
	v_mfma_f32_16x16x32_bf16 v[104:107], v[154:157], v[212:215], v[104:107]
	v_mfma_f32_16x16x32_bf16 v[92:95], v[146:149], v[220:223], v[92:95]
	v_mfma_f32_16x16x32_bf16 v[88:91], v[154:157], v[220:223], v[88:91]
	v_mfma_f32_16x16x32_bf16 v[76:79], v[146:149], v[228:231], v[76:79]
	v_mfma_f32_16x16x32_bf16 v[72:75], v[154:157], v[228:231], v[72:75]
	v_mfma_f32_16x16x32_bf16 v[124:127], v[150:153], v[208:211], v[124:127]
	v_mfma_f32_16x16x32_bf16 v[120:123], v[162:165], v[208:211], v[120:123]
	v_mfma_f32_16x16x32_bf16 v[108:111], v[150:153], v[216:219], v[108:111]
	v_mfma_f32_16x16x32_bf16 v[104:107], v[162:165], v[216:219], v[104:107]
	v_mfma_f32_16x16x32_bf16 v[92:95], v[150:153], v[224:227], v[92:95]
	v_mfma_f32_16x16x32_bf16 v[88:91], v[162:165], v[224:227], v[88:91]
	v_mfma_f32_16x16x32_bf16 v[76:79], v[150:153], v[232:235], v[76:79]
	v_mfma_f32_16x16x32_bf16 v[72:75], v[162:165], v[232:235], v[72:75]
	v_mfma_f32_16x16x32_bf16 v[116:119], v[166:169], v[204:207], v[116:119]
	v_mfma_f32_16x16x32_bf16 v[112:115], v[196:199], v[204:207], v[112:115]
	v_mfma_f32_16x16x32_bf16 v[100:103], v[166:169], v[212:215], v[100:103]
	v_mfma_f32_16x16x32_bf16 v[96:99], v[196:199], v[212:215], v[96:99]
	v_mfma_f32_16x16x32_bf16 v[84:87], v[166:169], v[220:223], v[84:87]
	v_mfma_f32_16x16x32_bf16 v[80:83], v[196:199], v[220:223], v[80:83]
	v_mfma_f32_16x16x32_bf16 v[68:71], v[166:169], v[228:231], v[68:71]
	v_mfma_f32_16x16x32_bf16 v[64:67], v[196:199], v[228:231], v[64:67]
	v_mfma_f32_16x16x32_bf16 v[116:119], v[192:195], v[208:211], v[116:119]
	v_mfma_f32_16x16x32_bf16 v[112:115], v[200:203], v[208:211], v[112:115]
	v_mfma_f32_16x16x32_bf16 v[100:103], v[192:195], v[216:219], v[100:103]
	v_mfma_f32_16x16x32_bf16 v[96:99], v[200:203], v[216:219], v[96:99]
	v_mfma_f32_16x16x32_bf16 v[84:87], v[192:195], v[224:227], v[84:87]
	v_mfma_f32_16x16x32_bf16 v[80:83], v[200:203], v[224:227], v[80:83]
	v_mfma_f32_16x16x32_bf16 v[68:71], v[192:195], v[232:235], v[68:71]
	v_mfma_f32_16x16x32_bf16 v[64:67], v[200:203], v[232:235], v[64:67]
	s_setprio 0
	s_barrier
; #define PG8_STAGE(bufoff, gbase, voff) do { _Pragma("unroll") for (int _i = 0; _i < 2; ++_i) \
;         __builtin_amdgcn_global_load_lds((const unsigned*)((const char*)(gbase) + (voff)[_i]), (PG8_LAS unsigned*)(lds + (bufoff) + ldsw + _i * 8192), 16, 0, 0); } while (0)
; #define PG8_LDA(dst, b, h) do { _Pragma("unroll") for (int m = 0; m < 4; ++m) _Pragma("unroll") for (int k = 0; k < 2; ++k) dst[m][k] = *(const PG8_LAS bf16x8*)(lds + PG8_SA(b, h) + aoff + m * 2048 + k * 1024); } while (0)
; #define PG8_MMA(ai, bj, At, Bt) do { __builtin_amdgcn_s_setprio(1); _Pragma("unroll") for (int m = 0; m < 4; ++m) _Pragma("unroll") for (int n = 0; n < 2; ++n) _Pragma("unroll") for (int k = 0; k < 2; ++k) \
;         acc[ai][bj][m][n] = __builtin_amdgcn_mfma_f32_16x16x32_bf16(Bt[n][k], At[m][k], acc[ai][bj][m][n], 0, 0, 0); __builtin_amdgcn_s_setprio(0); } while (0)
; #define PG8_WAIT_V(n) asm volatile("s_waitcnt vmcnt(" #n ")" ::: "memory")
; #define PG8_WAIT_L(n) asm volatile("s_waitcnt lgkmcnt(" #n ")" ::: "memory")
; #define PG8_BAR __builtin_amdgcn_s_barrier()
; #define PG8_SCHED __builtin_amdgcn_sched_barrier(0)
; template <class Epi, class Sched, bool ALIGN_EPI = false, bool SP2 = false>
; __device__ __forceinline__ void gemm_phase(PG8_LAS unsigned char* lds, const Gemm g, const Sched& S, const Epi& E) {
;     ...
;             PG8_LDA(At, 1, 1); PG8_STAGE(PG8_SB(1, 0), b3, voffB); PG8_STAGE(PG8_SB(1, 1), b3 + hstep, voffB); PG8_STAGE(PG8_SA(1, 0), a3, voffA);
;             PG8_WAIT_V(8); PG8_WAIT_L(0); PG8_BAR; PG8_MMA(1, 0, At, B0); PG8_MMA(1, 1, At, B1); PG8_BAR; PG8_SCHED;
;     ...
;         if constexpr (ALIGN_EPI) { if (wr == 0) PG8_BAR; }
	s_add_i32 s24, s47, s23
	v_lshl_add_u64 v[170:171], v[170:171], 0, s[14:15]
	s_mov_b32 m0, s24
	ds_read_b128 v[204:207], v161 offset:49152
	ds_read_b128 v[208:211], v161 offset:50176
	ds_read_b128 v[212:215], v161 offset:51200
	ds_read_b128 v[216:219], v161 offset:52224
	ds_read_b128 v[220:223], v161 offset:53248
	ds_read_b128 v[224:227], v161 offset:54272
	ds_read_b128 v[228:231], v161 offset:55296
	ds_read_b128 v[232:235], v161 offset:56320
	global_load_lds_dwordx4 v[170:171], off
	s_add_i32 m0, s24, 0x2000
	s_add_u32 s24, s58, 0x40080
	v_lshl_add_u64 v[170:171], v[236:237], 0, s[14:15]
	s_addc_u32 s25, s59, 0
	s_add_i32 s47, s50, s23
	global_load_lds_dwordx4 v[170:171], off
	v_lshl_add_u64 v[170:171], s[24:25], 0, v[132:133]
	s_mov_b32 m0, s47
	s_nop 0
	global_load_lds_dwordx4 v[170:171], off
	v_lshl_add_u64 v[170:171], s[24:25], 0, v[140:141]
	s_add_i32 m0, s47, 0x2000
	s_nop 0
	global_load_lds_dwordx4 v[170:171], off
	v_lshl_add_u64 v[170:171], v[238:239], 0, s[14:15]
	s_mov_b32 m0, s65
	s_nop 0
	global_load_lds_dwordx4 v[170:171], off
	v_lshl_add_u64 v[170:171], v[240:241], 0, s[14:15]
	s_mov_b32 m0, s66
	s_nop 0
	global_load_lds_dwordx4 v[170:171], off
	s_waitcnt vmcnt(8)
	s_waitcnt lgkmcnt(0)
	s_barrier
	s_setprio 1
	s_waitcnt lgkmcnt(0)
	v_mfma_f32_16x16x32_bf16 v[60:63], v[146:149], v[204:207], v[60:63]
	v_mfma_f32_16x16x32_bf16 v[56:59], v[154:157], v[204:207], v[56:59]
	v_mfma_f32_16x16x32_bf16 v[44:47], v[146:149], v[212:215], v[44:47]
	v_mfma_f32_16x16x32_bf16 v[40:43], v[154:157], v[212:215], v[40:43]
	v_mfma_f32_16x16x32_bf16 v[28:31], v[146:149], v[220:223], v[28:31]
	v_mfma_f32_16x16x32_bf16 v[24:27], v[154:157], v[220:223], v[24:27]
	v_mfma_f32_16x16x32_bf16 v[12:15], v[146:149], v[228:231], v[12:15]
	v_mfma_f32_16x16x32_bf16 v[8:11], v[154:157], v[228:231], v[8:11]
	v_mfma_f32_16x16x32_bf16 v[60:63], v[150:153], v[208:211], v[60:63]
	v_mfma_f32_16x16x32_bf16 v[56:59], v[162:165], v[208:211], v[56:59]
	v_mfma_f32_16x16x32_bf16 v[44:47], v[150:153], v[216:219], v[44:47]
	v_mfma_f32_16x16x32_bf16 v[40:43], v[162:165], v[216:219], v[40:43]
	v_mfma_f32_16x16x32_bf16 v[28:31], v[150:153], v[224:227], v[28:31]
	v_mfma_f32_16x16x32_bf16 v[24:27], v[162:165], v[224:227], v[24:27]
	v_mfma_f32_16x16x32_bf16 v[12:15], v[150:153], v[232:235], v[12:15]
	v_mfma_f32_16x16x32_bf16 v[8:11], v[162:165], v[232:235], v[8:11]
	v_mfma_f32_16x16x32_bf16 v[52:55], v[166:169], v[204:207], v[52:55]
	v_mfma_f32_16x16x32_bf16 v[48:51], v[196:199], v[204:207], v[48:51]
	v_mfma_f32_16x16x32_bf16 v[36:39], v[166:169], v[212:215], v[36:39]
	v_mfma_f32_16x16x32_bf16 v[32:35], v[196:199], v[212:215], v[32:35]
	v_mfma_f32_16x16x32_bf16 v[20:23], v[166:169], v[220:223], v[20:23]
	v_mfma_f32_16x16x32_bf16 v[16:19], v[196:199], v[220:223], v[16:19]
	v_mfma_f32_16x16x32_bf16 v[4:7], v[166:169], v[228:231], v[4:7]
	v_mfma_f32_16x16x32_bf16 v[0:3], v[196:199], v[228:231], v[0:3]
	v_mfma_f32_16x16x32_bf16 v[52:55], v[192:195], v[208:211], v[52:55]
	v_mfma_f32_16x16x32_bf16 v[48:51], v[200:203], v[208:211], v[48:51]
	v_mfma_f32_16x16x32_bf16 v[36:39], v[192:195], v[216:219], v[36:39]
	v_mfma_f32_16x16x32_bf16 v[32:35], v[200:203], v[216:219], v[32:35]
	v_mfma_f32_16x16x32_bf16 v[20:23], v[192:195], v[224:227], v[20:23]
	v_mfma_f32_16x16x32_bf16 v[16:19], v[200:203], v[224:227], v[16:19]
	v_mfma_f32_16x16x32_bf16 v[4:7], v[192:195], v[232:235], v[4:7]
	v_mfma_f32_16x16x32_bf16 v[0:3], v[200:203], v[232:235], v[0:3]
	s_setprio 0
	s_barrier
	s_add_i32 s45, s45, 2
	s_add_u32 s56, s56, 0x100
	s_addc_u32 s57, s57, 0
	s_add_u32 s22, s22, 0x100
	s_addc_u32 s33, s33, 0
	s_cmp_gt_u32 s45, 13
	s_cbranch_scc0 .LBB0_554
	s_and_b64 vcc, exec, s[8:9]
	s_cbranch_vccz .LBB0_557
	s_barrier

; #define PG8_STAGE(bufoff, gbase, voff) do { _Pragma("unroll") for (int _i = 0; _i < 2; ++_i) \
;         __builtin_amdgcn_global_load_lds((const unsigned*)((const char*)(gbase) + (voff)[_i]), (PG8_LAS unsigned*)(lds + (bufoff) + ldsw + _i * 8192), 16, 0, 0); } while (0)
; #define PG8_LDA(dst, b, h) do { _Pragma("unroll") for (int m = 0; m < 4; ++m) _Pragma("unroll") for (int k = 0; k < 2; ++k) dst[m][k] = *(const PG8_LAS bf16x8*)(lds + PG8_SA(b, h) + aoff + m * 2048 + k * 1024); } while (0)
; #define PG8_LDB(dst, b, h) do { _Pragma("unroll") for (int n = 0; n < 2; ++n) _Pragma("unroll") for (int k = 0; k < 2; ++k) dst[n][k] = *(const PG8_LAS bf16x8*)(lds + PG8_SB(b, h) + boff + n * 2048 + k * 1024); } while (0)
; #define PG8_MMA(ai, bj, At, Bt) do { __builtin_amdgcn_s_setprio(1); _Pragma("unroll") for (int m = 0; m < 4; ++m) _Pragma("unroll") for (int n = 0; n < 2; ++n) _Pragma("unroll") for (int k = 0; k < 2; ++k) \
;         acc[ai][bj][m][n] = __builtin_amdgcn_mfma_f32_16x16x32_bf16(Bt[n][k], At[m][k], acc[ai][bj][m][n], 0, 0, 0); __builtin_amdgcn_s_setprio(0); } while (0)
; #define PG8_WAIT_V(n) asm volatile("s_waitcnt vmcnt(" #n ")" ::: "memory")
; #define PG8_WAIT_L(n) asm volatile("s_waitcnt lgkmcnt(" #n ")" ::: "memory")
; #define PG8_BAR __builtin_amdgcn_s_barrier()
; #define PG8_SCHED __builtin_amdgcn_sched_barrier(0)
; template <class Epi, class Sched, bool ALIGN_EPI = false, bool SP2 = false>
; __device__ __forceinline__ void gemm_phase(PG8_LAS unsigned char* lds, const Gemm g, const Sched& S, const Epi& E) {
;     ...
;         for (int t = 0; t < nt; t += 2) {
;             const bool last = (t == nt - 2);
;             const char* a1 = cA + (size_t)(t + 1) * kstep;
;             const char* a2 = last ? nA : cA + (size_t)(t + 2) * kstep; const char* b2 = last ? nB : cB + (size_t)(t + 2) * kstep;
;             const char* a3 = a2 + kstep; const char* b3 = b2 + kstep;
;             if (last && has_next) S.a_ready(nxt);
;             if constexpr (SP2) {
;             PG8_LDB(B0, 0, 0); PG8_LDB(B1, 0, 1); PG8_SCHED; PG8_LDA(At, 0, 0); PG8_STAGE(PG8_SA(1, 1), a1 + hstep, voffA);
;             PG8_WAIT_V(8); PG8_WAIT_L(0); PG8_BAR; PG8_MMA(0, 0, At, B0); PG8_MMA(0, 1, At, B1); PG8_BAR; PG8_SCHED;
;             PG8_LDA(At, 0, 1); PG8_STAGE(PG8_SB(0, 0), b2, voffB); PG8_STAGE(PG8_SB(0, 1), b2 + hstep, voffB); PG8_STAGE(PG8_SA(0, 0), a2, voffA);
.LBB0_698:
	s_add_u32 s48, s48, 0x80
	s_addc_u32 s49, s49, 0
	s_add_u32 s59, s52, 0x100
	s_addc_u32 vcc_lo, s53, 0
	s_mov_b32 s52, 0
	s_add_i32 vcc_hi, s52, 2
	s_add_u32 s24, s48, 0x80
	s_addc_u32 s25, s49, 0
	s_add_i32 s66, 0, 0x10000
	s_cmp_eq_u32 s79, s52
	s_cselect_b32 s53, s39, s25
	s_cselect_b32 s52, s38, s24
	v_add_u32_e32 v132, s66, v147
	s_cselect_b32 s25, s43, vcc_lo
	s_cselect_b32 s24, s42, s59
	s_add_i32 s29, 0, 0x14000
	ds_read_b128 v[156:159], v132
	ds_read_b128 v[162:165], v132 offset:1024
	ds_read_b128 v[166:169], v132 offset:2048
	ds_read_b128 v[192:195], v132 offset:3072
	v_add_u32_e32 v132, s29, v147
	ds_read_b128 v[196:199], v132
	ds_read_b128 v[200:203], v132 offset:1024
	ds_read_b128 v[204:207], v132 offset:2048
	ds_read_b128 v[208:211], v132 offset:3072
	v_lshl_add_u64 v[170:171], s[48:49], 0, v[152:153]
	s_add_i32 m0, s90, 0xc000
	ds_read_b128 v[212:215], v160
	ds_read_b128 v[216:219], v160 offset:1024
	ds_read_b128 v[220:223], v160 offset:2048
	ds_read_b128 v[224:227], v160 offset:3072
	ds_read_b128 v[228:231], v160 offset:4096
	ds_read_b128 v[232:235], v160 offset:5120
	ds_read_b128 v[236:239], v160 offset:6144
	ds_read_b128 v[240:243], v160 offset:7168
	global_load_lds_dwordx4 v[170:171], off
	v_lshl_add_u64 v[170:171], s[48:49], 0, v[154:155]
	s_add_i32 m0, s90, 0xe000
	s_nop 0
	global_load_lds_dwordx4 v[170:171], off
	s_waitcnt vmcnt(8)
	s_waitcnt lgkmcnt(0)
	s_barrier
	s_setprio 1
	s_waitcnt lgkmcnt(0)
	v_mfma_f32_16x16x32_bf16 v[124:127], v[156:159], v[212:215], 0
	v_mfma_f32_16x16x32_bf16 v[120:123], v[166:169], v[212:215], 0
	v_mfma_f32_16x16x32_bf16 v[108:111], v[156:159], v[220:223], 0
	v_mfma_f32_16x16x32_bf16 v[104:107], v[166:169], v[220:223], 0
	v_mfma_f32_16x16x32_bf16 v[92:95], v[156:159], v[228:231], 0
	v_mfma_f32_16x16x32_bf16 v[88:91], v[166:169], v[228:231], 0
	v_mfma_f32_16x16x32_bf16 v[76:79], v[156:159], v[236:239], 0
	v_mfma_f32_16x16x32_bf16 v[72:75], v[166:169], v[236:239], 0
	v_mfma_f32_16x16x32_bf16 v[124:127], v[162:165], v[216:219], v[124:127]
	v_mfma_f32_16x16x32_bf16 v[120:123], v[192:195], v[216:219], v[120:123]
	v_mfma_f32_16x16x32_bf16 v[108:111], v[162:165], v[224:227], v[108:111]
	v_mfma_f32_16x16x32_bf16 v[104:107], v[192:195], v[224:227], v[104:107]
	v_mfma_f32_16x16x32_bf16 v[92:95], v[162:165], v[232:235], v[92:95]
	v_mfma_f32_16x16x32_bf16 v[88:91], v[192:195], v[232:235], v[88:91]
	v_mfma_f32_16x16x32_bf16 v[76:79], v[162:165], v[240:243], v[76:79]
	v_mfma_f32_16x16x32_bf16 v[72:75], v[192:195], v[240:243], v[72:75]
	v_mfma_f32_16x16x32_bf16 v[116:119], v[196:199], v[212:215], 0
	v_mfma_f32_16x16x32_bf16 v[112:115], v[204:207], v[212:215], 0
	v_mfma_f32_16x16x32_bf16 v[100:103], v[196:199], v[220:223], 0
	v_mfma_f32_16x16x32_bf16 v[96:99], v[204:207], v[220:223], 0
	v_mfma_f32_16x16x32_bf16 v[84:87], v[196:199], v[228:231], 0
	v_mfma_f32_16x16x32_bf16 v[80:83], v[204:207], v[228:231], 0
	v_mfma_f32_16x16x32_bf16 v[68:71], v[196:199], v[236:239], 0
	v_mfma_f32_16x16x32_bf16 v[64:67], v[204:207], v[236:239], 0
	v_mfma_f32_16x16x32_bf16 v[116:119], v[200:203], v[216:219], v[116:119]
	v_mfma_f32_16x16x32_bf16 v[112:115], v[208:211], v[216:219], v[112:115]
	v_mfma_f32_16x16x32_bf16 v[100:103], v[200:203], v[224:227], v[100:103]
	v_mfma_f32_16x16x32_bf16 v[96:99], v[208:211], v[224:227], v[96:99]
	v_mfma_f32_16x16x32_bf16 v[84:87], v[200:203], v[232:235], v[84:87]
	v_mfma_f32_16x16x32_bf16 v[80:83], v[208:211], v[232:235], v[80:83]
	v_mfma_f32_16x16x32_bf16 v[68:71], v[200:203], v[240:243], v[68:71]
	v_mfma_f32_16x16x32_bf16 v[64:67], v[208:211], v[240:243], v[64:67]
	s_setprio 0
	s_barrier
	s_add_i32 s66, s66, s89
	v_lshl_add_u64 v[170:171], s[24:25], 0, v[130:131]
	s_mov_b32 m0, s66
	ds_read_b128 v[212:215], v160 offset:16384
	ds_read_b128 v[216:219], v160 offset:17408
	ds_read_b128 v[220:223], v160 offset:18432
	ds_read_b128 v[224:227], v160 offset:19456
	ds_read_b128 v[228:231], v160 offset:20480
	ds_read_b128 v[232:235], v160 offset:21504
	ds_read_b128 v[236:239], v160 offset:22528
	ds_read_b128 v[240:243], v160 offset:23552
	global_load_lds_dwordx4 v[170:171], off
	s_add_i32 m0, s66, 0x2000
	v_lshl_add_u64 v[244:245], s[24:25], 0, v[142:143]
	s_add_u32 s24, s24, s10
	s_addc_u32 s25, s25, 0
	s_add_i32 s29, s29, s89
	global_load_lds_dwordx4 v[244:245], off
	v_lshl_add_u64 v[246:247], s[24:25], 0, v[130:131]
	s_mov_b32 m0, s29
	v_lshl_add_u64 v[248:249], s[24:25], 0, v[142:143]
	global_load_lds_dwordx4 v[246:247], off
	s_add_i32 m0, s29, 0x2000
	v_lshl_add_u64 v[250:251], s[52:53], 0, v[128:129]
	global_load_lds_dwordx4 v[248:249], off
	s_mov_b32 m0, s90
	v_lshl_add_u64 v[252:253], s[52:53], 0, v[140:141]
	global_load_lds_dwordx4 v[250:251], off
	s_mov_b32 m0, s91
	s_nop 0
	global_load_lds_dwordx4 v[252:253], off
	s_waitcnt vmcnt(8)
	s_waitcnt lgkmcnt(0)
	s_barrier
; #define PG8_STAGE(bufoff, gbase, voff) do { _Pragma("unroll") for (int _i = 0; _i < 2; ++_i) \
;         __builtin_amdgcn_global_load_lds((const unsigned*)((const char*)(gbase) + (voff)[_i]), (PG8_LAS unsigned*)(lds + (bufoff) + ldsw + _i * 8192), 16, 0, 0); } while (0)
; #define PG8_LDA(dst, b, h) do { _Pragma("unroll") for (int m = 0; m < 4; ++m) _Pragma("unroll") for (int k = 0; k < 2; ++k) dst[m][k] = *(const PG8_LAS bf16x8*)(lds + PG8_SA(b, h) + aoff + m * 2048 + k * 1024); } while (0)
; #define PG8_LDB(dst, b, h) do { _Pragma("unroll") for (int n = 0; n < 2; ++n) _Pragma("unroll") for (int k = 0; k < 2; ++k) dst[n][k] = *(const PG8_LAS bf16x8*)(lds + PG8_SB(b, h) + boff + n * 2048 + k * 1024); } while (0)
; #define PG8_MMA(ai, bj, At, Bt) do { __builtin_amdgcn_s_setprio(1); _Pragma("unroll") for (int m = 0; m < 4; ++m) _Pragma("unroll") for (int n = 0; n < 2; ++n) _Pragma("unroll") for (int k = 0; k < 2; ++k) \
;         acc[ai][bj][m][n] = __builtin_amdgcn_mfma_f32_16x16x32_bf16(Bt[n][k], At[m][k], acc[ai][bj][m][n], 0, 0, 0); __builtin_amdgcn_s_setprio(0); } while (0)
; #define PG8_WAIT_V(n) asm volatile("s_waitcnt vmcnt(" #n ")" ::: "memory")
; #define PG8_WAIT_L(n) asm volatile("s_waitcnt lgkmcnt(" #n ")" ::: "memory")
; #define PG8_BAR __builtin_amdgcn_s_barrier()
; #define PG8_SCHED __builtin_amdgcn_sched_barrier(0)
; template <class Epi, class Sched, bool ALIGN_EPI = false, bool SP2 = false>
; __device__ __forceinline__ void gemm_phase(PG8_LAS unsigned char* lds, const Gemm g, const Sched& S, const Epi& E) {
;     ...
;             PG8_WAIT_V(8); PG8_WAIT_L(0); PG8_BAR; PG8_MMA(1, 0, At, B0); PG8_MMA(1, 1, At, B1); PG8_BAR; PG8_SCHED;
;             PG8_LDB(B0, 1, 0); PG8_LDB(B1, 1, 1); PG8_SCHED; PG8_LDA(At, 1, 0); PG8_STAGE(PG8_SA(0, 1), a2 + hstep, voffA);
;             PG8_WAIT_V(8); PG8_WAIT_L(0); PG8_BAR; PG8_MMA(0, 0, At, B0); PG8_MMA(0, 1, At, B1); PG8_BAR; PG8_SCHED;
	s_setprio 1
	s_waitcnt lgkmcnt(0)
	v_mfma_f32_16x16x32_bf16 v[60:63], v[156:159], v[212:215], 0
	v_mfma_f32_16x16x32_bf16 v[56:59], v[166:169], v[212:215], 0
	v_mfma_f32_16x16x32_bf16 v[44:47], v[156:159], v[220:223], 0
	v_mfma_f32_16x16x32_bf16 v[40:43], v[166:169], v[220:223], 0
	v_mfma_f32_16x16x32_bf16 v[28:31], v[156:159], v[228:231], 0
	v_mfma_f32_16x16x32_bf16 v[24:27], v[166:169], v[228:231], 0
	v_mfma_f32_16x16x32_bf16 v[12:15], v[156:159], v[236:239], 0
	v_mfma_f32_16x16x32_bf16 v[8:11], v[166:169], v[236:239], 0
	v_mfma_f32_16x16x32_bf16 v[60:63], v[162:165], v[216:219], v[60:63]
	v_mfma_f32_16x16x32_bf16 v[56:59], v[192:195], v[216:219], v[56:59]
	v_mfma_f32_16x16x32_bf16 v[44:47], v[162:165], v[224:227], v[44:47]
	v_mfma_f32_16x16x32_bf16 v[40:43], v[192:195], v[224:227], v[40:43]
	v_mfma_f32_16x16x32_bf16 v[28:31], v[162:165], v[232:235], v[28:31]
	v_mfma_f32_16x16x32_bf16 v[24:27], v[192:195], v[232:235], v[24:27]
	v_mfma_f32_16x16x32_bf16 v[12:15], v[162:165], v[240:243], v[12:15]
	v_mfma_f32_16x16x32_bf16 v[8:11], v[192:195], v[240:243], v[8:11]
	v_mfma_f32_16x16x32_bf16 v[52:55], v[196:199], v[212:215], 0
	v_mfma_f32_16x16x32_bf16 v[48:51], v[204:207], v[212:215], 0
	v_mfma_f32_16x16x32_bf16 v[36:39], v[196:199], v[220:223], 0
	v_mfma_f32_16x16x32_bf16 v[32:35], v[204:207], v[220:223], 0
	v_mfma_f32_16x16x32_bf16 v[20:23], v[196:199], v[228:231], 0
	v_mfma_f32_16x16x32_bf16 v[16:19], v[204:207], v[228:231], 0
	v_mfma_f32_16x16x32_bf16 v[4:7], v[196:199], v[236:239], 0
	v_mfma_f32_16x16x32_bf16 v[0:3], v[204:207], v[236:239], 0
	v_mfma_f32_16x16x32_bf16 v[52:55], v[200:203], v[216:219], v[52:55]
	v_mfma_f32_16x16x32_bf16 v[48:51], v[208:211], v[216:219], v[48:51]
	v_mfma_f32_16x16x32_bf16 v[36:39], v[200:203], v[224:227], v[36:39]
	v_mfma_f32_16x16x32_bf16 v[32:35], v[208:211], v[224:227], v[32:35]
	v_mfma_f32_16x16x32_bf16 v[20:23], v[200:203], v[232:235], v[20:23]
	v_mfma_f32_16x16x32_bf16 v[16:19], v[208:211], v[232:235], v[16:19]
	v_mfma_f32_16x16x32_bf16 v[4:7], v[200:203], v[240:243], v[4:7]
	v_mfma_f32_16x16x32_bf16 v[0:3], v[208:211], v[240:243], v[0:3]
	s_setprio 0
	s_barrier
	s_add_i32 s29, 0, 0x18000
	v_add_u32_e32 v132, s29, v147
	s_add_i32 s66, 0, 0x1c000
	ds_read_b128 v[156:159], v132
	ds_read_b128 v[162:165], v132 offset:1024
	ds_read_b128 v[166:169], v132 offset:2048
	ds_read_b128 v[192:195], v132 offset:3072
	v_add_u32_e32 v132, s66, v147
	ds_read_b128 v[196:199], v132
	ds_read_b128 v[200:203], v132 offset:1024
	ds_read_b128 v[204:207], v132 offset:2048
	ds_read_b128 v[208:211], v132 offset:3072
	s_add_u32 s24, s52, s10
	s_addc_u32 s25, s53, 0
	s_mov_b32 m0, s92
	v_lshl_add_u64 v[184:185], s[24:25], 0, v[128:129]
	ds_read_b128 v[212:215], v160 offset:32768
	ds_read_b128 v[216:219], v160 offset:33792
	ds_read_b128 v[220:223], v160 offset:34816
	ds_read_b128 v[224:227], v160 offset:35840
	ds_read_b128 v[228:231], v160 offset:36864
	ds_read_b128 v[232:235], v160 offset:37888
	ds_read_b128 v[236:239], v160 offset:38912
	ds_read_b128 v[240:243], v160 offset:39936
	global_load_lds_dwordx4 v[184:185], off
	v_lshl_add_u64 v[184:185], s[24:25], 0, v[140:141]
	s_mov_b32 m0, s93
	s_nop 0
	global_load_lds_dwordx4 v[184:185], off
	s_waitcnt vmcnt(8)
	s_waitcnt lgkmcnt(0)
	s_barrier
	s_setprio 1
	s_waitcnt lgkmcnt(0)
	v_mfma_f32_16x16x32_bf16 v[124:127], v[156:159], v[212:215], v[124:127]
	v_mfma_f32_16x16x32_bf16 v[120:123], v[166:169], v[212:215], v[120:123]
	v_mfma_f32_16x16x32_bf16 v[108:111], v[156:159], v[220:223], v[108:111]
	v_mfma_f32_16x16x32_bf16 v[104:107], v[166:169], v[220:223], v[104:107]
	v_mfma_f32_16x16x32_bf16 v[92:95], v[156:159], v[228:231], v[92:95]
	v_mfma_f32_16x16x32_bf16 v[88:91], v[166:169], v[228:231], v[88:91]
	v_mfma_f32_16x16x32_bf16 v[76:79], v[156:159], v[236:239], v[76:79]
	v_mfma_f32_16x16x32_bf16 v[72:75], v[166:169], v[236:239], v[72:75]
	v_mfma_f32_16x16x32_bf16 v[124:127], v[162:165], v[216:219], v[124:127]
	v_mfma_f32_16x16x32_bf16 v[120:123], v[192:195], v[216:219], v[120:123]
	v_mfma_f32_16x16x32_bf16 v[108:111], v[162:165], v[224:227], v[108:111]
	v_mfma_f32_16x16x32_bf16 v[104:107], v[192:195], v[224:227], v[104:107]
	v_mfma_f32_16x16x32_bf16 v[92:95], v[162:165], v[232:235], v[92:95]
	v_mfma_f32_16x16x32_bf16 v[88:91], v[192:195], v[232:235], v[88:91]
	v_mfma_f32_16x16x32_bf16 v[76:79], v[162:165], v[240:243], v[76:79]
	v_mfma_f32_16x16x32_bf16 v[72:75], v[192:195], v[240:243], v[72:75]
	v_mfma_f32_16x16x32_bf16 v[116:119], v[196:199], v[212:215], v[116:119]
	v_mfma_f32_16x16x32_bf16 v[112:115], v[204:207], v[212:215], v[112:115]
	v_mfma_f32_16x16x32_bf16 v[100:103], v[196:199], v[220:223], v[100:103]
	v_mfma_f32_16x16x32_bf16 v[96:99], v[204:207], v[220:223], v[96:99]
	v_mfma_f32_16x16x32_bf16 v[84:87], v[196:199], v[228:231], v[84:87]
	v_mfma_f32_16x16x32_bf16 v[80:83], v[204:207], v[228:231], v[80:83]
	v_mfma_f32_16x16x32_bf16 v[68:71], v[196:199], v[236:239], v[68:71]
	v_mfma_f32_16x16x32_bf16 v[64:67], v[204:207], v[236:239], v[64:67]
	v_mfma_f32_16x16x32_bf16 v[116:119], v[200:203], v[216:219], v[116:119]
	v_mfma_f32_16x16x32_bf16 v[112:115], v[208:211], v[216:219], v[112:115]
	v_mfma_f32_16x16x32_bf16 v[100:103], v[200:203], v[224:227], v[100:103]
	v_mfma_f32_16x16x32_bf16 v[96:99], v[208:211], v[224:227], v[96:99]
	v_mfma_f32_16x16x32_bf16 v[84:87], v[200:203], v[232:235], v[84:87]
	v_mfma_f32_16x16x32_bf16 v[80:83], v[208:211], v[232:235], v[80:83]
	v_mfma_f32_16x16x32_bf16 v[68:71], v[200:203], v[240:243], v[68:71]
	v_mfma_f32_16x16x32_bf16 v[64:67], v[208:211], v[240:243], v[64:67]
	s_setprio 0
	s_barrier
; #define PG8_STAGE(bufoff, gbase, voff) do { _Pragma("unroll") for (int _i = 0; _i < 2; ++_i) \
;         __builtin_amdgcn_global_load_lds((const unsigned*)((const char*)(gbase) + (voff)[_i]), (PG8_LAS unsigned*)(lds + (bufoff) + ldsw + _i * 8192), 16, 0, 0); } while (0)
; #define PG8_LDA(dst, b, h) do { _Pragma("unroll") for (int m = 0; m < 4; ++m) _Pragma("unroll") for (int k = 0; k < 2; ++k) dst[m][k] = *(const PG8_LAS bf16x8*)(lds + PG8_SA(b, h) + aoff + m * 2048 + k * 1024); } while (0)
; #define PG8_LDB(dst, b, h) do { _Pragma("unroll") for (int n = 0; n < 2; ++n) _Pragma("unroll") for (int k = 0; k < 2; ++k) dst[n][k] = *(const PG8_LAS bf16x8*)(lds + PG8_SB(b, h) + boff + n * 2048 + k * 1024); } while (0)
; template <class Epi, class Sched, bool ALIGN_EPI = false, bool SP2 = false>
; __device__ __forceinline__ void gemm_phase(PG8_LAS unsigned char* lds, const Gemm g, const Sched& S, const Epi& E) {
;     ...
;         for (int t = 0; t < nt; t += 2) {
;             const bool last = (t == nt - 2);
;             const char* a1 = cA + (size_t)(t + 1) * kstep;
;             const char* a2 = last ? nA : cA + (size_t)(t + 2) * kstep; const char* b2 = last ? nB : cB + (size_t)(t + 2) * kstep;
;             const char* a3 = a2 + kstep; const char* b3 = b2 + kstep;
;             if (last && has_next) S.a_ready(nxt);
;             if constexpr (SP2) {
;             PG8_LDB(B0, 0, 0); PG8_LDB(B1, 0, 1); PG8_SCHED; PG8_LDA(At, 0, 0); PG8_STAGE(PG8_SA(1, 1), a1 + hstep, voffA);
;             PG8_WAIT_V(8); PG8_WAIT_L(0); PG8_BAR; PG8_MMA(0, 0, At, B0); PG8_MMA(0, 1, At, B1); PG8_BAR; PG8_SCHED;
;             PG8_LDA(At, 0, 1); PG8_STAGE(PG8_SB(0, 0), b2, voffB); PG8_STAGE(PG8_SB(0, 1), b2 + hstep, voffB); PG8_STAGE(PG8_SA(0, 0), a2, voffA);
;             PG8_WAIT_V(8); PG8_WAIT_L(0); PG8_BAR; PG8_MMA(1, 0, At, B0); PG8_MMA(1, 1, At, B1); PG8_BAR; PG8_SCHED;
;             PG8_LDB(B0, 1, 0); PG8_LDB(B1, 1, 1); PG8_SCHED; PG8_LDA(At, 1, 0); PG8_STAGE(PG8_SA(0, 1), a2 + hstep, voffA);
;             PG8_WAIT_V(8); PG8_WAIT_L(0); PG8_BAR; PG8_MMA(0, 0, At, B0); PG8_MMA(0, 1, At, B1); PG8_BAR; PG8_SCHED;
;             PG8_LDA(At, 1, 1); PG8_STAGE(PG8_SB(1, 0), b3, voffB); PG8_STAGE(PG8_SB(1, 1), b3 + hstep, voffB); PG8_STAGE(PG8_SA(1, 0), a3, voffA);
;             PG8_WAIT_V(8); PG8_WAIT_L(0); PG8_BAR; PG8_MMA(1, 0, At, B0); PG8_MMA(1, 1, At, B1); PG8_BAR; PG8_SCHED;
	s_add_i32 s24, s29, s89
	v_lshl_add_u64 v[170:171], v[170:171], 0, s[14:15]
	s_mov_b32 m0, s24
	ds_read_b128 v[212:215], v160 offset:49152
	ds_read_b128 v[216:219], v160 offset:50176
	ds_read_b128 v[220:223], v160 offset:51200
	ds_read_b128 v[224:227], v160 offset:52224
	ds_read_b128 v[228:231], v160 offset:53248
	ds_read_b128 v[232:235], v160 offset:54272
	ds_read_b128 v[236:239], v160 offset:55296
	ds_read_b128 v[240:243], v160 offset:56320
	global_load_lds_dwordx4 v[170:171], off
	v_lshl_add_u64 v[170:171], v[244:245], 0, s[14:15]
	s_add_i32 m0, s24, 0x2000
	s_add_i32 s24, s66, s89
	global_load_lds_dwordx4 v[170:171], off
	v_lshl_add_u64 v[170:171], v[246:247], 0, s[14:15]
	s_mov_b32 m0, s24
	s_nop 0
	global_load_lds_dwordx4 v[170:171], off
	v_lshl_add_u64 v[170:171], v[248:249], 0, s[14:15]
	s_add_i32 m0, s24, 0x2000
	s_nop 0
	global_load_lds_dwordx4 v[170:171], off
	v_lshl_add_u64 v[170:171], v[250:251], 0, s[14:15]
	s_mov_b32 m0, s96
	s_nop 0
	global_load_lds_dwordx4 v[170:171], off
	v_lshl_add_u64 v[170:171], v[252:253], 0, s[14:15]
	s_mov_b32 m0, s97
	s_nop 0
	global_load_lds_dwordx4 v[170:171], off
	s_waitcnt vmcnt(8)
	s_waitcnt lgkmcnt(0)
	s_barrier
	s_setprio 1
	s_waitcnt lgkmcnt(0)
	v_mfma_f32_16x16x32_bf16 v[60:63], v[156:159], v[212:215], v[60:63]
	v_mfma_f32_16x16x32_bf16 v[56:59], v[166:169], v[212:215], v[56:59]
	v_mfma_f32_16x16x32_bf16 v[44:47], v[156:159], v[220:223], v[44:47]
	v_mfma_f32_16x16x32_bf16 v[40:43], v[166:169], v[220:223], v[40:43]
	v_mfma_f32_16x16x32_bf16 v[28:31], v[156:159], v[228:231], v[28:31]
	v_mfma_f32_16x16x32_bf16 v[24:27], v[166:169], v[228:231], v[24:27]
	v_mfma_f32_16x16x32_bf16 v[12:15], v[156:159], v[236:239], v[12:15]
	v_mfma_f32_16x16x32_bf16 v[8:11], v[166:169], v[236:239], v[8:11]
	v_mfma_f32_16x16x32_bf16 v[60:63], v[162:165], v[216:219], v[60:63]
	v_mfma_f32_16x16x32_bf16 v[56:59], v[192:195], v[216:219], v[56:59]
	v_mfma_f32_16x16x32_bf16 v[44:47], v[162:165], v[224:227], v[44:47]
	v_mfma_f32_16x16x32_bf16 v[40:43], v[192:195], v[224:227], v[40:43]
	v_mfma_f32_16x16x32_bf16 v[28:31], v[162:165], v[232:235], v[28:31]
	v_mfma_f32_16x16x32_bf16 v[24:27], v[192:195], v[232:235], v[24:27]
	v_mfma_f32_16x16x32_bf16 v[12:15], v[162:165], v[240:243], v[12:15]
	v_mfma_f32_16x16x32_bf16 v[8:11], v[192:195], v[240:243], v[8:11]
	v_mfma_f32_16x16x32_bf16 v[52:55], v[196:199], v[212:215], v[52:55]
	v_mfma_f32_16x16x32_bf16 v[48:51], v[204:207], v[212:215], v[48:51]
	v_mfma_f32_16x16x32_bf16 v[36:39], v[196:199], v[220:223], v[36:39]
	v_mfma_f32_16x16x32_bf16 v[32:35], v[204:207], v[220:223], v[32:35]
	v_mfma_f32_16x16x32_bf16 v[20:23], v[196:199], v[228:231], v[20:23]
	v_mfma_f32_16x16x32_bf16 v[16:19], v[204:207], v[228:231], v[16:19]
	v_mfma_f32_16x16x32_bf16 v[4:7], v[196:199], v[236:239], v[4:7]
	v_mfma_f32_16x16x32_bf16 v[0:3], v[204:207], v[236:239], v[0:3]
	v_mfma_f32_16x16x32_bf16 v[52:55], v[200:203], v[216:219], v[52:55]
	v_mfma_f32_16x16x32_bf16 v[48:51], v[208:211], v[216:219], v[48:51]
	v_mfma_f32_16x16x32_bf16 v[36:39], v[200:203], v[224:227], v[36:39]
	v_mfma_f32_16x16x32_bf16 v[32:35], v[208:211], v[224:227], v[32:35]
	v_mfma_f32_16x16x32_bf16 v[20:23], v[200:203], v[232:235], v[20:23]
	v_mfma_f32_16x16x32_bf16 v[16:19], v[208:211], v[232:235], v[16:19]
	v_mfma_f32_16x16x32_bf16 v[4:7], v[200:203], v[240:243], v[4:7]
	v_mfma_f32_16x16x32_bf16 v[0:3], v[208:211], v[240:243], v[0:3]
	s_setprio 0
	s_barrier
	s_add_u32 s48, s48, 0x100
	s_addc_u32 s49, s49, 0
	s_add_u32 s59, s59, 0x100
	s_addc_u32 vcc_lo, vcc_lo, 0
	s_cmp_ge_u32 vcc_hi, s78
	s_mov_b32 s52, vcc_hi
.LBB0_699:
	s_add_i32 vcc_hi, s52, 2
	s_add_u32 s24, s48, 0x80
	s_addc_u32 s25, s49, 0
	s_add_i32 s66, 0, 0x10000
	s_cmp_eq_u32 s79, s52
	s_cselect_b32 s53, s39, s25
	s_cselect_b32 s52, s38, s24
	v_add_u32_e32 v132, s66, v147
	s_cselect_b32 s25, s43, vcc_lo
	s_cselect_b32 s24, s42, s59
	s_add_i32 s29, 0, 0x14000
	ds_read_b128 v[156:159], v132
	ds_read_b128 v[162:165], v132 offset:1024
	ds_read_b128 v[166:169], v132 offset:2048
	ds_read_b128 v[192:195], v132 offset:3072
	v_add_u32_e32 v132, s29, v147
	ds_read_b128 v[196:199], v132
	ds_read_b128 v[200:203], v132 offset:1024
	ds_read_b128 v[204:207], v132 offset:2048
	ds_read_b128 v[208:211], v132 offset:3072
	v_lshl_add_u64 v[170:171], s[48:49], 0, v[152:153]
	s_add_i32 m0, s90, 0xc000
	ds_read_b128 v[212:215], v160
	ds_read_b128 v[216:219], v160 offset:1024
	ds_read_b128 v[220:223], v160 offset:2048
	ds_read_b128 v[224:227], v160 offset:3072
	ds_read_b128 v[228:231], v160 offset:4096
	ds_read_b128 v[232:235], v160 offset:5120
	ds_read_b128 v[236:239], v160 offset:6144
	ds_read_b128 v[240:243], v160 offset:7168
	global_load_lds_dwordx4 v[170:171], off
	v_lshl_add_u64 v[170:171], s[48:49], 0, v[154:155]
	s_add_i32 m0, s90, 0xe000
	s_nop 0
	global_load_lds_dwordx4 v[170:171], off
	s_waitcnt vmcnt(8)
	s_waitcnt lgkmcnt(0)
	s_barrier
; #define PG8_STAGE(bufoff, gbase, voff) do { _Pragma("unroll") for (int _i = 0; _i < 2; ++_i) \
;         __builtin_amdgcn_global_load_lds((const unsigned*)((const char*)(gbase) + (voff)[_i]), (PG8_LAS unsigned*)(lds + (bufoff) + ldsw + _i * 8192), 16, 0, 0); } while (0)
; #define PG8_LDA(dst, b, h) do { _Pragma("unroll") for (int m = 0; m < 4; ++m) _Pragma("unroll") for (int k = 0; k < 2; ++k) dst[m][k] = *(const PG8_LAS bf16x8*)(lds + PG8_SA(b, h) + aoff + m * 2048 + k * 1024); } while (0)
; #define PG8_LDB(dst, b, h) do { _Pragma("unroll") for (int n = 0; n < 2; ++n) _Pragma("unroll") for (int k = 0; k < 2; ++k) dst[n][k] = *(const PG8_LAS bf16x8*)(lds + PG8_SB(b, h) + boff + n * 2048 + k * 1024); } while (0)
; #define PG8_MMA(ai, bj, At, Bt) do { __builtin_amdgcn_s_setprio(1); _Pragma("unroll") for (int m = 0; m < 4; ++m) _Pragma("unroll") for (int n = 0; n < 2; ++n) _Pragma("unroll") for (int k = 0; k < 2; ++k) \
;         acc[ai][bj][m][n] = __builtin_amdgcn_mfma_f32_16x16x32_bf16(Bt[n][k], At[m][k], acc[ai][bj][m][n], 0, 0, 0); __builtin_amdgcn_s_setprio(0); } while (0)
; #define PG8_WAIT_V(n) asm volatile("s_waitcnt vmcnt(" #n ")" ::: "memory")
; #define PG8_WAIT_L(n) asm volatile("s_waitcnt lgkmcnt(" #n ")" ::: "memory")
; #define PG8_BAR __builtin_amdgcn_s_barrier()
; #define PG8_SCHED __builtin_amdgcn_sched_barrier(0)
; template <class Epi, class Sched, bool ALIGN_EPI = false, bool SP2 = false>
; __device__ __forceinline__ void gemm_phase(PG8_LAS unsigned char* lds, const Gemm g, const Sched& S, const Epi& E) {
;     ...
;             PG8_LDB(B0, 0, 0); PG8_LDB(B1, 0, 1); PG8_SCHED; PG8_LDA(At, 0, 0); PG8_STAGE(PG8_SA(1, 1), a1 + hstep, voffA);
;             PG8_WAIT_V(8); PG8_WAIT_L(0); PG8_BAR; PG8_MMA(0, 0, At, B0); PG8_MMA(0, 1, At, B1); PG8_BAR; PG8_SCHED;
;             PG8_LDA(At, 0, 1); PG8_STAGE(PG8_SB(0, 0), b2, voffB); PG8_STAGE(PG8_SB(0, 1), b2 + hstep, voffB); PG8_STAGE(PG8_SA(0, 0), a2, voffA);
;             PG8_WAIT_V(8); PG8_WAIT_L(0); PG8_BAR; PG8_MMA(1, 0, At, B0); PG8_MMA(1, 1, At, B1); PG8_BAR; PG8_SCHED;
	s_setprio 1
	s_waitcnt lgkmcnt(0)
	v_mfma_f32_16x16x32_bf16 v[124:127], v[156:159], v[212:215], v[124:127]
	v_mfma_f32_16x16x32_bf16 v[120:123], v[166:169], v[212:215], v[120:123]
	v_mfma_f32_16x16x32_bf16 v[108:111], v[156:159], v[220:223], v[108:111]
	v_mfma_f32_16x16x32_bf16 v[104:107], v[166:169], v[220:223], v[104:107]
	v_mfma_f32_16x16x32_bf16 v[92:95], v[156:159], v[228:231], v[92:95]
	v_mfma_f32_16x16x32_bf16 v[88:91], v[166:169], v[228:231], v[88:91]
	v_mfma_f32_16x16x32_bf16 v[76:79], v[156:159], v[236:239], v[76:79]
	v_mfma_f32_16x16x32_bf16 v[72:75], v[166:169], v[236:239], v[72:75]
	v_mfma_f32_16x16x32_bf16 v[124:127], v[162:165], v[216:219], v[124:127]
	v_mfma_f32_16x16x32_bf16 v[120:123], v[192:195], v[216:219], v[120:123]
	v_mfma_f32_16x16x32_bf16 v[108:111], v[162:165], v[224:227], v[108:111]
	v_mfma_f32_16x16x32_bf16 v[104:107], v[192:195], v[224:227], v[104:107]
	v_mfma_f32_16x16x32_bf16 v[92:95], v[162:165], v[232:235], v[92:95]
	v_mfma_f32_16x16x32_bf16 v[88:91], v[192:195], v[232:235], v[88:91]
	v_mfma_f32_16x16x32_bf16 v[76:79], v[162:165], v[240:243], v[76:79]
	v_mfma_f32_16x16x32_bf16 v[72:75], v[192:195], v[240:243], v[72:75]
	v_mfma_f32_16x16x32_bf16 v[116:119], v[196:199], v[212:215], v[116:119]
	v_mfma_f32_16x16x32_bf16 v[112:115], v[204:207], v[212:215], v[112:115]
	v_mfma_f32_16x16x32_bf16 v[100:103], v[196:199], v[220:223], v[100:103]
	v_mfma_f32_16x16x32_bf16 v[96:99], v[204:207], v[220:223], v[96:99]
	v_mfma_f32_16x16x32_bf16 v[84:87], v[196:199], v[228:231], v[84:87]
	v_mfma_f32_16x16x32_bf16 v[80:83], v[204:207], v[228:231], v[80:83]
	v_mfma_f32_16x16x32_bf16 v[68:71], v[196:199], v[236:239], v[68:71]
	v_mfma_f32_16x16x32_bf16 v[64:67], v[204:207], v[236:239], v[64:67]
	v_mfma_f32_16x16x32_bf16 v[116:119], v[200:203], v[216:219], v[116:119]
	v_mfma_f32_16x16x32_bf16 v[112:115], v[208:211], v[216:219], v[112:115]
	v_mfma_f32_16x16x32_bf16 v[100:103], v[200:203], v[224:227], v[100:103]
	v_mfma_f32_16x16x32_bf16 v[96:99], v[208:211], v[224:227], v[96:99]
	v_mfma_f32_16x16x32_bf16 v[84:87], v[200:203], v[232:235], v[84:87]
	v_mfma_f32_16x16x32_bf16 v[80:83], v[208:211], v[232:235], v[80:83]
	v_mfma_f32_16x16x32_bf16 v[68:71], v[200:203], v[240:243], v[68:71]
	v_mfma_f32_16x16x32_bf16 v[64:67], v[208:211], v[240:243], v[64:67]
	s_setprio 0
	s_barrier
	s_add_i32 s66, s66, s89
	v_lshl_add_u64 v[170:171], s[24:25], 0, v[130:131]
	s_mov_b32 m0, s66
	ds_read_b128 v[212:215], v160 offset:16384
	ds_read_b128 v[216:219], v160 offset:17408
	ds_read_b128 v[220:223], v160 offset:18432
	ds_read_b128 v[224:227], v160 offset:19456
	ds_read_b128 v[228:231], v160 offset:20480
	ds_read_b128 v[232:235], v160 offset:21504
	ds_read_b128 v[236:239], v160 offset:22528
	ds_read_b128 v[240:243], v160 offset:23552
	global_load_lds_dwordx4 v[170:171], off
	s_add_i32 m0, s66, 0x2000
	v_lshl_add_u64 v[244:245], s[24:25], 0, v[142:143]
	s_add_u32 s24, s24, s10
	s_addc_u32 s25, s25, 0
	s_add_i32 s29, s29, s89
	global_load_lds_dwordx4 v[244:245], off
	v_lshl_add_u64 v[246:247], s[24:25], 0, v[130:131]
	s_mov_b32 m0, s29
	v_lshl_add_u64 v[248:249], s[24:25], 0, v[142:143]
	global_load_lds_dwordx4 v[246:247], off
	s_add_i32 m0, s29, 0x2000
	v_lshl_add_u64 v[250:251], s[52:53], 0, v[128:129]
	global_load_lds_dwordx4 v[248:249], off
	s_mov_b32 m0, s90
	v_lshl_add_u64 v[252:253], s[52:53], 0, v[140:141]
	global_load_lds_dwordx4 v[250:251], off
	s_mov_b32 m0, s91
	s_nop 0
	global_load_lds_dwordx4 v[252:253], off
	s_waitcnt vmcnt(8)
	s_waitcnt lgkmcnt(0)
	s_barrier
	s_setprio 1
	s_waitcnt lgkmcnt(0)
	v_mfma_f32_16x16x32_bf16 v[60:63], v[156:159], v[212:215], v[60:63]
	v_mfma_f32_16x16x32_bf16 v[56:59], v[166:169], v[212:215], v[56:59]
	v_mfma_f32_16x16x32_bf16 v[44:47], v[156:159], v[220:223], v[44:47]
	v_mfma_f32_16x16x32_bf16 v[40:43], v[166:169], v[220:223], v[40:43]
	v_mfma_f32_16x16x32_bf16 v[28:31], v[156:159], v[228:231], v[28:31]
	v_mfma_f32_16x16x32_bf16 v[24:27], v[166:169], v[228:231], v[24:27]
	v_mfma_f32_16x16x32_bf16 v[12:15], v[156:159], v[236:239], v[12:15]
	v_mfma_f32_16x16x32_bf16 v[8:11], v[166:169], v[236:239], v[8:11]
	v_mfma_f32_16x16x32_bf16 v[60:63], v[162:165], v[216:219], v[60:63]
	v_mfma_f32_16x16x32_bf16 v[56:59], v[192:195], v[216:219], v[56:59]
	v_mfma_f32_16x16x32_bf16 v[44:47], v[162:165], v[224:227], v[44:47]
	v_mfma_f32_16x16x32_bf16 v[40:43], v[192:195], v[224:227], v[40:43]
	v_mfma_f32_16x16x32_bf16 v[28:31], v[162:165], v[232:235], v[28:31]
	v_mfma_f32_16x16x32_bf16 v[24:27], v[192:195], v[232:235], v[24:27]
	v_mfma_f32_16x16x32_bf16 v[12:15], v[162:165], v[240:243], v[12:15]
	v_mfma_f32_16x16x32_bf16 v[8:11], v[192:195], v[240:243], v[8:11]
	v_mfma_f32_16x16x32_bf16 v[52:55], v[196:199], v[212:215], v[52:55]
	v_mfma_f32_16x16x32_bf16 v[48:51], v[204:207], v[212:215], v[48:51]
	v_mfma_f32_16x16x32_bf16 v[36:39], v[196:199], v[220:223], v[36:39]
	v_mfma_f32_16x16x32_bf16 v[32:35], v[204:207], v[220:223], v[32:35]
	v_mfma_f32_16x16x32_bf16 v[20:23], v[196:199], v[228:231], v[20:23]
	v_mfma_f32_16x16x32_bf16 v[16:19], v[204:207], v[228:231], v[16:19]
	v_mfma_f32_16x16x32_bf16 v[4:7], v[196:199], v[236:239], v[4:7]
	v_mfma_f32_16x16x32_bf16 v[0:3], v[204:207], v[236:239], v[0:3]
	v_mfma_f32_16x16x32_bf16 v[52:55], v[200:203], v[216:219], v[52:55]
	v_mfma_f32_16x16x32_bf16 v[48:51], v[208:211], v[216:219], v[48:51]
	v_mfma_f32_16x16x32_bf16 v[36:39], v[200:203], v[224:227], v[36:39]
	v_mfma_f32_16x16x32_bf16 v[32:35], v[208:211], v[224:227], v[32:35]
	v_mfma_f32_16x16x32_bf16 v[20:23], v[200:203], v[232:235], v[20:23]
	v_mfma_f32_16x16x32_bf16 v[16:19], v[208:211], v[232:235], v[16:19]
	v_mfma_f32_16x16x32_bf16 v[4:7], v[200:203], v[240:243], v[4:7]
	v_mfma_f32_16x16x32_bf16 v[0:3], v[208:211], v[240:243], v[0:3]
	s_setprio 0
	s_barrier
; #define PG8_STAGE(bufoff, gbase, voff) do { _Pragma("unroll") for (int _i = 0; _i < 2; ++_i) \
;         __builtin_amdgcn_global_load_lds((const unsigned*)((const char*)(gbase) + (voff)[_i]), (PG8_LAS unsigned*)(lds + (bufoff) + ldsw + _i * 8192), 16, 0, 0); } while (0)
; #define PG8_LDA(dst, b, h) do { _Pragma("unroll") for (int m = 0; m < 4; ++m) _Pragma("unroll") for (int k = 0; k < 2; ++k) dst[m][k] = *(const PG8_LAS bf16x8*)(lds + PG8_SA(b, h) + aoff + m * 2048 + k * 1024); } while (0)
; #define PG8_LDB(dst, b, h) do { _Pragma("unroll") for (int n = 0; n < 2; ++n) _Pragma("unroll") for (int k = 0; k < 2; ++k) dst[n][k] = *(const PG8_LAS bf16x8*)(lds + PG8_SB(b, h) + boff + n * 2048 + k * 1024); } while (0)
; #define PG8_MMA(ai, bj, At, Bt) do { __builtin_amdgcn_s_setprio(1); _Pragma("unroll") for (int m = 0; m < 4; ++m) _Pragma("unroll") for (int n = 0; n < 2; ++n) _Pragma("unroll") for (int k = 0; k < 2; ++k) \
;         acc[ai][bj][m][n] = __builtin_amdgcn_mfma_f32_16x16x32_bf16(Bt[n][k], At[m][k], acc[ai][bj][m][n], 0, 0, 0); __builtin_amdgcn_s_setprio(0); } while (0)
; #define PG8_WAIT_V(n) asm volatile("s_waitcnt vmcnt(" #n ")" ::: "memory")
; #define PG8_WAIT_L(n) asm volatile("s_waitcnt lgkmcnt(" #n ")" ::: "memory")
; #define PG8_BAR __builtin_amdgcn_s_barrier()
; #define PG8_SCHED __builtin_amdgcn_sched_barrier(0)
; template <class Epi, class Sched, bool ALIGN_EPI = false, bool SP2 = false>
; __device__ __forceinline__ void gemm_phase(PG8_LAS unsigned char* lds, const Gemm g, const Sched& S, const Epi& E) {
;     ...
;             PG8_LDB(B0, 1, 0); PG8_LDB(B1, 1, 1); PG8_SCHED; PG8_LDA(At, 1, 0); PG8_STAGE(PG8_SA(0, 1), a2 + hstep, voffA);
;             PG8_WAIT_V(8); PG8_WAIT_L(0); PG8_BAR; PG8_MMA(0, 0, At, B0); PG8_MMA(0, 1, At, B1); PG8_BAR; PG8_SCHED;
	s_add_i32 s29, 0, 0x18000
	v_add_u32_e32 v132, s29, v147
	s_add_i32 s66, 0, 0x1c000
	ds_read_b128 v[156:159], v132
	ds_read_b128 v[162:165], v132 offset:1024
	ds_read_b128 v[166:169], v132 offset:2048
	ds_read_b128 v[192:195], v132 offset:3072
	v_add_u32_e32 v132, s66, v147
	ds_read_b128 v[196:199], v132
	ds_read_b128 v[200:203], v132 offset:1024
	ds_read_b128 v[204:207], v132 offset:2048
	ds_read_b128 v[208:211], v132 offset:3072
	s_add_u32 s24, s52, s10
	s_addc_u32 s25, s53, 0
	s_mov_b32 m0, s92
	v_lshl_add_u64 v[184:185], s[24:25], 0, v[128:129]
	ds_read_b128 v[212:215], v160 offset:32768
	ds_read_b128 v[216:219], v160 offset:33792
	ds_read_b128 v[220:223], v160 offset:34816
	ds_read_b128 v[224:227], v160 offset:35840
	ds_read_b128 v[228:231], v160 offset:36864
	ds_read_b128 v[232:235], v160 offset:37888
	ds_read_b128 v[236:239], v160 offset:38912
	ds_read_b128 v[240:243], v160 offset:39936
	global_load_lds_dwordx4 v[184:185], off
	v_lshl_add_u64 v[184:185], s[24:25], 0, v[140:141]
	s_mov_b32 m0, s93
	s_nop 0
	global_load_lds_dwordx4 v[184:185], off
	s_waitcnt vmcnt(8)
	s_waitcnt lgkmcnt(0)
	s_barrier
	s_setprio 1
	s_waitcnt lgkmcnt(0)
	v_mfma_f32_16x16x32_bf16 v[124:127], v[156:159], v[212:215], v[124:127]
	v_mfma_f32_16x16x32_bf16 v[120:123], v[166:169], v[212:215], v[120:123]
	v_mfma_f32_16x16x32_bf16 v[108:111], v[156:159], v[220:223], v[108:111]
	v_mfma_f32_16x16x32_bf16 v[104:107], v[166:169], v[220:223], v[104:107]
	v_mfma_f32_16x16x32_bf16 v[92:95], v[156:159], v[228:231], v[92:95]
	v_mfma_f32_16x16x32_bf16 v[88:91], v[166:169], v[228:231], v[88:91]
	v_mfma_f32_16x16x32_bf16 v[76:79], v[156:159], v[236:239], v[76:79]
	v_mfma_f32_16x16x32_bf16 v[72:75], v[166:169], v[236:239], v[72:75]
	v_mfma_f32_16x16x32_bf16 v[124:127], v[162:165], v[216:219], v[124:127]
	v_mfma_f32_16x16x32_bf16 v[120:123], v[192:195], v[216:219], v[120:123]
	v_mfma_f32_16x16x32_bf16 v[108:111], v[162:165], v[224:227], v[108:111]
	v_mfma_f32_16x16x32_bf16 v[104:107], v[192:195], v[224:227], v[104:107]
	v_mfma_f32_16x16x32_bf16 v[92:95], v[162:165], v[232:235], v[92:95]
	v_mfma_f32_16x16x32_bf16 v[88:91], v[192:195], v[232:235], v[88:91]
	v_mfma_f32_16x16x32_bf16 v[76:79], v[162:165], v[240:243], v[76:79]
	v_mfma_f32_16x16x32_bf16 v[72:75], v[192:195], v[240:243], v[72:75]
	v_mfma_f32_16x16x32_bf16 v[116:119], v[196:199], v[212:215], v[116:119]
	v_mfma_f32_16x16x32_bf16 v[112:115], v[204:207], v[212:215], v[112:115]
	v_mfma_f32_16x16x32_bf16 v[100:103], v[196:199], v[220:223], v[100:103]
	v_mfma_f32_16x16x32_bf16 v[96:99], v[204:207], v[220:223], v[96:99]
	v_mfma_f32_16x16x32_bf16 v[84:87], v[196:199], v[228:231], v[84:87]
	v_mfma_f32_16x16x32_bf16 v[80:83], v[204:207], v[228:231], v[80:83]
	v_mfma_f32_16x16x32_bf16 v[68:71], v[196:199], v[236:239], v[68:71]
	v_mfma_f32_16x16x32_bf16 v[64:67], v[204:207], v[236:239], v[64:67]
	v_mfma_f32_16x16x32_bf16 v[116:119], v[200:203], v[216:219], v[116:119]
	v_mfma_f32_16x16x32_bf16 v[112:115], v[208:211], v[216:219], v[112:115]
	v_mfma_f32_16x16x32_bf16 v[100:103], v[200:203], v[224:227], v[100:103]
	v_mfma_f32_16x16x32_bf16 v[96:99], v[208:211], v[224:227], v[96:99]
	v_mfma_f32_16x16x32_bf16 v[84:87], v[200:203], v[232:235], v[84:87]
	v_mfma_f32_16x16x32_bf16 v[80:83], v[208:211], v[232:235], v[80:83]
	v_mfma_f32_16x16x32_bf16 v[68:71], v[200:203], v[240:243], v[68:71]
	v_mfma_f32_16x16x32_bf16 v[64:67], v[208:211], v[240:243], v[64:67]
	s_setprio 0
	s_barrier
; #define PG8_STAGE(bufoff, gbase, voff) do { _Pragma("unroll") for (int _i = 0; _i < 2; ++_i) \
;         __builtin_amdgcn_global_load_lds((const unsigned*)((const char*)(gbase) + (voff)[_i]), (PG8_LAS unsigned*)(lds + (bufoff) + ldsw + _i * 8192), 16, 0, 0); } while (0)
; #define PG8_LDA(dst, b, h) do { _Pragma("unroll") for (int m = 0; m < 4; ++m) _Pragma("unroll") for (int k = 0; k < 2; ++k) dst[m][k] = *(const PG8_LAS bf16x8*)(lds + PG8_SA(b, h) + aoff + m * 2048 + k * 1024); } while (0)
; #define PG8_MMA(ai, bj, At, Bt) do { __builtin_amdgcn_s_setprio(1); _Pragma("unroll") for (int m = 0; m < 4; ++m) _Pragma("unroll") for (int n = 0; n < 2; ++n) _Pragma("unroll") for (int k = 0; k < 2; ++k) \
;         acc[ai][bj][m][n] = __builtin_amdgcn_mfma_f32_16x16x32_bf16(Bt[n][k], At[m][k], acc[ai][bj][m][n], 0, 0, 0); __builtin_amdgcn_s_setprio(0); } while (0)
; #define PG8_WAIT_V(n) asm volatile("s_waitcnt vmcnt(" #n ")" ::: "memory")
; #define PG8_WAIT_L(n) asm volatile("s_waitcnt lgkmcnt(" #n ")" ::: "memory")
; #define PG8_BAR __builtin_amdgcn_s_barrier()
; #define PG8_SCHED __builtin_amdgcn_sched_barrier(0)
; template <class Epi, class Sched, bool ALIGN_EPI = false, bool SP2 = false>
; __device__ __forceinline__ void gemm_phase(PG8_LAS unsigned char* lds, const Gemm g, const Sched& S, const Epi& E) {
;     ...
;         for (int t = 0; t < nt; t += 2) {
;     ...
;             PG8_LDA(At, 1, 1); PG8_STAGE(PG8_SB(1, 0), b3, voffB); PG8_STAGE(PG8_SB(1, 1), b3 + hstep, voffB); PG8_STAGE(PG8_SA(1, 0), a3, voffA);
;             PG8_WAIT_V(8); PG8_WAIT_L(0); PG8_BAR; PG8_MMA(1, 0, At, B0); PG8_MMA(1, 1, At, B1); PG8_BAR; PG8_SCHED;
	s_add_i32 s24, s29, s89
	v_lshl_add_u64 v[170:171], v[170:171], 0, s[14:15]
	s_mov_b32 m0, s24
	ds_read_b128 v[212:215], v160 offset:49152
	ds_read_b128 v[216:219], v160 offset:50176
	ds_read_b128 v[220:223], v160 offset:51200
	ds_read_b128 v[224:227], v160 offset:52224
	ds_read_b128 v[228:231], v160 offset:53248
	ds_read_b128 v[232:235], v160 offset:54272
	ds_read_b128 v[236:239], v160 offset:55296
	ds_read_b128 v[240:243], v160 offset:56320
	global_load_lds_dwordx4 v[170:171], off
	v_lshl_add_u64 v[170:171], v[244:245], 0, s[14:15]
	s_add_i32 m0, s24, 0x2000
	s_add_i32 s24, s66, s89
	global_load_lds_dwordx4 v[170:171], off
	v_lshl_add_u64 v[170:171], v[246:247], 0, s[14:15]
	s_mov_b32 m0, s24
	s_nop 0
	global_load_lds_dwordx4 v[170:171], off
	v_lshl_add_u64 v[170:171], v[248:249], 0, s[14:15]
	s_add_i32 m0, s24, 0x2000
	s_nop 0
	global_load_lds_dwordx4 v[170:171], off
	v_lshl_add_u64 v[170:171], v[250:251], 0, s[14:15]
	s_mov_b32 m0, s96
	s_nop 0
	global_load_lds_dwordx4 v[170:171], off
	v_lshl_add_u64 v[170:171], v[252:253], 0, s[14:15]
	s_mov_b32 m0, s97
	s_nop 0
	global_load_lds_dwordx4 v[170:171], off
	s_waitcnt vmcnt(8)
	s_waitcnt lgkmcnt(0)
	s_barrier
	s_setprio 1
	s_waitcnt lgkmcnt(0)
	v_mfma_f32_16x16x32_bf16 v[60:63], v[156:159], v[212:215], v[60:63]
	v_mfma_f32_16x16x32_bf16 v[56:59], v[166:169], v[212:215], v[56:59]
	v_mfma_f32_16x16x32_bf16 v[44:47], v[156:159], v[220:223], v[44:47]
	v_mfma_f32_16x16x32_bf16 v[40:43], v[166:169], v[220:223], v[40:43]
	v_mfma_f32_16x16x32_bf16 v[28:31], v[156:159], v[228:231], v[28:31]
	v_mfma_f32_16x16x32_bf16 v[24:27], v[166:169], v[228:231], v[24:27]
	v_mfma_f32_16x16x32_bf16 v[12:15], v[156:159], v[236:239], v[12:15]
	v_mfma_f32_16x16x32_bf16 v[8:11], v[166:169], v[236:239], v[8:11]
	v_mfma_f32_16x16x32_bf16 v[60:63], v[162:165], v[216:219], v[60:63]
	v_mfma_f32_16x16x32_bf16 v[56:59], v[192:195], v[216:219], v[56:59]
	v_mfma_f32_16x16x32_bf16 v[44:47], v[162:165], v[224:227], v[44:47]
	v_mfma_f32_16x16x32_bf16 v[40:43], v[192:195], v[224:227], v[40:43]
	v_mfma_f32_16x16x32_bf16 v[28:31], v[162:165], v[232:235], v[28:31]
	v_mfma_f32_16x16x32_bf16 v[24:27], v[192:195], v[232:235], v[24:27]
	v_mfma_f32_16x16x32_bf16 v[12:15], v[162:165], v[240:243], v[12:15]
	v_mfma_f32_16x16x32_bf16 v[8:11], v[192:195], v[240:243], v[8:11]
	v_mfma_f32_16x16x32_bf16 v[52:55], v[196:199], v[212:215], v[52:55]
	v_mfma_f32_16x16x32_bf16 v[48:51], v[204:207], v[212:215], v[48:51]
	v_mfma_f32_16x16x32_bf16 v[36:39], v[196:199], v[220:223], v[36:39]
	v_mfma_f32_16x16x32_bf16 v[32:35], v[204:207], v[220:223], v[32:35]
	v_mfma_f32_16x16x32_bf16 v[20:23], v[196:199], v[228:231], v[20:23]
	v_mfma_f32_16x16x32_bf16 v[16:19], v[204:207], v[228:231], v[16:19]
	v_mfma_f32_16x16x32_bf16 v[4:7], v[196:199], v[236:239], v[4:7]
	v_mfma_f32_16x16x32_bf16 v[0:3], v[204:207], v[236:239], v[0:3]
	v_mfma_f32_16x16x32_bf16 v[52:55], v[200:203], v[216:219], v[52:55]
	v_mfma_f32_16x16x32_bf16 v[48:51], v[208:211], v[216:219], v[48:51]
	v_mfma_f32_16x16x32_bf16 v[36:39], v[200:203], v[224:227], v[36:39]
	v_mfma_f32_16x16x32_bf16 v[32:35], v[208:211], v[224:227], v[32:35]
	v_mfma_f32_16x16x32_bf16 v[20:23], v[200:203], v[232:235], v[20:23]
	v_mfma_f32_16x16x32_bf16 v[16:19], v[208:211], v[232:235], v[16:19]
	v_mfma_f32_16x16x32_bf16 v[4:7], v[200:203], v[240:243], v[4:7]
	v_mfma_f32_16x16x32_bf16 v[0:3], v[208:211], v[240:243], v[0:3]
	s_setprio 0
	s_barrier
	s_add_u32 s48, s48, 0x100
	s_addc_u32 s49, s49, 0
	s_add_u32 s59, s59, 0x100
	s_addc_u32 vcc_lo, vcc_lo, 0
	s_cmp_ge_u32 vcc_hi, s78
	s_mov_b32 s52, vcc_hi
	s_cbranch_scc0 .LBB0_699
	s_and_b64 vcc, exec, s[36:37]
	s_cbranch_vccz .LBB0_702
